# f32 weight loads of the three weight-conversion passes marked nt (streamed once), on top of previous
# speedup vs baseline: 1.0128x; 1.0061x over previous
;     const int nblk = N / 64, kb = item / nblk, nb = item % nblk, k0 = 64 * kb, n0 = 64 * nb;
;     const int r16 = lane & 15, q = lane >> 4;
;     const float* src = W + (size_t)(k0 + 2 * q) * N + n0 + 4 * r16;
;     f32x4 v[16];
; #pragma unroll
;     for (int j = 0; j < 16; ++j) v[j] = *(const f32x4*)(src + (size_t)(8 * (j >> 1) + (j & 1)) * N);
;     if (nscale) { const f32x4 ns = *(const f32x4*)(nscale + n0 + 4 * r16);
; #pragma unroll
;         for (int j = 0; j < 16; ++j) v[j] = v[j] * ns; }
;     if (kscale) {
; #pragma unroll
; __device__ __forceinline__ void weights_pass(const Args& a, LAS unsigned char* scr, int gw, int NGW, int lane, int pass) {
;     ...
;     for (int it = gw + (pass == 1 ? PER_LAYER : 0); it < (pass == 2 ? PER_LAYER : 2 * PER_LAYER); it += NGW) {
;         const int l = it / PER_LAYER; int r = it % PER_LAYER;
;         { const bool shared = (r >= I_IN + I_OUT / 2 && r < I_IN + I_OUT) || (r >= I_IN + I_OUT + I_QM && r < I_IN + I_OUT + 3 * I_QM);
;           const int ip = (shared || (l == 0 && r < I_IN)) ? 0 : (l == 0 ? 2 : 1);
;           if (ip != pass) continue; }
;         unsigned char* wl = ws + WS_W + (size_t)l * WL_SIZE;
;         if (r < I_IN) { transpose_item<1>(a.in[I_WIN] + (size_t)l * DM * INW, DM, INW, (bf16_t*)(wl + WL_IN), a.in[I_GMIX] + l * DM, nullptr, 0, scr, r, lane); continue; } r -= I_IN;
;         if (r < I_OUT / 2) { transpose_item<0>(a.in[I_WOUT] + (size_t)l * DM * DM, 2048, DM, (bf16_t*)(wl + WL_OUT), nullptr, nullptr, 0, scr, r, lane, DM); continue; } r -= I_OUT / 2;
;         if (r < I_OUT / 2) { transpose_item<0>(a.in[I_WOUT] + (size_t)l * DM * DM + (size_t)2048 * DM, 2048, DM, (bf16_t*)(ws + WS_WLOW) + (size_t)l * DM * 2048, nullptr, nullptr, 0, scr, r, lane); continue; } r -= I_OUT / 2;
;         if (r < I_QM) { transpose_item<0>(a.in[I_WQM] + (size_t)l * DM * MW, DM, MW, (bf16_t*)(wl + WL_Q), a.in[I_GCROSS] + l * DM, nullptr, 0, scr, r, lane); continue; } r -= I_QM;
;         if (r < I_QM) { transpose_item<1>(a.in[I_WKM] + (size_t)l * DM * MW, DM, MW, (bf16_t*)(ws + WS_WKV) + (size_t)l * 1024 * DM, a.in[I_GMEM] + l * DM, nullptr, 0, scr, r, lane); continue; } r -= I_QM;
;         if (r < I_QM) { transpose_item<1>(a.in[I_WVM] + (size_t)l * DM * MW, DM, MW, (bf16_t*)(ws + WS_WKV) + (size_t)l * 1024 * DM, a.in[I_GMEM] + l * DM, nullptr, 512, scr, r, lane); continue; } r -= I_QM;
.LBB0_11:
	s_mul_hi_i32 s0, s46, 0xbfa02fe9
	s_add_i32 s0, s0, s46
	s_lshr_b32 s1, s0, 31
	s_ashr_i32 s0, s0, 15
	s_add_i32 s10, s0, s1
	s_mul_i32 s0, s10, 0xffff5500
	s_add_i32 s49, s46, s0
	s_add_i32 s51, s49, 0xffffe600
	s_cmpk_lt_u32 s51, 0x800
	s_cselect_b64 s[0:1], -1, 0
	s_and_b32 s2, s49, 0xfffffc00
	s_cmpk_eq_i32 s2, 0x2400
	s_cselect_b64 s[12:13], -1, 0
	s_or_b64 s[12:13], s[0:1], s[12:13]
	s_add_i32 s0, s46, 0xaaff
	s_cmp_lt_u32 s0, 0x155ff
	s_cselect_b64 s[14:15], -1, 0
	s_cmpk_gt_i32 s49, 0x11ff
	s_cselect_b64 s[0:1], -1, 0
	s_cmpk_lt_i32 s49, 0x1200
	s_cselect_b64 s[52:53], -1, 0
	s_and_b64 s[14:15], s[14:15], s[52:53]
	s_or_b64 s[12:13], s[12:13], s[14:15]
	s_andn2_b64 vcc, exec, s[12:13]
	s_cbranch_vccnz .LBB0_10
	s_ashr_i32 s11, s10, 31
	s_mul_i32 s8, s10, 0x15000000
	s_mul_hi_i32 s2, s10, 0x15000000
	s_add_u32 s47, s17, s8
	s_addc_u32 s48, s18, s2
	s_mov_b64 s[12:13], -1
	s_and_b64 vcc, exec, s[0:1]
	s_cbranch_vccz .LBB0_35
	s_cmpk_gt_u32 s49, 0x19ff
	s_mov_b64 s[0:1], -1
	s_cbranch_scc0 .LBB0_32
	s_cmpk_gt_u32 s49, 0x21ff
	s_cbranch_scc0 .LBB0_29
	s_lshl_b64 s[12:13], s[10:11], 23
	s_cmpk_gt_u32 s49, 0x23ff
	s_cbranch_scc0 .LBB0_24
	s_add_u32 s52, s19, s12
	s_mul_i32 s0, s10, 0xffd54000
	s_addc_u32 s53, s25, s13
	s_add_i32 s2, s35, s0
	s_and_b32 s54, s2, 0x1c0
	s_cmpk_gt_u32 s49, 0x25ff
	s_mov_b64 s[14:15], -1
	v_cmp_ne_u32_e64 s[0:1], 1, v106
	s_cbranch_scc0 .LBB0_20
	v_readlane_b32 s56, v250, 46
	v_readlane_b32 s64, v250, 54
	v_readlane_b32 s65, v250, 55
	s_add_u32 s14, s64, s12
	s_mul_i32 s8, s10, 0xfffaa800
	s_addc_u32 s15, s65, s13
	s_add_i32 s8, s31, s8
	s_addk_i32 s8, 0xe000
	s_and_b32 s55, s8, 0x7ffc0
	v_or_b32_e32 v2, s55, v74
	v_lshlrev_b32_e32 v2, 11, v2
	v_mov_b32_e32 v3, v71
	v_lshl_add_u64 v[2:3], s[14:15], 0, v[2:3]
	s_lshl_b32 s8, s54, 2
	v_lshl_add_u64 v[2:3], v[2:3], 0, s[8:9]
	v_lshl_add_u64 v[2:3], v[2:3], 0, v[70:71]
	v_add_co_u32_e32 v4, vcc, s39, v2
	global_load_dwordx4 v[58:61], v[2:3], off nt
	global_load_dwordx4 v[62:65], v[2:3], off offset:2048 nt
	v_addc_co_u32_e32 v5, vcc, 0, v3, vcc
	global_load_dwordx4 v[50:53], v[4:5], off nt
	global_load_dwordx4 v[54:57], v[4:5], off offset:2048 nt
	v_add_co_u32_e32 v4, vcc, s40, v2
	v_readlane_b32 s58, v250, 48
	s_nop 0
	v_addc_co_u32_e32 v5, vcc, 0, v3, vcc
	global_load_dwordx4 v[42:45], v[4:5], off nt
	global_load_dwordx4 v[46:49], v[4:5], off offset:2048 nt
	v_add_co_u32_e32 v4, vcc, s41, v2
	v_readlane_b32 s59, v250, 49
	s_nop 0
	v_addc_co_u32_e32 v5, vcc, 0, v3, vcc
	global_load_dwordx4 v[34:37], v[4:5], off nt
	global_load_dwordx4 v[38:41], v[4:5], off offset:2048 nt
	v_add_co_u32_e32 v4, vcc, s42, v2
	v_readlane_b32 s57, v250, 47
	s_nop 0
	v_addc_co_u32_e32 v5, vcc, 0, v3, vcc
	global_load_dwordx4 v[26:29], v[4:5], off nt
	global_load_dwordx4 v[30:33], v[4:5], off offset:2048 nt
	v_add_co_u32_e32 v4, vcc, s43, v2
	v_readlane_b32 s60, v250, 50
	s_nop 0
	v_addc_co_u32_e32 v5, vcc, 0, v3, vcc
	global_load_dwordx4 v[18:21], v[4:5], off nt
	global_load_dwordx4 v[22:25], v[4:5], off offset:2048 nt
	v_add_co_u32_e32 v4, vcc, 0x18000, v2
	v_readlane_b32 s61, v250, 51
	s_nop 0
	v_addc_co_u32_e32 v5, vcc, 0, v3, vcc
	v_add_co_u32_e32 v6, vcc, 0x1c000, v2
	global_load_dwordx4 v[10:13], v[4:5], off nt
	global_load_dwordx4 v[14:17], v[4:5], off offset:2048 nt
	v_addc_co_u32_e32 v7, vcc, 0, v3, vcc
	global_load_dwordx4 v[2:5], v[6:7], off nt
	s_nop 0
	global_load_dwordx4 v[6:9], v[6:7], off offset:2048 nt
	s_and_b64 vcc, exec, s[0:1]
	v_readlane_b32 s62, v250, 52
	v_readlane_b32 s63, v250, 53
	v_readlane_b32 s66, v250, 56
	v_readlane_b32 s67, v250, 57
	v_readlane_b32 s68, v250, 58
	v_readlane_b32 s69, v250, 59
	v_readlane_b32 s70, v250, 60
	v_readlane_b32 s71, v250, 61
	s_cbranch_vccnz .LBB0_19
	s_lshl_b32 s14, s10, 12
	s_ashr_i32 s15, s14, 31
	s_lshl_b64 s[14:15], s[14:15], 2
	s_add_u32 s8, s58, s14
	s_addc_u32 s15, s59, s15
	s_lshl_b32 s14, s55, 2
	s_add_u32 s14, s8, s14
	s_addc_u32 s15, s15, 0
	global_load_dwordx2 v[114:115], v107, s[14:15]
	s_waitcnt vmcnt(0)
	v_pk_mul_f32 v[60:61], v[60:61], v[114:115] op_sel_hi:[1,0]
	v_pk_mul_f32 v[58:59], v[58:59], v[114:115] op_sel_hi:[1,0]
	v_pk_mul_f32 v[64:65], v[64:65], v[114:115] op_sel:[0,1]
	v_pk_mul_f32 v[62:63], v[62:63], v[114:115] op_sel:[0,1]
	global_load_dwordx2 v[114:115], v107, s[14:15] offset:32
	s_waitcnt vmcnt(0)
	v_pk_mul_f32 v[52:53], v[52:53], v[114:115] op_sel_hi:[1,0]
	v_pk_mul_f32 v[50:51], v[50:51], v[114:115] op_sel_hi:[1,0]
	v_pk_mul_f32 v[56:57], v[56:57], v[114:115] op_sel:[0,1]
	v_pk_mul_f32 v[54:55], v[54:55], v[114:115] op_sel:[0,1]
	global_load_dwordx2 v[114:115], v107, s[14:15] offset:64
	s_waitcnt vmcnt(0)
	v_pk_mul_f32 v[44:45], v[44:45], v[114:115] op_sel_hi:[1,0]
	v_pk_mul_f32 v[42:43], v[42:43], v[114:115] op_sel_hi:[1,0]
	v_pk_mul_f32 v[48:49], v[48:49], v[114:115] op_sel:[0,1]
	v_pk_mul_f32 v[46:47], v[46:47], v[114:115] op_sel:[0,1]
	global_load_dwordx2 v[114:115], v107, s[14:15] offset:96
	s_waitcnt vmcnt(0)
	v_pk_mul_f32 v[36:37], v[36:37], v[114:115] op_sel_hi:[1,0]
	v_pk_mul_f32 v[34:35], v[34:35], v[114:115] op_sel_hi:[1,0]
	v_pk_mul_f32 v[40:41], v[40:41], v[114:115] op_sel:[0,1]
	v_pk_mul_f32 v[38:39], v[38:39], v[114:115] op_sel:[0,1]
	global_load_dwordx2 v[114:115], v107, s[14:15] offset:128
	s_waitcnt vmcnt(0)
	v_pk_mul_f32 v[28:29], v[28:29], v[114:115] op_sel_hi:[1,0]
	v_pk_mul_f32 v[26:27], v[26:27], v[114:115] op_sel_hi:[1,0]
	v_pk_mul_f32 v[32:33], v[32:33], v[114:115] op_sel:[0,1]
	v_pk_mul_f32 v[30:31], v[30:31], v[114:115] op_sel:[0,1]
	global_load_dwordx2 v[114:115], v107, s[14:15] offset:160
	s_waitcnt vmcnt(0)
	v_pk_mul_f32 v[20:21], v[20:21], v[114:115] op_sel_hi:[1,0]
	v_pk_mul_f32 v[18:19], v[18:19], v[114:115] op_sel_hi:[1,0]
	v_pk_mul_f32 v[24:25], v[24:25], v[114:115] op_sel:[0,1]
	v_pk_mul_f32 v[22:23], v[22:23], v[114:115] op_sel:[0,1]
	global_load_dwordx2 v[114:115], v107, s[14:15] offset:192
	s_waitcnt vmcnt(0)
	v_pk_mul_f32 v[12:13], v[12:13], v[114:115] op_sel_hi:[1,0]
	v_pk_mul_f32 v[10:11], v[10:11], v[114:115] op_sel_hi:[1,0]
	v_pk_mul_f32 v[16:17], v[16:17], v[114:115] op_sel:[0,1]
	v_pk_mul_f32 v[14:15], v[14:15], v[114:115] op_sel:[0,1]
	global_load_dwordx2 v[114:115], v107, s[14:15] offset:224
	s_waitcnt vmcnt(0)
	v_pk_mul_f32 v[4:5], v[4:5], v[114:115] op_sel_hi:[1,0]
	v_pk_mul_f32 v[2:3], v[2:3], v[114:115] op_sel_hi:[1,0]
	v_pk_mul_f32 v[8:9], v[8:9], v[114:115] op_sel:[0,1]
	v_pk_mul_f32 v[6:7], v[6:7], v[114:115] op_sel:[0,1]

;     const int nblk = N / 64, kb = item / nblk, nb = item % nblk, k0 = 64 * kb, n0 = 64 * nb;
;     const int r16 = lane & 15, q = lane >> 4;
;     const float* src = W + (size_t)(k0 + 2 * q) * N + n0 + 4 * r16;
;     f32x4 v[16];
; #pragma unroll
;     for (int j = 0; j < 16; ++j) v[j] = *(const f32x4*)(src + (size_t)(8 * (j >> 1) + (j & 1)) * N);
;     if (nscale) { const f32x4 ns = *(const f32x4*)(nscale + n0 + 4 * r16);
; #pragma unroll
;         for (int j = 0; j < 16; ++j) v[j] = v[j] * ns; }
;     if (kscale) {
; #pragma unroll
; __device__ __forceinline__ void weights_pass(const Args& a, LAS unsigned char* scr, int gw, int NGW, int lane, int pass) {
;     ...
;     for (int it = gw + (pass == 1 ? PER_LAYER : 0); it < (pass == 2 ? PER_LAYER : 2 * PER_LAYER); it += NGW) {
;         const int l = it / PER_LAYER; int r = it % PER_LAYER;
;         { const bool shared = (r >= I_IN + I_OUT / 2 && r < I_IN + I_OUT) || (r >= I_IN + I_OUT + I_QM && r < I_IN + I_OUT + 3 * I_QM);
;           const int ip = (shared || (l == 0 && r < I_IN)) ? 0 : (l == 0 ? 2 : 1);
;           if (ip != pass) continue; }
;         unsigned char* wl = ws + WS_W + (size_t)l * WL_SIZE;
;         if (r < I_IN) { transpose_item<1>(a.in[I_WIN] + (size_t)l * DM * INW, DM, INW, (bf16_t*)(wl + WL_IN), a.in[I_GMIX] + l * DM, nullptr, 0, scr, r, lane); continue; } r -= I_IN;
;         if (r < I_OUT / 2) { transpose_item<0>(a.in[I_WOUT] + (size_t)l * DM * DM, 2048, DM, (bf16_t*)(wl + WL_OUT), nullptr, nullptr, 0, scr, r, lane, DM); continue; } r -= I_OUT / 2;
;         if (r < I_OUT / 2) { transpose_item<0>(a.in[I_WOUT] + (size_t)l * DM * DM + (size_t)2048 * DM, 2048, DM, (bf16_t*)(ws + WS_WLOW) + (size_t)l * DM * 2048, nullptr, nullptr, 0, scr, r, lane); continue; } r -= I_OUT / 2;
;         if (r < I_QM) { transpose_item<0>(a.in[I_WQM] + (size_t)l * DM * MW, DM, MW, (bf16_t*)(wl + WL_Q), a.in[I_GCROSS] + l * DM, nullptr, 0, scr, r, lane); continue; } r -= I_QM;
;         if (r < I_QM) { transpose_item<1>(a.in[I_WKM] + (size_t)l * DM * MW, DM, MW, (bf16_t*)(ws + WS_WKV) + (size_t)l * 1024 * DM, a.in[I_GMEM] + l * DM, nullptr, 0, scr, r, lane); continue; } r -= I_QM;
;         if (r < I_QM) { transpose_item<1>(a.in[I_WVM] + (size_t)l * DM * MW, DM, MW, (bf16_t*)(ws + WS_WKV) + (size_t)l * 1024 * DM, a.in[I_GMEM] + l * DM, nullptr, 512, scr, r, lane); continue; } r -= I_QM;
.LBB0_20:
	s_and_b64 vcc, exec, s[14:15]
	s_cbranch_vccz .LBB0_38
	v_readlane_b32 s60, v250, 46
	v_readlane_b32 s66, v250, 52
	v_readlane_b32 s67, v250, 53
	s_add_u32 s56, s66, s12
	s_mul_i32 s8, s10, 0xfffaa800
	s_addc_u32 s57, s67, s13
	s_add_i32 s8, s31, s8
	s_addk_i32 s8, 0xf000
	s_and_b32 s14, s8, 0x7ffc0
	v_or_b32_e32 v2, s14, v74
	v_lshlrev_b32_e32 v2, 11, v2
	v_mov_b32_e32 v3, v71
	v_lshl_add_u64 v[2:3], s[56:57], 0, v[2:3]
	s_lshl_b32 s8, s54, 2
	v_lshl_add_u64 v[2:3], v[2:3], 0, s[8:9]
	v_lshl_add_u64 v[2:3], v[2:3], 0, v[70:71]
	v_add_co_u32_e32 v4, vcc, s39, v2
	global_load_dwordx4 v[58:61], v[2:3], off nt
	global_load_dwordx4 v[62:65], v[2:3], off offset:2048 nt
	v_addc_co_u32_e32 v5, vcc, 0, v3, vcc
	global_load_dwordx4 v[50:53], v[4:5], off nt
	global_load_dwordx4 v[54:57], v[4:5], off offset:2048 nt
	v_add_co_u32_e32 v4, vcc, s40, v2
	v_readlane_b32 s62, v250, 48
	s_nop 0
	v_addc_co_u32_e32 v5, vcc, 0, v3, vcc
	global_load_dwordx4 v[42:45], v[4:5], off nt
	global_load_dwordx4 v[46:49], v[4:5], off offset:2048 nt
	v_add_co_u32_e32 v4, vcc, s41, v2
	v_readlane_b32 s63, v250, 49
	s_nop 0
	v_addc_co_u32_e32 v5, vcc, 0, v3, vcc
	global_load_dwordx4 v[34:37], v[4:5], off nt
	global_load_dwordx4 v[38:41], v[4:5], off offset:2048 nt
	v_add_co_u32_e32 v4, vcc, s42, v2
	v_readlane_b32 s61, v250, 47
	s_nop 0
	v_addc_co_u32_e32 v5, vcc, 0, v3, vcc
	global_load_dwordx4 v[26:29], v[4:5], off nt
	global_load_dwordx4 v[30:33], v[4:5], off offset:2048 nt
	v_add_co_u32_e32 v4, vcc, s43, v2
	v_readlane_b32 s64, v250, 50
	s_nop 0
	v_addc_co_u32_e32 v5, vcc, 0, v3, vcc
	global_load_dwordx4 v[18:21], v[4:5], off nt
	global_load_dwordx4 v[22:25], v[4:5], off offset:2048 nt
	v_add_co_u32_e32 v4, vcc, 0x18000, v2
	v_readlane_b32 s65, v250, 51
	s_nop 0
	v_addc_co_u32_e32 v5, vcc, 0, v3, vcc
	v_add_co_u32_e32 v6, vcc, 0x1c000, v2
	global_load_dwordx4 v[10:13], v[4:5], off nt
	global_load_dwordx4 v[14:17], v[4:5], off offset:2048 nt
	v_addc_co_u32_e32 v7, vcc, 0, v3, vcc
	global_load_dwordx4 v[2:5], v[6:7], off nt
	s_nop 0
	global_load_dwordx4 v[6:9], v[6:7], off offset:2048 nt
	s_and_b64 vcc, exec, s[0:1]
	v_readlane_b32 s68, v250, 54
	v_readlane_b32 s69, v250, 55
	v_readlane_b32 s70, v250, 56
	v_readlane_b32 s71, v250, 57
	v_readlane_b32 s72, v250, 58
	v_readlane_b32 s73, v250, 59
	v_readlane_b32 s74, v250, 60
	v_readlane_b32 s75, v250, 61
	s_cbranch_vccnz .LBB0_23
	s_lshl_b32 s0, s10, 12
	s_ashr_i32 s1, s0, 31
	s_lshl_b64 s[0:1], s[0:1], 2
	s_add_u32 s0, s62, s0
	s_addc_u32 s1, s63, s1
	s_lshl_b32 s8, s14, 2
	s_add_u32 s0, s0, s8
	s_addc_u32 s1, s1, 0
	global_load_dwordx2 v[114:115], v107, s[0:1]
	s_waitcnt vmcnt(0)
	v_pk_mul_f32 v[60:61], v[60:61], v[114:115] op_sel_hi:[1,0]
	v_pk_mul_f32 v[58:59], v[58:59], v[114:115] op_sel_hi:[1,0]
	v_pk_mul_f32 v[64:65], v[64:65], v[114:115] op_sel:[0,1]
	v_pk_mul_f32 v[62:63], v[62:63], v[114:115] op_sel:[0,1]
	global_load_dwordx2 v[114:115], v107, s[0:1] offset:32
	s_waitcnt vmcnt(0)
	v_pk_mul_f32 v[52:53], v[52:53], v[114:115] op_sel_hi:[1,0]
	v_pk_mul_f32 v[50:51], v[50:51], v[114:115] op_sel_hi:[1,0]
	v_pk_mul_f32 v[56:57], v[56:57], v[114:115] op_sel:[0,1]
	v_pk_mul_f32 v[54:55], v[54:55], v[114:115] op_sel:[0,1]
	global_load_dwordx2 v[114:115], v107, s[0:1] offset:64
	s_waitcnt vmcnt(0)
	v_pk_mul_f32 v[44:45], v[44:45], v[114:115] op_sel_hi:[1,0]
	v_pk_mul_f32 v[42:43], v[42:43], v[114:115] op_sel_hi:[1,0]
	v_pk_mul_f32 v[48:49], v[48:49], v[114:115] op_sel:[0,1]
	v_pk_mul_f32 v[46:47], v[46:47], v[114:115] op_sel:[0,1]
	global_load_dwordx2 v[114:115], v107, s[0:1] offset:96
	s_waitcnt vmcnt(0)
	v_pk_mul_f32 v[36:37], v[36:37], v[114:115] op_sel_hi:[1,0]
	v_pk_mul_f32 v[34:35], v[34:35], v[114:115] op_sel_hi:[1,0]
	v_pk_mul_f32 v[40:41], v[40:41], v[114:115] op_sel:[0,1]
	v_pk_mul_f32 v[38:39], v[38:39], v[114:115] op_sel:[0,1]
	global_load_dwordx2 v[114:115], v107, s[0:1] offset:128
	s_waitcnt vmcnt(0)
	v_pk_mul_f32 v[28:29], v[28:29], v[114:115] op_sel_hi:[1,0]
	v_pk_mul_f32 v[26:27], v[26:27], v[114:115] op_sel_hi:[1,0]
	v_pk_mul_f32 v[32:33], v[32:33], v[114:115] op_sel:[0,1]
	v_pk_mul_f32 v[30:31], v[30:31], v[114:115] op_sel:[0,1]
	global_load_dwordx2 v[114:115], v107, s[0:1] offset:160
	s_waitcnt vmcnt(0)
	v_pk_mul_f32 v[20:21], v[20:21], v[114:115] op_sel_hi:[1,0]
	v_pk_mul_f32 v[18:19], v[18:19], v[114:115] op_sel_hi:[1,0]
	v_pk_mul_f32 v[24:25], v[24:25], v[114:115] op_sel:[0,1]
	v_pk_mul_f32 v[22:23], v[22:23], v[114:115] op_sel:[0,1]
	global_load_dwordx2 v[114:115], v107, s[0:1] offset:192
	s_waitcnt vmcnt(0)
	v_pk_mul_f32 v[12:13], v[12:13], v[114:115] op_sel_hi:[1,0]
	v_pk_mul_f32 v[10:11], v[10:11], v[114:115] op_sel_hi:[1,0]
	v_pk_mul_f32 v[16:17], v[16:17], v[114:115] op_sel:[0,1]
	v_pk_mul_f32 v[14:15], v[14:15], v[114:115] op_sel:[0,1]
	global_load_dwordx2 v[114:115], v107, s[0:1] offset:224
	s_waitcnt vmcnt(0)
	v_pk_mul_f32 v[4:5], v[4:5], v[114:115] op_sel_hi:[1,0]
	v_pk_mul_f32 v[2:3], v[2:3], v[114:115] op_sel_hi:[1,0]
	v_pk_mul_f32 v[8:9], v[8:9], v[114:115] op_sel:[0,1]
	v_pk_mul_f32 v[6:7], v[6:7], v[114:115] op_sel:[0,1]

;     const int nblk = N / 64, kb = item / nblk, nb = item % nblk, k0 = 64 * kb, n0 = 64 * nb;
;     const int r16 = lane & 15, q = lane >> 4;
;     const float* src = W + (size_t)(k0 + 2 * q) * N + n0 + 4 * r16;
;     f32x4 v[16];
; #pragma unroll
;     for (int j = 0; j < 16; ++j) v[j] = *(const f32x4*)(src + (size_t)(8 * (j >> 1) + (j & 1)) * N);
;     if (nscale) { const f32x4 ns = *(const f32x4*)(nscale + n0 + 4 * r16);
; #pragma unroll
;         for (int j = 0; j < 16; ++j) v[j] = v[j] * ns; }
;     if (kscale) {
; #pragma unroll
;         for (int i = 0; i < 8; ++i) { const f32x2 g = *(const f32x2*)(kscale + k0 + 8 * i + 2 * q); v[2 * i] = v[2 * i] * g[0]; v[2 * i + 1] = v[2 * i + 1] * g[1]; } }
.LBB0_25:
	v_readlane_b32 s52, v250, 46
	v_readlane_b32 s56, v250, 50
	v_readlane_b32 s57, v250, 51
	s_add_u32 s0, s56, s12
	s_mul_i32 s2, s10, 0xfffaa800
	s_addc_u32 s1, s57, s13
	s_add_i32 s2, s31, s2
	s_and_b32 s2, s2, 0x7ffc0
	s_lshl_b32 s8, s49, 6
	v_or_b32_e32 v2, s2, v74
	s_and_b32 s12, s8, 0x1c0
	v_lshlrev_b32_e32 v2, 11, v2
	v_mov_b32_e32 v3, v71
	v_lshl_add_u64 v[2:3], s[0:1], 0, v[2:3]
	s_lshl_b32 s8, s12, 2
	v_lshl_add_u64 v[2:3], v[2:3], 0, s[8:9]
	v_lshl_add_u64 v[2:3], v[2:3], 0, v[70:71]
	v_add_co_u32_e32 v4, vcc, s39, v2
	global_load_dwordx4 v[58:61], v[2:3], off nt
	global_load_dwordx4 v[62:65], v[2:3], off offset:2048 nt
	v_addc_co_u32_e32 v5, vcc, 0, v3, vcc
	global_load_dwordx4 v[50:53], v[4:5], off nt
	global_load_dwordx4 v[54:57], v[4:5], off offset:2048 nt
	v_add_co_u32_e32 v4, vcc, s40, v2
	v_readlane_b32 s53, v250, 47
	s_nop 0
	v_addc_co_u32_e32 v5, vcc, 0, v3, vcc
	global_load_dwordx4 v[42:45], v[4:5], off nt
	global_load_dwordx4 v[46:49], v[4:5], off offset:2048 nt
	v_add_co_u32_e32 v4, vcc, s41, v2
	v_readlane_b32 s54, v250, 48
	s_nop 0
	v_addc_co_u32_e32 v5, vcc, 0, v3, vcc
	global_load_dwordx4 v[34:37], v[4:5], off nt
	global_load_dwordx4 v[38:41], v[4:5], off offset:2048 nt
	v_add_co_u32_e32 v4, vcc, s42, v2
	v_readlane_b32 s55, v250, 49
	s_nop 0
	v_addc_co_u32_e32 v5, vcc, 0, v3, vcc
	global_load_dwordx4 v[26:29], v[4:5], off nt
	global_load_dwordx4 v[30:33], v[4:5], off offset:2048 nt
	v_add_co_u32_e32 v4, vcc, s43, v2
	v_readlane_b32 s58, v250, 52
	s_nop 0
	v_addc_co_u32_e32 v5, vcc, 0, v3, vcc
	global_load_dwordx4 v[18:21], v[4:5], off nt
	global_load_dwordx4 v[22:25], v[4:5], off offset:2048 nt
	v_add_co_u32_e32 v4, vcc, 0x18000, v2
	v_readlane_b32 s59, v250, 53
	s_nop 0
	v_addc_co_u32_e32 v5, vcc, 0, v3, vcc
	v_add_co_u32_e32 v6, vcc, 0x1c000, v2
	global_load_dwordx4 v[10:13], v[4:5], off nt
	global_load_dwordx4 v[14:17], v[4:5], off offset:2048 nt
	v_addc_co_u32_e32 v7, vcc, 0, v3, vcc
	global_load_dwordx4 v[2:5], v[6:7], off nt
	s_nop 0
	global_load_dwordx4 v[6:9], v[6:7], off offset:2048 nt
	s_andn2_b64 vcc, exec, s[4:5]
	v_readlane_b32 s60, v250, 54
	v_readlane_b32 s61, v250, 55
	v_readlane_b32 s62, v250, 56
	v_readlane_b32 s63, v250, 57
	v_readlane_b32 s64, v250, 58
	v_readlane_b32 s65, v250, 59
	v_readlane_b32 s66, v250, 60
	v_readlane_b32 s67, v250, 61
	s_cbranch_vccnz .LBB0_27
	s_lshl_b32 s0, s10, 12
	s_ashr_i32 s1, s0, 31
	s_lshl_b64 s[0:1], s[0:1], 2
	s_add_u32 s0, s52, s0
	s_addc_u32 s1, s53, s1
	s_lshl_b32 s8, s2, 2
	s_add_u32 s0, s0, s8
	s_addc_u32 s1, s1, 0
	global_load_dwordx2 v[114:115], v107, s[0:1]
	s_waitcnt vmcnt(0)
	v_pk_mul_f32 v[60:61], v[60:61], v[114:115] op_sel_hi:[1,0]
	v_pk_mul_f32 v[58:59], v[58:59], v[114:115] op_sel_hi:[1,0]
	v_pk_mul_f32 v[64:65], v[64:65], v[114:115] op_sel:[0,1]
	v_pk_mul_f32 v[62:63], v[62:63], v[114:115] op_sel:[0,1]
	global_load_dwordx2 v[114:115], v107, s[0:1] offset:32
	s_waitcnt vmcnt(0)
	v_pk_mul_f32 v[52:53], v[52:53], v[114:115] op_sel_hi:[1,0]
	v_pk_mul_f32 v[50:51], v[50:51], v[114:115] op_sel_hi:[1,0]
	v_pk_mul_f32 v[56:57], v[56:57], v[114:115] op_sel:[0,1]
	v_pk_mul_f32 v[54:55], v[54:55], v[114:115] op_sel:[0,1]
	global_load_dwordx2 v[114:115], v107, s[0:1] offset:64
	s_waitcnt vmcnt(0)
	v_pk_mul_f32 v[44:45], v[44:45], v[114:115] op_sel_hi:[1,0]
	v_pk_mul_f32 v[42:43], v[42:43], v[114:115] op_sel_hi:[1,0]
	v_pk_mul_f32 v[48:49], v[48:49], v[114:115] op_sel:[0,1]
	v_pk_mul_f32 v[46:47], v[46:47], v[114:115] op_sel:[0,1]
	global_load_dwordx2 v[114:115], v107, s[0:1] offset:96
	s_waitcnt vmcnt(0)
	v_pk_mul_f32 v[36:37], v[36:37], v[114:115] op_sel_hi:[1,0]
	v_pk_mul_f32 v[34:35], v[34:35], v[114:115] op_sel_hi:[1,0]
	v_pk_mul_f32 v[40:41], v[40:41], v[114:115] op_sel:[0,1]
	v_pk_mul_f32 v[38:39], v[38:39], v[114:115] op_sel:[0,1]
	global_load_dwordx2 v[114:115], v107, s[0:1] offset:128
	s_waitcnt vmcnt(0)
	v_pk_mul_f32 v[28:29], v[28:29], v[114:115] op_sel_hi:[1,0]
	v_pk_mul_f32 v[26:27], v[26:27], v[114:115] op_sel_hi:[1,0]
	v_pk_mul_f32 v[32:33], v[32:33], v[114:115] op_sel:[0,1]
	v_pk_mul_f32 v[30:31], v[30:31], v[114:115] op_sel:[0,1]
	global_load_dwordx2 v[114:115], v107, s[0:1] offset:160
	s_waitcnt vmcnt(0)
	v_pk_mul_f32 v[20:21], v[20:21], v[114:115] op_sel_hi:[1,0]
	v_pk_mul_f32 v[18:19], v[18:19], v[114:115] op_sel_hi:[1,0]
	v_pk_mul_f32 v[24:25], v[24:25], v[114:115] op_sel:[0,1]
	v_pk_mul_f32 v[22:23], v[22:23], v[114:115] op_sel:[0,1]
	global_load_dwordx2 v[114:115], v107, s[0:1] offset:192
	s_waitcnt vmcnt(0)
	v_pk_mul_f32 v[12:13], v[12:13], v[114:115] op_sel_hi:[1,0]
	v_pk_mul_f32 v[10:11], v[10:11], v[114:115] op_sel_hi:[1,0]
	v_pk_mul_f32 v[16:17], v[16:17], v[114:115] op_sel:[0,1]
	v_pk_mul_f32 v[14:15], v[14:15], v[114:115] op_sel:[0,1]
	global_load_dwordx2 v[114:115], v107, s[0:1] offset:224
	s_waitcnt vmcnt(0)
	v_pk_mul_f32 v[4:5], v[4:5], v[114:115] op_sel_hi:[1,0]
	v_pk_mul_f32 v[2:3], v[2:3], v[114:115] op_sel_hi:[1,0]
	v_pk_mul_f32 v[8:9], v[8:9], v[114:115] op_sel:[0,1]
	v_pk_mul_f32 v[6:7], v[6:7], v[114:115] op_sel:[0,1]

; #define LAS __attribute__((address_space(3)))
; __device__ __forceinline__ unsigned cvt_pk_bf16(float lo, float hi) { unsigned r; asm volatile("v_cvt_pk_bf16_f32 %0, %1, %2" : "=v"(r) : "v"(lo), "v"(hi)); return r; }
;     ...
;     const float* src = W + (size_t)(k0 + 2 * q) * N + n0 + 4 * r16;
;     f32x4 v[16];
; #pragma unroll
;     for (int j = 0; j < 16; ++j) v[j] = *(const f32x4*)(src + (size_t)(8 * (j >> 1) + (j & 1)) * N);
;     if (nscale) { const f32x4 ns = *(const f32x4*)(nscale + n0 + 4 * r16);
; #pragma unroll
;         for (int j = 0; j < 16; ++j) v[j] = v[j] * ns; }
;     if (kscale) {
; #pragma unroll
;         for (int i = 0; i < 8; ++i) { const f32x2 g = *(const f32x2*)(kscale + k0 + 8 * i + 2 * q); v[2 * i] = v[2 * i] * g[0]; v[2 * i + 1] = v[2 * i + 1] * g[1]; } }
; #pragma unroll
;     for (int i = 0; i < 8; ++i)
; #pragma unroll
;         for (int e = 0; e < 4; ++e) *(LAS unsigned*)(scr + (4 * r16 + e) * 128 + ((i ^ (r16 & 7)) * 16) + q * 4) = cvt_pk_bf16(v[2 * i][e], v[2 * i + 1][e]);
.LBB0_29:
	s_andn2_b64 vcc, exec, s[0:1]
	s_cbranch_vccnz .LBB0_31
	v_readlane_b32 s52, v250, 10
	s_lshl_b64 s[0:1], s[10:11], 26
	v_readlane_b32 s66, v250, 24
	v_readlane_b32 s67, v250, 25
	s_add_u32 s14, s66, s0
	s_addc_u32 s15, s67, s1
	s_lshl_b64 s[12:13], s[10:11], 24
	s_add_u32 s1, s27, s12
	s_addc_u32 s2, s30, s13
	s_and_b32 s12, s51, 0xffc0
	s_lshl_b32 s0, s49, 6
	v_lshlrev_b32_e32 v2, 2, v67
	s_and_b32 s0, s0, 0xfc0
	v_lshl_or_b32 v2, s12, 14, v2
	v_mov_b32_e32 v3, v71
	v_lshl_add_u64 v[2:3], s[14:15], 0, v[2:3]
	s_lshl_b32 s8, s0, 2
	v_lshl_add_u64 v[2:3], v[2:3], 0, s[8:9]
	v_lshl_add_u64 v[58:59], v[2:3], 0, v[70:71]
	s_brev_b32 s8, 64
	v_add_co_u32_e32 v2, vcc, s8, v58
	s_mov_b32 s8, 0x2004000
	s_nop 0
	v_addc_co_u32_e32 v3, vcc, 0, v59, vcc
	v_add_co_u32_e32 v6, vcc, s8, v58
	s_mov_b32 s8, 0x2020000
	s_nop 0
	v_addc_co_u32_e32 v7, vcc, 0, v59, vcc
	global_load_dwordx4 v[2:5], v[2:3], off nt
	s_nop 0
	global_load_dwordx4 v[6:9], v[6:7], off nt
	v_add_co_u32_e32 v10, vcc, s8, v58
	s_mov_b32 s8, 0x2024000
	s_nop 0
	v_addc_co_u32_e32 v11, vcc, 0, v59, vcc
	v_add_co_u32_e32 v14, vcc, s8, v58
	s_mov_b32 s8, 0x2040000
	s_nop 0
	v_addc_co_u32_e32 v15, vcc, 0, v59, vcc
	global_load_dwordx4 v[10:13], v[10:11], off nt
	s_nop 0
	global_load_dwordx4 v[14:17], v[14:15], off nt
	v_add_co_u32_e32 v18, vcc, s8, v58
	s_mov_b32 s8, 0x2044000
	s_nop 0
	v_addc_co_u32_e32 v19, vcc, 0, v59, vcc
	v_add_co_u32_e32 v22, vcc, s8, v58
	s_mov_b32 s8, 0x2060000
	s_nop 0
	v_addc_co_u32_e32 v23, vcc, 0, v59, vcc
	global_load_dwordx4 v[18:21], v[18:19], off nt
	s_nop 0
	global_load_dwordx4 v[22:25], v[22:23], off nt
	v_add_co_u32_e32 v26, vcc, s8, v58
	s_mov_b32 s8, 0x2064000
	s_nop 0
	v_addc_co_u32_e32 v27, vcc, 0, v59, vcc
	v_add_co_u32_e32 v30, vcc, s8, v58
	s_mov_b32 s8, 0x2080000
	s_nop 0
	v_addc_co_u32_e32 v31, vcc, 0, v59, vcc
	global_load_dwordx4 v[26:29], v[26:27], off nt
	s_nop 0
	global_load_dwordx4 v[30:33], v[30:31], off nt
	v_add_co_u32_e32 v34, vcc, s8, v58
	s_mov_b32 s8, 0x2084000
	s_nop 0
	v_addc_co_u32_e32 v35, vcc, 0, v59, vcc
	v_add_co_u32_e32 v38, vcc, s8, v58
	s_mov_b32 s8, 0x20a0000
	s_nop 0
	v_addc_co_u32_e32 v39, vcc, 0, v59, vcc
	global_load_dwordx4 v[34:37], v[34:35], off nt
	s_nop 0
	global_load_dwordx4 v[38:41], v[38:39], off nt
	v_add_co_u32_e32 v42, vcc, s8, v58
	s_mov_b32 s8, 0x20a4000
	s_nop 0
	v_addc_co_u32_e32 v43, vcc, 0, v59, vcc
	v_add_co_u32_e32 v46, vcc, s8, v58
	s_mov_b32 s8, 0x20c0000
	s_nop 0
	v_addc_co_u32_e32 v47, vcc, 0, v59, vcc
	global_load_dwordx4 v[42:45], v[42:43], off nt
	s_nop 0
	global_load_dwordx4 v[46:49], v[46:47], off nt
	v_add_co_u32_e32 v50, vcc, s8, v58
	s_mov_b32 s8, 0x20c4000
	s_nop 0
	v_addc_co_u32_e32 v51, vcc, 0, v59, vcc
	v_add_co_u32_e32 v54, vcc, s8, v58
	s_mov_b32 s8, 0x20e0000
	s_nop 0
	v_addc_co_u32_e32 v55, vcc, 0, v59, vcc
	global_load_dwordx4 v[50:53], v[50:51], off nt
	s_nop 0
	global_load_dwordx4 v[54:57], v[54:55], off nt
	v_add_co_u32_e32 v60, vcc, s8, v58
	s_mov_b32 s8, 0x20e4000
	s_nop 0
	v_addc_co_u32_e32 v61, vcc, 0, v59, vcc
	v_add_co_u32_e32 v62, vcc, s8, v58
	s_lshl_b32 s8, s12, 1
	s_nop 0
	v_addc_co_u32_e32 v63, vcc, 0, v59, vcc
	global_load_dwordx4 v[58:61], v[60:61], off nt
	s_nop 0
	global_load_dwordx4 v[62:65], v[62:63], off nt
	s_waitcnt vmcnt(14)
	v_cvt_pk_bf16_f32 v2, v2, v6
	v_add_u32_e32 v6, v73, v75
	ds_write_b32 v6, v2
	v_cvt_pk_bf16_f32 v2, v3, v7
	ds_write_b32 v6, v2 offset:128
	v_cvt_pk_bf16_f32 v2, v4, v8
	ds_write_b32 v6, v2 offset:256
	v_cvt_pk_bf16_f32 v2, v5, v9
	ds_write_b32 v6, v2 offset:384
	s_waitcnt vmcnt(12)
	v_cvt_pk_bf16_f32 v2, v10, v14
	v_add_u32_e32 v3, v76, v75
	ds_write_b32 v3, v2
	v_cvt_pk_bf16_f32 v2, v11, v15
	ds_write_b32 v3, v2 offset:128
	v_cvt_pk_bf16_f32 v2, v12, v16
	ds_write_b32 v3, v2 offset:256
	v_cvt_pk_bf16_f32 v2, v13, v17
	ds_write_b32 v3, v2 offset:384
	s_waitcnt vmcnt(10)
	v_cvt_pk_bf16_f32 v2, v18, v22
	v_add_u32_e32 v3, v77, v75
	ds_write_b32 v3, v2
	v_cvt_pk_bf16_f32 v2, v19, v23
	ds_write_b32 v3, v2 offset:128
	v_cvt_pk_bf16_f32 v2, v20, v24
	ds_write_b32 v3, v2 offset:256
	v_cvt_pk_bf16_f32 v2, v21, v25
	ds_write_b32 v3, v2 offset:384
	s_waitcnt vmcnt(8)
; #define LAS __attribute__((address_space(3)))
; #define LDS_WAIT() asm volatile("s_waitcnt lgkmcnt(0)" ::: "memory")
; __device__ __forceinline__ unsigned cvt_pk_bf16(float lo, float hi) { unsigned r; asm volatile("v_cvt_pk_bf16_f32 %0, %1, %2" : "=v"(r) : "v"(lo), "v"(hi)); return r; }
;     ...
; #pragma unroll
;     for (int i = 0; i < 8; ++i)
; #pragma unroll
;         for (int e = 0; e < 4; ++e) *(LAS unsigned*)(scr + (4 * r16 + e) * 128 + ((i ^ (r16 & 7)) * 16) + q * 4) = cvt_pk_bf16(v[2 * i][e], v[2 * i + 1][e]);
;     LDS_WAIT(); asm volatile("" ::: "memory");
;     const int c = lane & 7;
; #pragma unroll
;     for (int j = 0; j < 8; ++j) { const int row = (lane >> 3) + 8 * j; const u32x4 o = *(const LAS u32x4*)(scr + row * 128 + ((c ^ ((row >> 2) & 7)) * 16));
;         const int lc = col_off + n0 + row; int dr;
;         if (MODE == 0) dr = lc;
;         else if (MODE == 1) dr = (lc & ~255) + 128 * ((lc >> 5) & 1) + 32 * ((lc >> 6) & 3) + (lc & 31);
;         else if (MODE == 2) dr = 256 * (lc >> 7) + (lc & 127);
;         else dr = 256 * (lc >> 7) + 128 + (lc & 127);
;         *(u32x4*)(WT + (size_t)dr * (ldt ? ldt : K) + k0 + 8 * c) = o; }
;     LDS_WAIT(); asm volatile("" ::: "memory");
	v_cvt_pk_bf16_f32 v2, v26, v30
	v_add_u32_e32 v3, v78, v75
	ds_write_b32 v3, v2
	v_cvt_pk_bf16_f32 v2, v27, v31
	ds_write_b32 v3, v2 offset:128
	v_cvt_pk_bf16_f32 v2, v28, v32
	ds_write_b32 v3, v2 offset:256
	v_cvt_pk_bf16_f32 v2, v29, v33
	ds_write_b32 v3, v2 offset:384
	s_waitcnt vmcnt(6)
	v_cvt_pk_bf16_f32 v2, v34, v38
	v_add_u32_e32 v3, v79, v75
	ds_write_b32 v3, v2
	v_cvt_pk_bf16_f32 v2, v35, v39
	ds_write_b32 v3, v2 offset:128
	v_cvt_pk_bf16_f32 v2, v36, v40
	ds_write_b32 v3, v2 offset:256
	v_cvt_pk_bf16_f32 v2, v37, v41
	ds_write_b32 v3, v2 offset:384
	s_waitcnt vmcnt(4)
	v_cvt_pk_bf16_f32 v2, v42, v46
	v_add_u32_e32 v3, v80, v75
	ds_write_b32 v3, v2
	v_cvt_pk_bf16_f32 v2, v43, v47
	ds_write_b32 v3, v2 offset:128
	v_cvt_pk_bf16_f32 v2, v44, v48
	ds_write_b32 v3, v2 offset:256
	v_cvt_pk_bf16_f32 v2, v45, v49
	ds_write_b32 v3, v2 offset:384
	s_waitcnt vmcnt(2)
	v_cvt_pk_bf16_f32 v2, v50, v54
	v_add_u32_e32 v3, v81, v75
	ds_write_b32 v3, v2
	v_cvt_pk_bf16_f32 v2, v51, v55
	ds_write_b32 v3, v2 offset:128
	v_cvt_pk_bf16_f32 v2, v52, v56
	ds_write_b32 v3, v2 offset:256
	v_cvt_pk_bf16_f32 v2, v53, v57
	ds_write_b32 v3, v2 offset:384
	s_waitcnt vmcnt(0)
	v_cvt_pk_bf16_f32 v2, v58, v62
	v_add_u32_e32 v3, v82, v75
	ds_write_b32 v3, v2
	v_cvt_pk_bf16_f32 v2, v59, v63
	ds_write_b32 v3, v2 offset:128
	v_cvt_pk_bf16_f32 v2, v60, v64
	ds_write_b32 v3, v2 offset:256
	v_cvt_pk_bf16_f32 v2, v61, v65
	ds_write_b32 v3, v2 offset:384
	s_add_u32 s12, s1, s8
	s_waitcnt lgkmcnt(0)
	s_addc_u32 s13, s2, 0
	v_lshlrev_b32_e32 v2, 1, v72
	v_mov_b32_e32 v3, v71
	v_lshl_add_u64 v[10:11], s[12:13], 0, v[2:3]
	v_add_u32_e32 v2, v84, v85
	ds_read_b128 v[2:5], v2
	v_or_b32_e32 v6, s0, v83
	v_lshlrev_b32_e32 v6, 12, v6
	v_mov_b32_e32 v7, v71
	v_lshl_add_u64 v[12:13], v[10:11], 0, v[6:7]
	v_add_u32_e32 v6, v87, v88
	ds_read_b128 v[6:9], v6
	s_waitcnt lgkmcnt(1)
	global_store_dwordx4 v[12:13], v[2:5], off
	v_readlane_b32 s53, v250, 11
	v_readlane_b32 s54, v250, 12
	v_or_b32_e32 v2, s0, v86
	v_lshlrev_b32_e32 v2, 12, v2
	v_mov_b32_e32 v3, v71
	v_lshl_add_u64 v[2:3], v[10:11], 0, v[2:3]
	s_waitcnt lgkmcnt(0)
	global_store_dwordx4 v[2:3], v[6:9], off
	v_add_u32_e32 v2, v90, v91
	ds_read_b128 v[2:5], v2
	v_or_b32_e32 v6, s0, v89
	v_lshlrev_b32_e32 v6, 12, v6
	v_mov_b32_e32 v7, v71
	v_lshl_add_u64 v[12:13], v[10:11], 0, v[6:7]
	v_add_u32_e32 v6, v93, v94
	ds_read_b128 v[6:9], v6
	s_waitcnt lgkmcnt(1)
	global_store_dwordx4 v[12:13], v[2:5], off
	v_readlane_b32 s55, v250, 13
	v_readlane_b32 s56, v250, 14
	v_or_b32_e32 v2, s0, v92
	v_lshlrev_b32_e32 v2, 12, v2
	v_mov_b32_e32 v3, v71
	v_lshl_add_u64 v[2:3], v[10:11], 0, v[2:3]
	s_waitcnt lgkmcnt(0)
	global_store_dwordx4 v[2:3], v[6:9], off
	v_add_u32_e32 v2, v96, v85
	ds_read_b128 v[2:5], v2
	v_or_b32_e32 v6, s0, v95
	v_lshlrev_b32_e32 v6, 12, v6
	v_mov_b32_e32 v7, v71
	v_lshl_add_u64 v[12:13], v[10:11], 0, v[6:7]
	v_add_u32_e32 v6, v98, v99
	ds_read_b128 v[6:9], v6
	s_waitcnt lgkmcnt(1)
	global_store_dwordx4 v[12:13], v[2:5], off
	v_readlane_b32 s57, v250, 15
	v_readlane_b32 s58, v250, 16
	v_or_b32_e32 v2, s0, v97
	v_lshlrev_b32_e32 v2, 12, v2
	v_mov_b32_e32 v3, v71
	v_lshl_add_u64 v[2:3], v[10:11], 0, v[2:3]
	s_waitcnt lgkmcnt(0)
	global_store_dwordx4 v[2:3], v[6:9], off
	v_add_u32_e32 v2, v101, v102
	ds_read_b128 v[2:5], v2
	v_or_b32_e32 v6, s0, v100
	v_lshlrev_b32_e32 v6, 12, v6
	v_mov_b32_e32 v7, v71
	v_lshl_add_u64 v[12:13], v[10:11], 0, v[6:7]
	v_add_u32_e32 v6, v104, v105
	ds_read_b128 v[6:9], v6
	s_waitcnt lgkmcnt(1)
	global_store_dwordx4 v[12:13], v[2:5], off
	v_readlane_b32 s59, v250, 17
	v_readlane_b32 s60, v250, 18
	v_or_b32_e32 v2, s0, v103
	v_lshlrev_b32_e32 v2, 12, v2
	v_mov_b32_e32 v3, v71
	v_lshl_add_u64 v[2:3], v[10:11], 0, v[2:3]
	s_waitcnt lgkmcnt(0)
	global_store_dwordx4 v[2:3], v[6:9], off
	s_waitcnt lgkmcnt(0)
	v_readlane_b32 s61, v250, 19
	v_readlane_b32 s62, v250, 20
	v_readlane_b32 s63, v250, 21
	v_readlane_b32 s64, v250, 22
	v_readlane_b32 s65, v250, 23

; #define LAS __attribute__((address_space(3)))
; __device__ __forceinline__ unsigned cvt_pk_bf16(float lo, float hi) { unsigned r; asm volatile("v_cvt_pk_bf16_f32 %0, %1, %2" : "=v"(r) : "v"(lo), "v"(hi)); return r; }
;     const int nblk = N / 64, kb = item / nblk, nb = item % nblk, k0 = 64 * kb, n0 = 64 * nb;
;     const int r16 = lane & 15, q = lane >> 4;
;     const float* src = W + (size_t)(k0 + 2 * q) * N + n0 + 4 * r16;
;     f32x4 v[16];
; #pragma unroll
;     for (int j = 0; j < 16; ++j) v[j] = *(const f32x4*)(src + (size_t)(8 * (j >> 1) + (j & 1)) * N);
;     if (nscale) { const f32x4 ns = *(const f32x4*)(nscale + n0 + 4 * r16);
; #pragma unroll
;         for (int j = 0; j < 16; ++j) v[j] = v[j] * ns; }
;     if (kscale) {
; #pragma unroll
;         for (int i = 0; i < 8; ++i) { const f32x2 g = *(const f32x2*)(kscale + k0 + 8 * i + 2 * q); v[2 * i] = v[2 * i] * g[0]; v[2 * i + 1] = v[2 * i + 1] * g[1]; } }
; #pragma unroll
;     for (int i = 0; i < 8; ++i)
; #pragma unroll
;         for (int e = 0; e < 4; ++e) *(LAS unsigned*)(scr + (4 * r16 + e) * 128 + ((i ^ (r16 & 7)) * 16) + q * 4) = cvt_pk_bf16(v[2 * i][e], v[2 * i + 1][e]);
.LBB0_32:
	s_andn2_b64 vcc, exec, s[0:1]
	s_cbranch_vccnz .LBB0_34
	v_readlane_b32 s52, v250, 10
	s_lshl_b64 s[0:1], s[10:11], 26
	v_readlane_b32 s66, v250, 24
	v_readlane_b32 s67, v250, 25
	s_add_u32 s12, s66, s0
	s_addc_u32 s13, s67, s1
	s_add_i32 s0, s49, 0xee00
	s_and_b32 s1, s0, 0xffc0
	s_lshl_b32 s0, s49, 6
	v_lshlrev_b32_e32 v2, 2, v67
	s_and_b32 s0, s0, 0xfc0
	v_lshl_or_b32 v2, s1, 14, v2
	v_mov_b32_e32 v3, v71
	v_lshl_add_u64 v[2:3], s[12:13], 0, v[2:3]
	s_lshl_b32 s8, s0, 2
	v_lshl_add_u64 v[2:3], v[2:3], 0, s[8:9]
	v_lshl_add_u64 v[58:59], v[2:3], 0, v[70:71]
	v_add_co_u32_e32 v6, vcc, s39, v58
	s_mov_b32 s2, 0x20000
	s_nop 0
	v_addc_co_u32_e32 v7, vcc, 0, v59, vcc
	global_load_dwordx4 v[2:5], v[58:59], off nt
	s_nop 0
	global_load_dwordx4 v[6:9], v[6:7], off nt
	v_add_co_u32_e32 v10, vcc, s2, v58
	s_mov_b32 s2, 0x40000
	s_nop 0
	v_addc_co_u32_e32 v11, vcc, 0, v59, vcc
	v_add_co_u32_e32 v14, vcc, s45, v58
	s_lshl_b32 s1, s1, 1
	s_nop 0
	v_addc_co_u32_e32 v15, vcc, 0, v59, vcc
	global_load_dwordx4 v[10:13], v[10:11], off nt
	s_nop 0
	global_load_dwordx4 v[14:17], v[14:15], off nt
	v_add_co_u32_e32 v18, vcc, s2, v58
	s_mov_b32 s2, 0x44000
	s_nop 0
	v_addc_co_u32_e32 v19, vcc, 0, v59, vcc
	v_add_co_u32_e32 v22, vcc, s2, v58
	s_mov_b32 s2, 0x60000
	s_nop 0
	v_addc_co_u32_e32 v23, vcc, 0, v59, vcc
	global_load_dwordx4 v[18:21], v[18:19], off nt
	s_nop 0
	global_load_dwordx4 v[22:25], v[22:23], off nt
	v_add_co_u32_e32 v26, vcc, s2, v58
	s_mov_b32 s2, 0x64000
	s_nop 0
	v_addc_co_u32_e32 v27, vcc, 0, v59, vcc
	v_add_co_u32_e32 v30, vcc, s2, v58
	s_mov_b32 s2, 0x80000
	s_nop 0
	v_addc_co_u32_e32 v31, vcc, 0, v59, vcc
	global_load_dwordx4 v[26:29], v[26:27], off nt
	s_nop 0
	global_load_dwordx4 v[30:33], v[30:31], off nt
	v_add_co_u32_e32 v34, vcc, s2, v58
	s_mov_b32 s2, 0x84000
	s_nop 0
	v_addc_co_u32_e32 v35, vcc, 0, v59, vcc
	v_add_co_u32_e32 v38, vcc, s2, v58
	s_mov_b32 s2, 0xa0000
	s_nop 0
	v_addc_co_u32_e32 v39, vcc, 0, v59, vcc
	global_load_dwordx4 v[34:37], v[34:35], off nt
	s_nop 0
	global_load_dwordx4 v[38:41], v[38:39], off nt
	v_add_co_u32_e32 v42, vcc, s2, v58
	s_mov_b32 s2, 0xa4000
	s_nop 0
	v_addc_co_u32_e32 v43, vcc, 0, v59, vcc
	v_add_co_u32_e32 v46, vcc, s2, v58
	s_mov_b32 s2, 0xc0000
	s_nop 0
	v_addc_co_u32_e32 v47, vcc, 0, v59, vcc
	global_load_dwordx4 v[42:45], v[42:43], off nt
	s_nop 0
	global_load_dwordx4 v[46:49], v[46:47], off nt
	v_add_co_u32_e32 v50, vcc, s2, v58
	s_mov_b32 s2, 0xc4000
	s_nop 0
	v_addc_co_u32_e32 v51, vcc, 0, v59, vcc
	v_add_co_u32_e32 v54, vcc, s2, v58
	s_mov_b32 s2, 0xe0000
	s_nop 0
	v_addc_co_u32_e32 v55, vcc, 0, v59, vcc
	global_load_dwordx4 v[50:53], v[50:51], off nt
	s_nop 0
	global_load_dwordx4 v[54:57], v[54:55], off nt
	v_add_co_u32_e32 v60, vcc, s2, v58
	s_mov_b32 s2, 0xe4000
	s_nop 0
	v_addc_co_u32_e32 v61, vcc, 0, v59, vcc
	v_add_co_u32_e32 v62, vcc, s2, v58
	s_add_u32 s12, s47, s1
	s_nop 0
	v_addc_co_u32_e32 v63, vcc, 0, v59, vcc
	global_load_dwordx4 v[58:61], v[60:61], off nt
	s_nop 0
	global_load_dwordx4 v[62:65], v[62:63], off nt
	s_waitcnt vmcnt(14)
	v_cvt_pk_bf16_f32 v2, v2, v6
	v_add_u32_e32 v6, v73, v75
	ds_write_b32 v6, v2
	v_cvt_pk_bf16_f32 v2, v3, v7
	ds_write_b32 v6, v2 offset:128
	v_cvt_pk_bf16_f32 v2, v4, v8
	ds_write_b32 v6, v2 offset:256
	v_cvt_pk_bf16_f32 v2, v5, v9
	ds_write_b32 v6, v2 offset:384
	s_waitcnt vmcnt(12)
	v_cvt_pk_bf16_f32 v2, v10, v14
	v_add_u32_e32 v3, v76, v75
	ds_write_b32 v3, v2
	v_cvt_pk_bf16_f32 v2, v11, v15
	ds_write_b32 v3, v2 offset:128
	v_cvt_pk_bf16_f32 v2, v12, v16
	ds_write_b32 v3, v2 offset:256
	v_cvt_pk_bf16_f32 v2, v13, v17
	ds_write_b32 v3, v2 offset:384
	s_waitcnt vmcnt(10)
	v_cvt_pk_bf16_f32 v2, v18, v22
	v_add_u32_e32 v3, v77, v75
	ds_write_b32 v3, v2
	v_cvt_pk_bf16_f32 v2, v19, v23
	ds_write_b32 v3, v2 offset:128
	v_cvt_pk_bf16_f32 v2, v20, v24
	ds_write_b32 v3, v2 offset:256
	v_cvt_pk_bf16_f32 v2, v21, v25
	ds_write_b32 v3, v2 offset:384
	s_waitcnt vmcnt(8)
; #define LAS __attribute__((address_space(3)))
; #define LDS_WAIT() asm volatile("s_waitcnt lgkmcnt(0)" ::: "memory")
; __device__ __forceinline__ unsigned cvt_pk_bf16(float lo, float hi) { unsigned r; asm volatile("v_cvt_pk_bf16_f32 %0, %1, %2" : "=v"(r) : "v"(lo), "v"(hi)); return r; }
;     ...
; #pragma unroll
;     for (int i = 0; i < 8; ++i)
; #pragma unroll
;         for (int e = 0; e < 4; ++e) *(LAS unsigned*)(scr + (4 * r16 + e) * 128 + ((i ^ (r16 & 7)) * 16) + q * 4) = cvt_pk_bf16(v[2 * i][e], v[2 * i + 1][e]);
;     LDS_WAIT(); asm volatile("" ::: "memory");
;     const int c = lane & 7;
; #pragma unroll
;     for (int j = 0; j < 8; ++j) { const int row = (lane >> 3) + 8 * j; const u32x4 o = *(const LAS u32x4*)(scr + row * 128 + ((c ^ ((row >> 2) & 7)) * 16));
;         const int lc = col_off + n0 + row; int dr;
;         if (MODE == 0) dr = lc;
;         else if (MODE == 1) dr = (lc & ~255) + 128 * ((lc >> 5) & 1) + 32 * ((lc >> 6) & 3) + (lc & 31);
;         else if (MODE == 2) dr = 256 * (lc >> 7) + (lc & 127);
;         else dr = 256 * (lc >> 7) + 128 + (lc & 127);
;         *(u32x4*)(WT + (size_t)dr * (ldt ? ldt : K) + k0 + 8 * c) = o; }
;     LDS_WAIT(); asm volatile("" ::: "memory");
	v_cvt_pk_bf16_f32 v2, v26, v30
	v_add_u32_e32 v3, v78, v75
	ds_write_b32 v3, v2
	v_cvt_pk_bf16_f32 v2, v27, v31
	ds_write_b32 v3, v2 offset:128
	v_cvt_pk_bf16_f32 v2, v28, v32
	ds_write_b32 v3, v2 offset:256
	v_cvt_pk_bf16_f32 v2, v29, v33
	ds_write_b32 v3, v2 offset:384
	s_waitcnt vmcnt(6)
	v_cvt_pk_bf16_f32 v2, v34, v38
	v_add_u32_e32 v3, v79, v75
	ds_write_b32 v3, v2
	v_cvt_pk_bf16_f32 v2, v35, v39
	ds_write_b32 v3, v2 offset:128
	v_cvt_pk_bf16_f32 v2, v36, v40
	ds_write_b32 v3, v2 offset:256
	v_cvt_pk_bf16_f32 v2, v37, v41
	ds_write_b32 v3, v2 offset:384
	s_waitcnt vmcnt(4)
	v_cvt_pk_bf16_f32 v2, v42, v46
	v_add_u32_e32 v3, v80, v75
	ds_write_b32 v3, v2
	v_cvt_pk_bf16_f32 v2, v43, v47
	ds_write_b32 v3, v2 offset:128
	v_cvt_pk_bf16_f32 v2, v44, v48
	ds_write_b32 v3, v2 offset:256
	v_cvt_pk_bf16_f32 v2, v45, v49
	ds_write_b32 v3, v2 offset:384
	s_waitcnt vmcnt(2)
	v_cvt_pk_bf16_f32 v2, v50, v54
	v_add_u32_e32 v3, v81, v75
	ds_write_b32 v3, v2
	v_cvt_pk_bf16_f32 v2, v51, v55
	ds_write_b32 v3, v2 offset:128
	v_cvt_pk_bf16_f32 v2, v52, v56
	ds_write_b32 v3, v2 offset:256
	v_cvt_pk_bf16_f32 v2, v53, v57
	ds_write_b32 v3, v2 offset:384
	s_waitcnt vmcnt(0)
	v_cvt_pk_bf16_f32 v2, v58, v62
	v_add_u32_e32 v3, v82, v75
	ds_write_b32 v3, v2
	v_cvt_pk_bf16_f32 v2, v59, v63
	ds_write_b32 v3, v2 offset:128
	v_cvt_pk_bf16_f32 v2, v60, v64
	ds_write_b32 v3, v2 offset:256
	v_cvt_pk_bf16_f32 v2, v61, v65
	ds_write_b32 v3, v2 offset:384
	s_addc_u32 s13, s48, 0
	v_lshlrev_b32_e32 v2, 1, v72
	v_mov_b32_e32 v3, v71
	s_waitcnt lgkmcnt(0)
	v_lshl_add_u64 v[2:3], s[12:13], 0, v[2:3]
	s_mov_b64 s[12:13], 0x2600000
	v_lshl_add_u64 v[10:11], v[2:3], 0, s[12:13]
	v_add_u32_e32 v2, v84, v85
	ds_read_b128 v[2:5], v2
	v_or_b32_e32 v6, s0, v83
	v_lshlrev_b32_e32 v6, 13, v6
	v_mov_b32_e32 v7, v71
	v_lshl_add_u64 v[12:13], v[10:11], 0, v[6:7]
	v_add_u32_e32 v6, v87, v88
	ds_read_b128 v[6:9], v6
	s_waitcnt lgkmcnt(1)
	global_store_dwordx4 v[12:13], v[2:5], off
	v_readlane_b32 s53, v250, 11
	v_readlane_b32 s54, v250, 12
	v_or_b32_e32 v2, s0, v86
	v_lshlrev_b32_e32 v2, 13, v2
	v_mov_b32_e32 v3, v71
	v_lshl_add_u64 v[2:3], v[10:11], 0, v[2:3]
	s_waitcnt lgkmcnt(0)
	global_store_dwordx4 v[2:3], v[6:9], off
	v_add_u32_e32 v2, v90, v91
	ds_read_b128 v[2:5], v2
	v_or_b32_e32 v6, s0, v89
	v_lshlrev_b32_e32 v6, 13, v6
	v_mov_b32_e32 v7, v71
	v_lshl_add_u64 v[12:13], v[10:11], 0, v[6:7]
	v_add_u32_e32 v6, v93, v94
	ds_read_b128 v[6:9], v6
	s_waitcnt lgkmcnt(1)
	global_store_dwordx4 v[12:13], v[2:5], off
	v_readlane_b32 s55, v250, 13
	v_readlane_b32 s56, v250, 14
	v_or_b32_e32 v2, s0, v92
	v_lshlrev_b32_e32 v2, 13, v2
	v_mov_b32_e32 v3, v71
	v_lshl_add_u64 v[2:3], v[10:11], 0, v[2:3]
	s_waitcnt lgkmcnt(0)
	global_store_dwordx4 v[2:3], v[6:9], off
	v_add_u32_e32 v2, v96, v85
	ds_read_b128 v[2:5], v2
	v_or_b32_e32 v6, s0, v95
	v_lshlrev_b32_e32 v6, 13, v6
	v_mov_b32_e32 v7, v71
	v_lshl_add_u64 v[12:13], v[10:11], 0, v[6:7]
	v_add_u32_e32 v6, v98, v99
	ds_read_b128 v[6:9], v6
	s_waitcnt lgkmcnt(1)
	global_store_dwordx4 v[12:13], v[2:5], off
	v_readlane_b32 s57, v250, 15
	v_readlane_b32 s58, v250, 16
	v_or_b32_e32 v2, s0, v97
	v_lshlrev_b32_e32 v2, 13, v2
	v_mov_b32_e32 v3, v71
	v_lshl_add_u64 v[2:3], v[10:11], 0, v[2:3]
	s_waitcnt lgkmcnt(0)
	global_store_dwordx4 v[2:3], v[6:9], off
	v_add_u32_e32 v2, v101, v102
	ds_read_b128 v[2:5], v2
	v_or_b32_e32 v6, s0, v100
	v_lshlrev_b32_e32 v6, 13, v6
	v_mov_b32_e32 v7, v71
	v_lshl_add_u64 v[12:13], v[10:11], 0, v[6:7]
	v_add_u32_e32 v6, v104, v105
	ds_read_b128 v[6:9], v6
	s_waitcnt lgkmcnt(1)
	global_store_dwordx4 v[12:13], v[2:5], off
	v_readlane_b32 s59, v250, 17
	v_readlane_b32 s60, v250, 18
	v_or_b32_e32 v2, s0, v103
	v_lshlrev_b32_e32 v2, 13, v2
	v_mov_b32_e32 v3, v71
	v_lshl_add_u64 v[2:3], v[10:11], 0, v[2:3]
	s_waitcnt lgkmcnt(0)
	global_store_dwordx4 v[2:3], v[6:9], off
	s_waitcnt lgkmcnt(0)
	v_readlane_b32 s61, v250, 19
	v_readlane_b32 s62, v250, 20
	v_readlane_b32 s63, v250, 21
	v_readlane_b32 s64, v250, 22
	v_readlane_b32 s65, v250, 23

;     const int nblk = N / 64, kb = item / nblk, nb = item % nblk, k0 = 64 * kb, n0 = 64 * nb;
;     const int r16 = lane & 15, q = lane >> 4;
;     const float* src = W + (size_t)(k0 + 2 * q) * N + n0 + 4 * r16;
;     f32x4 v[16];
; #pragma unroll
;     for (int j = 0; j < 16; ++j) v[j] = *(const f32x4*)(src + (size_t)(8 * (j >> 1) + (j & 1)) * N);
;     if (nscale) { const f32x4 ns = *(const f32x4*)(nscale + n0 + 4 * r16);
; #pragma unroll
;         for (int j = 0; j < 16; ++j) v[j] = v[j] * ns; }
;     if (kscale) {
; #pragma unroll
;         for (int i = 0; i < 8; ++i) { const f32x2 g = *(const f32x2*)(kscale + k0 + 8 * i + 2 * q); v[2 * i] = v[2 * i] * g[0]; v[2 * i + 1] = v[2 * i + 1] * g[1]; } }
.LBB0_35:
	s_andn2_b64 vcc, exec, s[12:13]
	s_cbranch_vccnz .LBB0_10
	v_readlane_b32 s52, v250, 10
	s_mul_i32 s2, s10, 0x4800000
	v_readlane_b32 s54, v250, 12
	s_mul_hi_i32 s1, s10, 0x4800000
	v_readlane_b32 s55, v250, 13
	s_add_u32 s14, s54, s2
	s_addc_u32 s15, s55, s1
	s_mul_hi_i32 s1, s49, 0x38e38e39
	s_lshr_b32 s2, s1, 31
	s_ashr_i32 s1, s1, 4
	s_add_i32 s1, s1, s2
	s_mul_i32 s0, s10, 0xab00
	s_mul_i32 s2, s1, 0xffffffb8
	s_lshl_b32 s12, s1, 6
	s_sub_i32 s0, s2, s0
	v_or_b32_e32 v2, s12, v74
	s_movk_i32 s1, 0x1200
	s_add_i32 s0, s46, s0
	v_mul_lo_u32 v2, v2, s1
	s_lshl_b32 s0, s0, 6
	v_ashrrev_i32_e32 v3, 31, v2
	v_lshl_add_u64 v[2:3], v[2:3], 2, s[14:15]
	s_ashr_i32 s1, s0, 31
	v_lshl_add_u64 v[2:3], s[0:1], 2, v[2:3]
	v_lshl_add_u64 v[2:3], v[2:3], 0, v[70:71]
	v_add_co_u32_e32 v4, vcc, s39, v2
	s_mov_b32 s1, 0x28000
	s_nop 0
	v_addc_co_u32_e32 v5, vcc, 0, v3, vcc
	global_load_dwordx4 v[58:61], v[2:3], off nt
	global_load_dwordx4 v[62:65], v[4:5], off offset:2048 nt
	v_add_co_u32_e32 v4, vcc, s45, v2
	v_readlane_b32 s53, v250, 11
	s_nop 0
	v_addc_co_u32_e32 v5, vcc, 0, v3, vcc
	v_add_co_u32_e32 v6, vcc, s1, v2
	s_mov_b32 s1, 0x48000
	s_nop 0
	v_addc_co_u32_e32 v7, vcc, 0, v3, vcc
	global_load_dwordx4 v[50:53], v[4:5], off nt
	global_load_dwordx4 v[54:57], v[6:7], off offset:2048 nt
	v_add_co_u32_e32 v4, vcc, s1, v2
	s_mov_b32 s1, 0x4c000
	s_nop 0
	v_addc_co_u32_e32 v5, vcc, 0, v3, vcc
	v_add_co_u32_e32 v6, vcc, s1, v2
	s_mov_b32 s1, 0x6c000
	s_nop 0
	v_addc_co_u32_e32 v7, vcc, 0, v3, vcc
	global_load_dwordx4 v[42:45], v[4:5], off nt
	global_load_dwordx4 v[46:49], v[6:7], off offset:2048 nt
	v_add_co_u32_e32 v4, vcc, s1, v2
	s_mov_b32 s1, 0x70000
	s_nop 0
	v_addc_co_u32_e32 v5, vcc, 0, v3, vcc
	v_add_co_u32_e32 v6, vcc, s1, v2
	s_mov_b32 s1, 0x90000
	s_nop 0
	v_addc_co_u32_e32 v7, vcc, 0, v3, vcc
	global_load_dwordx4 v[26:29], v[4:5], off nt
	global_load_dwordx4 v[38:41], v[6:7], off offset:2048 nt
	v_add_co_u32_e32 v4, vcc, s1, v2
	s_mov_b32 s1, 0x94000
	s_nop 0
	v_addc_co_u32_e32 v5, vcc, 0, v3, vcc
	v_add_co_u32_e32 v6, vcc, s1, v2
	s_mov_b32 s1, 0xb4000
	s_nop 0
	v_addc_co_u32_e32 v7, vcc, 0, v3, vcc
	global_load_dwordx4 v[18:21], v[4:5], off nt
	global_load_dwordx4 v[34:37], v[6:7], off offset:2048 nt
	v_add_co_u32_e32 v4, vcc, s1, v2
	s_mov_b32 s1, 0xb8000
	s_nop 0
	v_addc_co_u32_e32 v5, vcc, 0, v3, vcc
	v_add_co_u32_e32 v6, vcc, s1, v2
	s_ashr_i32 s13, s12, 31
	s_nop 0
	v_addc_co_u32_e32 v7, vcc, 0, v3, vcc
	global_load_dwordx4 v[14:17], v[4:5], off nt
	global_load_dwordx4 v[30:33], v[6:7], off offset:2048 nt
	v_add_co_u32_e32 v4, vcc, 0xd8000, v2
	v_readlane_b32 s56, v250, 14
	s_nop 0
	v_addc_co_u32_e32 v5, vcc, 0, v3, vcc
	v_add_co_u32_e32 v10, vcc, 0xdc000, v2
	v_readlane_b32 s57, v250, 15
	s_nop 0
	v_addc_co_u32_e32 v11, vcc, 0, v3, vcc
	global_load_dwordx4 v[6:9], v[4:5], off nt
	global_load_dwordx4 v[22:25], v[10:11], off offset:2048 nt
	v_add_co_u32_e32 v4, vcc, 0xfc000, v2
	v_readlane_b32 s58, v250, 16
	s_nop 0
	v_addc_co_u32_e32 v5, vcc, 0, v3, vcc
	v_add_co_u32_e32 v10, vcc, 0x100000, v2
	v_readlane_b32 s59, v250, 17
	s_nop 0
	v_addc_co_u32_e32 v11, vcc, 0, v3, vcc
	global_load_dwordx4 v[2:5], v[4:5], off nt
	s_nop 0
	global_load_dwordx4 v[10:13], v[10:11], off offset:2048 nt
	s_andn2_b64 vcc, exec, s[6:7]
	v_readlane_b32 s60, v250, 18
	v_readlane_b32 s61, v250, 19
	v_readlane_b32 s62, v250, 20
	v_readlane_b32 s63, v250, 21
	v_readlane_b32 s64, v250, 22
	v_readlane_b32 s65, v250, 23
	v_readlane_b32 s66, v250, 24
	v_readlane_b32 s67, v250, 25
	s_cbranch_vccnz .LBB0_9
	s_lshl_b32 s10, s10, 12
	s_ashr_i32 s11, s10, 31
	s_lshl_b64 s[10:11], s[10:11], 2
	s_add_u32 s1, s52, s10
	s_addc_u32 s2, s53, s11
	s_lshl_b64 s[10:11], s[12:13], 2
	s_add_u32 s10, s1, s10
	s_addc_u32 s11, s2, s11
	global_load_dwordx2 v[114:115], v107, s[10:11]
	s_waitcnt vmcnt(0)
	v_pk_mul_f32 v[60:61], v[60:61], v[114:115] op_sel_hi:[1,0]
	v_pk_mul_f32 v[58:59], v[58:59], v[114:115] op_sel_hi:[1,0]
	v_pk_mul_f32 v[64:65], v[64:65], v[114:115] op_sel:[0,1]
	v_pk_mul_f32 v[62:63], v[62:63], v[114:115] op_sel:[0,1]
	global_load_dwordx2 v[114:115], v107, s[10:11] offset:32
	s_waitcnt vmcnt(0)
	v_pk_mul_f32 v[52:53], v[52:53], v[114:115] op_sel_hi:[1,0]
	v_pk_mul_f32 v[50:51], v[50:51], v[114:115] op_sel_hi:[1,0]
	v_pk_mul_f32 v[56:57], v[56:57], v[114:115] op_sel:[0,1]
	v_pk_mul_f32 v[54:55], v[54:55], v[114:115] op_sel:[0,1]
	global_load_dwordx2 v[114:115], v107, s[10:11] offset:64
	s_waitcnt vmcnt(0)
	v_pk_mul_f32 v[44:45], v[44:45], v[114:115] op_sel_hi:[1,0]
	v_pk_mul_f32 v[42:43], v[42:43], v[114:115] op_sel_hi:[1,0]
	v_pk_mul_f32 v[48:49], v[48:49], v[114:115] op_sel:[0,1]
	v_pk_mul_f32 v[46:47], v[46:47], v[114:115] op_sel:[0,1]
	global_load_dwordx2 v[114:115], v107, s[10:11] offset:96
	s_waitcnt vmcnt(0)
	v_pk_mul_f32 v[28:29], v[28:29], v[114:115] op_sel_hi:[1,0]
	v_pk_mul_f32 v[26:27], v[26:27], v[114:115] op_sel_hi:[1,0]
	v_pk_mul_f32 v[40:41], v[40:41], v[114:115] op_sel:[0,1]
	v_pk_mul_f32 v[38:39], v[38:39], v[114:115] op_sel:[0,1]
	global_load_dwordx2 v[114:115], v107, s[10:11] offset:128
	s_waitcnt vmcnt(0)
	v_pk_mul_f32 v[20:21], v[20:21], v[114:115] op_sel_hi:[1,0]
	v_pk_mul_f32 v[18:19], v[18:19], v[114:115] op_sel_hi:[1,0]
	v_pk_mul_f32 v[36:37], v[36:37], v[114:115] op_sel:[0,1]
	v_pk_mul_f32 v[34:35], v[34:35], v[114:115] op_sel:[0,1]
	global_load_dwordx2 v[114:115], v107, s[10:11] offset:160
	s_waitcnt vmcnt(0)
	v_pk_mul_f32 v[16:17], v[16:17], v[114:115] op_sel_hi:[1,0]
	v_pk_mul_f32 v[14:15], v[14:15], v[114:115] op_sel_hi:[1,0]
	v_pk_mul_f32 v[32:33], v[32:33], v[114:115] op_sel:[0,1]
	v_pk_mul_f32 v[30:31], v[30:31], v[114:115] op_sel:[0,1]
	global_load_dwordx2 v[114:115], v107, s[10:11] offset:192
	s_waitcnt vmcnt(0)
	v_pk_mul_f32 v[8:9], v[8:9], v[114:115] op_sel_hi:[1,0]
	v_pk_mul_f32 v[6:7], v[6:7], v[114:115] op_sel_hi:[1,0]
	v_pk_mul_f32 v[24:25], v[24:25], v[114:115] op_sel:[0,1]
	v_pk_mul_f32 v[22:23], v[22:23], v[114:115] op_sel:[0,1]
	global_load_dwordx2 v[114:115], v107, s[10:11] offset:224
	s_waitcnt vmcnt(0)
	v_pk_mul_f32 v[4:5], v[4:5], v[114:115] op_sel_hi:[1,0]
	v_pk_mul_f32 v[2:3], v[2:3], v[114:115] op_sel_hi:[1,0]
	v_pk_mul_f32 v[12:13], v[12:13], v[114:115] op_sel:[0,1]
	v_pk_mul_f32 v[10:11], v[10:11], v[114:115] op_sel:[0,1]
	s_branch .LBB0_9

; __device__ __forceinline__ void weights_pass(const Args& a, LAS unsigned char* scr, int gw, int NGW, int lane, int pass) {
;     ...
;     for (int it = gw + (pass == 1 ? PER_LAYER : 0); it < (pass == 2 ? PER_LAYER : 2 * PER_LAYER); it += NGW) {
;         const int l = it / PER_LAYER; int r = it % PER_LAYER;
;         { const bool shared = (r >= I_IN + I_OUT / 2 && r < I_IN + I_OUT) || (r >= I_IN + I_OUT + I_QM && r < I_IN + I_OUT + 3 * I_QM);
;           const int ip = (shared || (l == 0 && r < I_IN)) ? 0 : (l == 0 ? 2 : 1);
;           if (ip != pass) continue; }
;         unsigned char* wl = ws + WS_W + (size_t)l * WL_SIZE;
;         if (r < I_IN) { transpose_item<1>(a.in[I_WIN] + (size_t)l * DM * INW, DM, INW, (bf16_t*)(wl + WL_IN), a.in[I_GMIX] + l * DM, nullptr, 0, scr, r, lane); continue; } r -= I_IN;
;         if (r < I_OUT / 2) { transpose_item<0>(a.in[I_WOUT] + (size_t)l * DM * DM, 2048, DM, (bf16_t*)(wl + WL_OUT), nullptr, nullptr, 0, scr, r, lane, DM); continue; } r -= I_OUT / 2;
;         if (r < I_OUT / 2) { transpose_item<0>(a.in[I_WOUT] + (size_t)l * DM * DM + (size_t)2048 * DM, 2048, DM, (bf16_t*)(ws + WS_WLOW) + (size_t)l * DM * 2048, nullptr, nullptr, 0, scr, r, lane); continue; } r -= I_OUT / 2;
;         if (r < I_QM) { transpose_item<0>(a.in[I_WQM] + (size_t)l * DM * MW, DM, MW, (bf16_t*)(wl + WL_Q), a.in[I_GCROSS] + l * DM, nullptr, 0, scr, r, lane); continue; } r -= I_QM;
;         if (r < I_QM) { transpose_item<1>(a.in[I_WKM] + (size_t)l * DM * MW, DM, MW, (bf16_t*)(ws + WS_WKV) + (size_t)l * 1024 * DM, a.in[I_GMEM] + l * DM, nullptr, 0, scr, r, lane); continue; } r -= I_QM;
;         if (r < I_QM) { transpose_item<1>(a.in[I_WVM] + (size_t)l * DM * MW, DM, MW, (bf16_t*)(ws + WS_WKV) + (size_t)l * 1024 * DM, a.in[I_GMEM] + l * DM, nullptr, 512, scr, r, lane); continue; } r -= I_QM;
;         if (r < I_OMI) { transpose_item<0>(a.in[I_WOM] + (size_t)l * MW * DM, MW, DM, (bf16_t*)(wl + WL_OM), nullptr, nullptr, 0, scr, r, lane); continue; } r -= I_OMI;
;         if (r < I_G) { transpose_item<2>(a.in[I_WGATE] + (size_t)l * DM * DFF, DM, DFF, (bf16_t*)(wl + WL_GU), a.in[I_GFFN] + l * DM, nullptr, 0, scr, r, lane); continue; } r -= I_G;
;         if (r < I_G) { transpose_item<3>(a.in[I_WUP] + (size_t)l * DM * DFF, DM, DFF, (bf16_t*)(wl + WL_GU), a.in[I_GFFN] + l * DM, nullptr, 0, scr, r, lane); continue; } r -= I_G;
.LBB0_625:
	s_mul_hi_i32 s0, s8, 0xbfa02fe9
	s_add_i32 s0, s0, s8
	s_lshr_b32 s1, s0, 31
	s_ashr_i32 s0, s0, 15
	s_add_i32 s0, s0, s1
	s_mul_i32 s1, s0, 0xffff5500
	s_add_i32 s20, s8, s1
	s_add_i32 s21, s20, 0xffffe600
	s_cmpk_gt_u32 s21, 0x7ff
	s_cselect_b64 s[2:3], -1, 0
	s_and_b32 s1, s20, 0xfffffc00
	s_cmpk_lg_i32 s1, 0x2400
	s_cselect_b64 s[4:5], -1, 0
	s_and_b64 s[2:3], s[2:3], s[4:5]
	s_cmp_gt_i32 s8, 0xffff5500
	s_cselect_b64 s[4:5], -1, 0
	s_cmpk_gt_i32 s20, 0x11ff
	s_cselect_b64 s[6:7], -1, 0
	s_and_b64 s[4:5], s[4:5], s[6:7]
	s_and_b64 s[2:3], s[2:3], s[4:5]
	s_andn2_b64 vcc, exec, s[2:3]
	s_cbranch_vccnz .LBB0_624
	s_ashr_i32 s1, s0, 31
	s_mul_i32 s3, s0, 0x15000000
	v_readlane_b32 s4, v251, 12
	s_mul_hi_i32 s2, s0, 0x15000000
	s_add_u32 s18, s4, s3
	v_readlane_b32 s3, v251, 13
	s_addc_u32 s19, s3, s2
	s_cmpk_gt_u32 s20, 0x19ff
	s_mov_b64 s[4:5], -1
	s_cbranch_scc0 .LBB0_666
	s_cmpk_gt_u32 s20, 0x21ff
	s_cbranch_scc0 .LBB0_663
	s_cmpk_gt_u32 s20, 0x23ff
	s_cbranch_scc0 .LBB0_658
	s_cmpk_gt_u32 s20, 0x25ff
	s_cbranch_scc0 .LBB0_653
	s_cmpk_gt_u32 s20, 0x27ff
	s_cbranch_scc0 .LBB0_648
	s_cmpk_gt_u32 s20, 0x29ff
	s_cbranch_scc0 .LBB0_645
	s_cmpk_gt_u32 s20, 0x54ff
	s_mul_hi_i32 s2, s0, 0xac00000
	s_mul_i32 s3, s0, 0xac00000
	s_cbranch_scc0 .LBB0_640
	s_cmpk_gt_u32 s20, 0x7fff
	s_cbranch_scc0 .LBB0_635
	v_readlane_b32 s36, v250, 0
	v_readlane_b32 s42, v250, 6
	v_readlane_b32 s43, v250, 7
	s_add_u32 s6, s42, s3
	s_addc_u32 s7, s43, s2
	s_and_b32 s4, s20, 0xffc0
	s_xor_b32 s5, s4, 0x8000
	s_lshl_b32 s4, s20, 6
	v_lshlrev_b32_e32 v4, 2, v69
	s_and_b32 s4, s4, 0xfc0
	v_lshl_or_b32 v4, s5, 14, v4
	v_mov_b32_e32 v5, v2
	v_lshl_add_u64 v[4:5], s[6:7], 0, v[4:5]
	s_lshl_b32 s14, s4, 2
	v_lshl_add_u64 v[4:5], v[4:5], 0, s[14:15]
	v_lshlrev_b32_e32 v6, 2, v68
	v_mov_b32_e32 v7, v2
	v_lshl_add_u64 v[60:61], v[4:5], 0, v[6:7]
	s_movk_i32 s6, 0x4000
	v_add_co_u32_e32 v8, vcc, s6, v60
	s_mov_b32 s6, 0x24000
	s_nop 0
	v_addc_co_u32_e32 v9, vcc, 0, v61, vcc
	global_load_dwordx4 v[4:7], v[60:61], off nt
	s_nop 0
	global_load_dwordx4 v[8:11], v[8:9], off nt
	v_add_co_u32_e32 v12, vcc, s22, v60
	s_lshl_b32 s5, s5, 1
	s_nop 0
	v_addc_co_u32_e32 v13, vcc, 0, v61, vcc
	v_add_co_u32_e32 v16, vcc, s6, v60
	s_mov_b32 s6, 0x40000
	s_nop 0
	v_addc_co_u32_e32 v17, vcc, 0, v61, vcc
	global_load_dwordx4 v[12:15], v[12:13], off nt
	s_nop 0
	global_load_dwordx4 v[16:19], v[16:17], off nt
	v_add_co_u32_e32 v20, vcc, s6, v60
	s_mov_b32 s6, 0x44000
	s_nop 0
	v_addc_co_u32_e32 v21, vcc, 0, v61, vcc
	v_add_co_u32_e32 v24, vcc, s6, v60
	s_mov_b32 s6, 0x60000
	s_nop 0
	v_addc_co_u32_e32 v25, vcc, 0, v61, vcc
	global_load_dwordx4 v[20:23], v[20:21], off nt
	s_nop 0
	global_load_dwordx4 v[24:27], v[24:25], off nt
	v_add_co_u32_e32 v28, vcc, s6, v60
	s_mov_b32 s6, 0x64000
	s_nop 0
	v_addc_co_u32_e32 v29, vcc, 0, v61, vcc
	v_add_co_u32_e32 v32, vcc, s6, v60
	s_mov_b32 s6, 0x80000
	s_nop 0
	v_addc_co_u32_e32 v33, vcc, 0, v61, vcc
	global_load_dwordx4 v[28:31], v[28:29], off nt
	s_nop 0
	global_load_dwordx4 v[32:35], v[32:33], off nt
	v_add_co_u32_e32 v36, vcc, s6, v60
	s_mov_b32 s6, 0x84000
	s_nop 0
	v_addc_co_u32_e32 v37, vcc, 0, v61, vcc
	v_add_co_u32_e32 v40, vcc, s6, v60
	s_mov_b32 s6, 0xa0000
	s_nop 0
	v_addc_co_u32_e32 v41, vcc, 0, v61, vcc
	global_load_dwordx4 v[36:39], v[36:37], off nt
	s_nop 0
	global_load_dwordx4 v[40:43], v[40:41], off nt
	v_add_co_u32_e32 v44, vcc, s6, v60
	s_mov_b32 s6, 0xa4000
	s_nop 0
	v_addc_co_u32_e32 v45, vcc, 0, v61, vcc
	v_add_co_u32_e32 v48, vcc, s6, v60
	s_mov_b32 s6, 0xc0000
	s_nop 0
	v_addc_co_u32_e32 v49, vcc, 0, v61, vcc
	global_load_dwordx4 v[44:47], v[44:45], off nt
	s_nop 0
	global_load_dwordx4 v[48:51], v[48:49], off nt
	v_add_co_u32_e32 v52, vcc, s6, v60
	s_mov_b32 s6, 0xc4000
	s_nop 0
	v_addc_co_u32_e32 v53, vcc, 0, v61, vcc
	v_add_co_u32_e32 v56, vcc, s6, v60
	s_mov_b32 s6, 0xe0000
	s_nop 0
	v_addc_co_u32_e32 v57, vcc, 0, v61, vcc
	global_load_dwordx4 v[52:55], v[52:53], off nt
	s_nop 0
	global_load_dwordx4 v[56:59], v[56:57], off nt
	v_add_co_u32_e32 v62, vcc, s6, v60
	s_mov_b32 s6, 0xe4000
	s_nop 0
	v_addc_co_u32_e32 v63, vcc, 0, v61, vcc
	v_add_co_u32_e32 v64, vcc, s6, v60
	s_add_u32 s6, s18, s5
	s_nop 0
	v_addc_co_u32_e32 v65, vcc, 0, v61, vcc
	global_load_dwordx4 v[60:63], v[62:63], off nt
	s_nop 0
	global_load_dwordx4 v[64:67], v[64:65], off nt
	s_waitcnt vmcnt(0)
	v_cvt_pk_bf16_f32 v4, v4, v8
	v_add_u32_e32 v8, v71, v73
	ds_write_b32 v8, v4
	v_cvt_pk_bf16_f32 v4, v5, v9
	ds_write_b32 v8, v4 offset:128
	v_cvt_pk_bf16_f32 v4, v6, v10
	ds_write_b32 v8, v4 offset:256
	v_cvt_pk_bf16_f32 v4, v7, v11
	ds_write_b32 v8, v4 offset:384
	v_cvt_pk_bf16_f32 v4, v12, v16
	v_add_u32_e32 v5, v74, v73
	ds_write_b32 v5, v4
	v_cvt_pk_bf16_f32 v4, v13, v17
	ds_write_b32 v5, v4 offset:128
	v_cvt_pk_bf16_f32 v4, v14, v18
	ds_write_b32 v5, v4 offset:256
	v_cvt_pk_bf16_f32 v4, v15, v19
	ds_write_b32 v5, v4 offset:384
	v_cvt_pk_bf16_f32 v4, v20, v24
	v_add_u32_e32 v5, v75, v73
	ds_write_b32 v5, v4
	v_cvt_pk_bf16_f32 v4, v21, v25
	ds_write_b32 v5, v4 offset:128
	v_cvt_pk_bf16_f32 v4, v22, v26
	ds_write_b32 v5, v4 offset:256
	v_cvt_pk_bf16_f32 v4, v23, v27
	ds_write_b32 v5, v4 offset:384
	v_cvt_pk_bf16_f32 v4, v28, v32
	v_add_u32_e32 v5, v76, v73
	ds_write_b32 v5, v4
	v_cvt_pk_bf16_f32 v4, v29, v33
	ds_write_b32 v5, v4 offset:128
	v_cvt_pk_bf16_f32 v4, v30, v34
	ds_write_b32 v5, v4 offset:256
	v_cvt_pk_bf16_f32 v4, v31, v35
	ds_write_b32 v5, v4 offset:384
	v_cvt_pk_bf16_f32 v4, v36, v40
	v_add_u32_e32 v5, v77, v73
	ds_write_b32 v5, v4
	v_cvt_pk_bf16_f32 v4, v37, v41
	ds_write_b32 v5, v4 offset:128
	v_cvt_pk_bf16_f32 v4, v38, v42
	ds_write_b32 v5, v4 offset:256
	v_cvt_pk_bf16_f32 v4, v39, v43
	ds_write_b32 v5, v4 offset:384
	v_cvt_pk_bf16_f32 v4, v44, v48
	v_add_u32_e32 v5, v78, v73
	ds_write_b32 v5, v4
	v_cvt_pk_bf16_f32 v4, v45, v49
	ds_write_b32 v5, v4 offset:128
	v_cvt_pk_bf16_f32 v4, v46, v50
	ds_write_b32 v5, v4 offset:256
	v_cvt_pk_bf16_f32 v4, v47, v51
	ds_write_b32 v5, v4 offset:384
	v_cvt_pk_bf16_f32 v4, v52, v56
	v_add_u32_e32 v5, v79, v73
	ds_write_b32 v5, v4
	v_cvt_pk_bf16_f32 v4, v53, v57
	ds_write_b32 v5, v4 offset:128
	v_cvt_pk_bf16_f32 v4, v54, v58
	ds_write_b32 v5, v4 offset:256
	v_cvt_pk_bf16_f32 v4, v55, v59
	ds_write_b32 v5, v4 offset:384
	v_cvt_pk_bf16_f32 v4, v60, v64
	v_add_u32_e32 v5, v80, v73
	ds_write_b32 v5, v4
	v_cvt_pk_bf16_f32 v4, v61, v65
	ds_write_b32 v5, v4 offset:128
	v_cvt_pk_bf16_f32 v4, v62, v66
	ds_write_b32 v5, v4 offset:256
	v_cvt_pk_bf16_f32 v4, v63, v67
	ds_write_b32 v5, v4 offset:384
	s_addc_u32 s7, s19, 0
	v_lshlrev_b32_e32 v4, 1, v70
	v_mov_b32_e32 v5, v2
	s_waitcnt lgkmcnt(0)
; #define LAS __attribute__((address_space(3)))
; #define LDS_WAIT() asm volatile("s_waitcnt lgkmcnt(0)" ::: "memory")
;     ...
;     LDS_WAIT(); asm volatile("" ::: "memory");
;     const int c = lane & 7;
; #pragma unroll
;     for (int j = 0; j < 8; ++j) { const int row = (lane >> 3) + 8 * j; const u32x4 o = *(const LAS u32x4*)(scr + row * 128 + ((c ^ ((row >> 2) & 7)) * 16));
;         const int lc = col_off + n0 + row; int dr;
;         if (MODE == 0) dr = lc;
;         else if (MODE == 1) dr = (lc & ~255) + 128 * ((lc >> 5) & 1) + 32 * ((lc >> 6) & 3) + (lc & 31);
;         else if (MODE == 2) dr = 256 * (lc >> 7) + (lc & 127);
;         else dr = 256 * (lc >> 7) + 128 + (lc & 127);
;         *(u32x4*)(WT + (size_t)dr * (ldt ? ldt : K) + k0 + 8 * c) = o; }
;     LDS_WAIT(); asm volatile("" ::: "memory");
	v_lshl_add_u64 v[4:5], s[6:7], 0, v[4:5]
	s_mov_b64 s[6:7], 0xfa00000
	v_lshl_add_u64 v[12:13], v[4:5], 0, s[6:7]
	v_add_u32_e32 v4, v82, v83
	ds_read_b128 v[4:7], v4
	v_or_b32_e32 v8, s4, v81
	v_mul_u32_u24_e32 v8, 0x2b00, v8
	v_lshlrev_b32_e32 v8, 1, v8
	v_mov_b32_e32 v9, v2
	v_lshl_add_u64 v[14:15], v[12:13], 0, v[8:9]
	v_add_u32_e32 v8, v85, v86
	ds_read_b128 v[8:11], v8
	s_waitcnt lgkmcnt(1)
	global_store_dwordx4 v[14:15], v[4:7], off
	v_readlane_b32 s37, v250, 1
	v_readlane_b32 s38, v250, 2
	v_or_b32_e32 v4, s4, v84
	v_mul_u32_u24_e32 v4, 0x2b00, v4
	v_lshlrev_b32_e32 v4, 1, v4
	v_mov_b32_e32 v5, v2
	v_lshl_add_u64 v[4:5], v[12:13], 0, v[4:5]
	s_waitcnt lgkmcnt(0)
	global_store_dwordx4 v[4:5], v[8:11], off
	v_add_u32_e32 v4, v88, v89
	ds_read_b128 v[4:7], v4
	v_or_b32_e32 v8, s4, v87
	v_mul_u32_u24_e32 v8, 0x2b00, v8
	v_lshlrev_b32_e32 v8, 1, v8
	v_mov_b32_e32 v9, v2
	v_lshl_add_u64 v[14:15], v[12:13], 0, v[8:9]
	v_add_u32_e32 v8, v91, v92
	ds_read_b128 v[8:11], v8
	s_waitcnt lgkmcnt(1)
	global_store_dwordx4 v[14:15], v[4:7], off
	v_readlane_b32 s39, v250, 3
	v_readlane_b32 s40, v250, 4
	v_or_b32_e32 v4, s4, v90
	v_mul_u32_u24_e32 v4, 0x2b00, v4
	v_lshlrev_b32_e32 v4, 1, v4
	v_mov_b32_e32 v5, v2
	v_lshl_add_u64 v[4:5], v[12:13], 0, v[4:5]
	s_waitcnt lgkmcnt(0)
	global_store_dwordx4 v[4:5], v[8:11], off
	v_add_u32_e32 v4, v94, v83
	ds_read_b128 v[4:7], v4
	v_or_b32_e32 v8, s4, v93
	v_mul_u32_u24_e32 v8, 0x2b00, v8
	v_lshlrev_b32_e32 v8, 1, v8
	v_mov_b32_e32 v9, v2
	v_lshl_add_u64 v[14:15], v[12:13], 0, v[8:9]
	v_add_u32_e32 v8, v96, v97
	ds_read_b128 v[8:11], v8
	s_waitcnt lgkmcnt(1)
	global_store_dwordx4 v[14:15], v[4:7], off
	v_readlane_b32 s41, v250, 5
	s_nop 0
	v_or_b32_e32 v4, s4, v95
	v_mul_u32_u24_e32 v4, 0x2b00, v4
	v_lshlrev_b32_e32 v4, 1, v4
	v_mov_b32_e32 v5, v2
	v_lshl_add_u64 v[4:5], v[12:13], 0, v[4:5]
	s_waitcnt lgkmcnt(0)
	global_store_dwordx4 v[4:5], v[8:11], off
	v_add_u32_e32 v4, v99, v100
	ds_read_b128 v[4:7], v4
	v_or_b32_e32 v8, s4, v98
	v_mul_u32_u24_e32 v8, 0x2b00, v8
	v_lshlrev_b32_e32 v8, 1, v8
	v_mov_b32_e32 v9, v2
	v_lshl_add_u64 v[14:15], v[12:13], 0, v[8:9]
	v_add_u32_e32 v8, v102, v103
	ds_read_b128 v[8:11], v8
	s_waitcnt lgkmcnt(1)
	global_store_dwordx4 v[14:15], v[4:7], off
	s_nop 1
	v_or_b32_e32 v4, s4, v101
	v_mul_u32_u24_e32 v4, 0x2b00, v4
	v_lshlrev_b32_e32 v4, 1, v4
	v_mov_b32_e32 v5, v2
	v_lshl_add_u64 v[4:5], v[12:13], 0, v[4:5]
	s_waitcnt lgkmcnt(0)
	global_store_dwordx4 v[4:5], v[8:11], off
	s_waitcnt lgkmcnt(0)
	s_mov_b64 s[4:5], 0
;     const int nblk = N / 64, kb = item / nblk, nb = item % nblk, k0 = 64 * kb, n0 = 64 * nb;
;     const int r16 = lane & 15, q = lane >> 4;
;     const float* src = W + (size_t)(k0 + 2 * q) * N + n0 + 4 * r16;
;     f32x4 v[16];
; #pragma unroll
;     for (int j = 0; j < 16; ++j) v[j] = *(const f32x4*)(src + (size_t)(8 * (j >> 1) + (j & 1)) * N);
;     if (nscale) { const f32x4 ns = *(const f32x4*)(nscale + n0 + 4 * r16);
; #pragma unroll
;         for (int j = 0; j < 16; ++j) v[j] = v[j] * ns; }
;     if (kscale) {
; #pragma unroll
;         for (int i = 0; i < 8; ++i) { const f32x2 g = *(const f32x2*)(kscale + k0 + 8 * i + 2 * q); v[2 * i] = v[2 * i] * g[0]; v[2 * i + 1] = v[2 * i + 1] * g[1]; } }
.LBB0_635:
	s_andn2_b64 vcc, exec, s[4:5]
	s_cbranch_vccnz .LBB0_639
	v_readlane_b32 s36, v250, 0
	v_readlane_b32 s40, v250, 4
	v_readlane_b32 s41, v250, 5
	s_add_u32 s4, s40, s3
	s_addc_u32 s5, s41, s2
	s_add_i32 s6, s20, 0xab00
	s_and_b32 s7, s6, 0xffff
	s_mul_i32 s7, s7, 0xbe83
	s_lshr_b32 s14, s7, 23
	s_mul_i32 s7, s14, 0xac
	s_sub_i32 s6, s6, s7
	s_and_b32 s7, s6, 0xffff
	s_lshl_b32 s6, s14, 6
	v_or_b32_e32 v4, s6, v72
	v_mul_u32_u24_e32 v4, 0x2b00, v4
	v_lshlrev_b32_e32 v4, 2, v4
	v_mov_b32_e32 v5, v2
	v_lshl_add_u64 v[4:5], s[4:5], 0, v[4:5]
	s_lshl_b32 s14, s7, 8
	v_lshl_add_u64 v[4:5], v[4:5], 0, s[14:15]
	v_lshlrev_b32_e32 v6, 2, v68
	v_mov_b32_e32 v7, v2
	v_lshl_add_u64 v[4:5], v[4:5], 0, v[6:7]
	s_mov_b32 s4, 0xa000
	v_add_co_u32_e32 v6, vcc, s4, v4
	s_mov_b32 s4, 0x56000
	s_nop 0
	v_addc_co_u32_e32 v7, vcc, 0, v5, vcc
	global_load_dwordx4 v[60:63], v[4:5], off nt
	global_load_dwordx4 v[64:67], v[6:7], off offset:3072 nt
	v_add_co_u32_e32 v6, vcc, s4, v4
	s_mov_b32 s4, 0x60000
	s_nop 0
	v_addc_co_u32_e32 v7, vcc, 0, v5, vcc
	v_add_co_u32_e32 v8, vcc, s4, v4
	s_mov_b32 s4, 0xac000
	s_nop 0
	v_addc_co_u32_e32 v9, vcc, 0, v5, vcc
	global_load_dwordx4 v[52:55], v[6:7], off nt
	global_load_dwordx4 v[56:59], v[8:9], off offset:3072 nt
	v_add_co_u32_e32 v6, vcc, s4, v4
	s_mov_b32 s4, 0xb6000
	s_nop 0
	v_addc_co_u32_e32 v7, vcc, 0, v5, vcc
	v_add_co_u32_e32 v8, vcc, s4, v4
	s_mov_b32 s4, 0x102000
	s_nop 0
	v_addc_co_u32_e32 v9, vcc, 0, v5, vcc
	global_load_dwordx4 v[44:47], v[6:7], off nt
	global_load_dwordx4 v[48:51], v[8:9], off offset:3072 nt
	v_add_co_u32_e32 v6, vcc, s4, v4
	s_mov_b32 s4, 0x10c000
	s_nop 0
	v_addc_co_u32_e32 v7, vcc, 0, v5, vcc
	v_add_co_u32_e32 v8, vcc, s4, v4
	s_mov_b32 s4, 0x158000
	s_nop 0
	v_addc_co_u32_e32 v9, vcc, 0, v5, vcc
	global_load_dwordx4 v[36:39], v[6:7], off nt
	global_load_dwordx4 v[40:43], v[8:9], off offset:3072 nt
	v_add_co_u32_e32 v6, vcc, s4, v4
	s_mov_b32 s4, 0x162000
	s_nop 0
	v_addc_co_u32_e32 v7, vcc, 0, v5, vcc
	v_add_co_u32_e32 v8, vcc, s4, v4
	s_mov_b32 s4, 0x1ae000
	s_nop 0
	v_addc_co_u32_e32 v9, vcc, 0, v5, vcc
	global_load_dwordx4 v[20:23], v[6:7], off nt
	global_load_dwordx4 v[32:35], v[8:9], off offset:3072 nt
	v_add_co_u32_e32 v6, vcc, s4, v4
	s_mov_b32 s4, 0x1b8000
	s_nop 0
	v_addc_co_u32_e32 v7, vcc, 0, v5, vcc
	v_add_co_u32_e32 v8, vcc, s4, v4
	s_mov_b32 s4, 0x204000
	s_nop 0
	v_addc_co_u32_e32 v9, vcc, 0, v5, vcc
	global_load_dwordx4 v[16:19], v[6:7], off nt
	global_load_dwordx4 v[28:31], v[8:9], off offset:3072 nt
	v_add_co_u32_e32 v6, vcc, s4, v4
	v_readlane_b32 s4, v253, 7
	s_nop 0
	v_addc_co_u32_e32 v7, vcc, 0, v5, vcc
	v_add_co_u32_e32 v12, vcc, 0x20e000, v4
	v_readlane_b32 s5, v253, 8
	s_nop 0
	v_addc_co_u32_e32 v13, vcc, 0, v5, vcc
	global_load_dwordx4 v[8:11], v[6:7], off nt
	global_load_dwordx4 v[24:27], v[12:13], off offset:3072 nt
	v_add_co_u32_e32 v6, vcc, 0x25a000, v4
	v_readlane_b32 s37, v250, 1
	s_nop 0
	v_addc_co_u32_e32 v7, vcc, 0, v5, vcc
	v_add_co_u32_e32 v12, vcc, 0x264000, v4
	v_readlane_b32 s38, v250, 2
	s_nop 0
	v_addc_co_u32_e32 v13, vcc, 0, v5, vcc
	global_load_dwordx4 v[4:7], v[6:7], off nt
	s_nop 0
	global_load_dwordx4 v[12:15], v[12:13], off offset:3072 nt
	s_andn2_b64 vcc, exec, s[4:5]
	v_readlane_b32 s39, v250, 3
	v_readlane_b32 s42, v250, 6
	v_readlane_b32 s43, v250, 7
	s_cbranch_vccnz .LBB0_638
	s_lshl_b32 s4, s0, 12
	s_ashr_i32 s5, s4, 31
	s_lshl_b64 s[4:5], s[4:5], 2
	s_add_u32 s4, s36, s4
	s_addc_u32 s5, s37, s5
	s_lshl_b32 s14, s6, 2
	s_add_u32 s4, s4, s14
	s_addc_u32 s5, s5, 0
	v_lshlrev_b32_e32 v106, 2, v72
	global_load_dwordx2 v[104:105], v106, s[4:5]
	s_waitcnt vmcnt(0)
	v_pk_mul_f32 v[62:63], v[62:63], v[104:105] op_sel_hi:[1,0]
	v_pk_mul_f32 v[60:61], v[60:61], v[104:105] op_sel_hi:[1,0]
	v_pk_mul_f32 v[66:67], v[66:67], v[104:105] op_sel:[0,1]
	v_pk_mul_f32 v[64:65], v[64:65], v[104:105] op_sel:[0,1]
	global_load_dwordx2 v[104:105], v106, s[4:5] offset:32
	s_waitcnt vmcnt(0)
	v_pk_mul_f32 v[54:55], v[54:55], v[104:105] op_sel_hi:[1,0]
	v_pk_mul_f32 v[52:53], v[52:53], v[104:105] op_sel_hi:[1,0]
	v_pk_mul_f32 v[58:59], v[58:59], v[104:105] op_sel:[0,1]
	v_pk_mul_f32 v[56:57], v[56:57], v[104:105] op_sel:[0,1]
	global_load_dwordx2 v[104:105], v106, s[4:5] offset:64
	s_waitcnt vmcnt(0)
	v_pk_mul_f32 v[46:47], v[46:47], v[104:105] op_sel_hi:[1,0]
	v_pk_mul_f32 v[44:45], v[44:45], v[104:105] op_sel_hi:[1,0]
	v_pk_mul_f32 v[50:51], v[50:51], v[104:105] op_sel:[0,1]
	v_pk_mul_f32 v[48:49], v[48:49], v[104:105] op_sel:[0,1]
	global_load_dwordx2 v[104:105], v106, s[4:5] offset:96
	s_waitcnt vmcnt(0)
	v_pk_mul_f32 v[38:39], v[38:39], v[104:105] op_sel_hi:[1,0]
	v_pk_mul_f32 v[36:37], v[36:37], v[104:105] op_sel_hi:[1,0]
	v_pk_mul_f32 v[42:43], v[42:43], v[104:105] op_sel:[0,1]
	v_pk_mul_f32 v[40:41], v[40:41], v[104:105] op_sel:[0,1]
	global_load_dwordx2 v[104:105], v106, s[4:5] offset:128
	s_waitcnt vmcnt(0)
	v_pk_mul_f32 v[22:23], v[22:23], v[104:105] op_sel_hi:[1,0]
	v_pk_mul_f32 v[20:21], v[20:21], v[104:105] op_sel_hi:[1,0]
	v_pk_mul_f32 v[34:35], v[34:35], v[104:105] op_sel:[0,1]
	v_pk_mul_f32 v[32:33], v[32:33], v[104:105] op_sel:[0,1]
	global_load_dwordx2 v[104:105], v106, s[4:5] offset:160
	s_waitcnt vmcnt(0)
	v_pk_mul_f32 v[18:19], v[18:19], v[104:105] op_sel_hi:[1,0]
	v_pk_mul_f32 v[16:17], v[16:17], v[104:105] op_sel_hi:[1,0]
	v_pk_mul_f32 v[30:31], v[30:31], v[104:105] op_sel:[0,1]
	v_pk_mul_f32 v[28:29], v[28:29], v[104:105] op_sel:[0,1]
	global_load_dwordx2 v[104:105], v106, s[4:5] offset:192
	s_waitcnt vmcnt(0)
	v_pk_mul_f32 v[10:11], v[10:11], v[104:105] op_sel_hi:[1,0]
	v_pk_mul_f32 v[8:9], v[8:9], v[104:105] op_sel_hi:[1,0]
	v_pk_mul_f32 v[26:27], v[26:27], v[104:105] op_sel:[0,1]
	v_pk_mul_f32 v[24:25], v[24:25], v[104:105] op_sel:[0,1]
	global_load_dwordx2 v[104:105], v106, s[4:5] offset:224
	s_waitcnt vmcnt(0)
	v_pk_mul_f32 v[6:7], v[6:7], v[104:105] op_sel_hi:[1,0]
	v_pk_mul_f32 v[4:5], v[4:5], v[104:105] op_sel_hi:[1,0]
	v_pk_mul_f32 v[14:15], v[14:15], v[104:105] op_sel:[0,1]
	v_pk_mul_f32 v[12:13], v[12:13], v[104:105] op_sel:[0,1]

;     const int nblk = N / 64, kb = item / nblk, nb = item % nblk, k0 = 64 * kb, n0 = 64 * nb;
;     const int r16 = lane & 15, q = lane >> 4;
;     const float* src = W + (size_t)(k0 + 2 * q) * N + n0 + 4 * r16;
;     f32x4 v[16];
; #pragma unroll
;     for (int j = 0; j < 16; ++j) v[j] = *(const f32x4*)(src + (size_t)(8 * (j >> 1) + (j & 1)) * N);
;     if (nscale) { const f32x4 ns = *(const f32x4*)(nscale + n0 + 4 * r16);
; #pragma unroll
;         for (int j = 0; j < 16; ++j) v[j] = v[j] * ns; }
;     if (kscale) {
; #pragma unroll
;         for (int i = 0; i < 8; ++i) { const f32x2 g = *(const f32x2*)(kscale + k0 + 8 * i + 2 * q); v[2 * i] = v[2 * i] * g[0]; v[2 * i + 1] = v[2 * i + 1] * g[1]; } }
.LBB0_640:
	s_andn2_b64 vcc, exec, s[4:5]
	s_cbranch_vccnz .LBB0_644
	v_readlane_b32 s36, v250, 0
	v_readlane_b32 s38, v250, 2
	v_readlane_b32 s39, v250, 3
	s_add_u32 s4, s38, s3
	s_addc_u32 s5, s39, s2
	s_add_i32 s2, s20, 0xd600
	s_and_b32 s3, s2, 0xffff
	s_mul_i32 s3, s3, 0xbe83
	s_lshr_b32 s6, s3, 23
	s_mul_i32 s3, s6, 0xac
	s_sub_i32 s2, s2, s3
	s_and_b32 s3, s2, 0xffff
	s_lshl_b32 s2, s6, 6
	v_or_b32_e32 v4, s2, v72
	v_mul_u32_u24_e32 v4, 0x2b00, v4
	v_lshlrev_b32_e32 v4, 2, v4
	v_mov_b32_e32 v5, v2
	v_lshl_add_u64 v[4:5], s[4:5], 0, v[4:5]
	s_lshl_b32 s14, s3, 8
	v_lshl_add_u64 v[4:5], v[4:5], 0, s[14:15]
	v_lshlrev_b32_e32 v6, 2, v68
	v_mov_b32_e32 v7, v2
	v_lshl_add_u64 v[4:5], v[4:5], 0, v[6:7]
	s_mov_b32 s4, 0xa000
	v_add_co_u32_e32 v6, vcc, s4, v4
	s_mov_b32 s4, 0x56000
	s_nop 0
	v_addc_co_u32_e32 v7, vcc, 0, v5, vcc
	global_load_dwordx4 v[60:63], v[4:5], off nt
	global_load_dwordx4 v[64:67], v[6:7], off offset:3072 nt
	v_add_co_u32_e32 v6, vcc, s4, v4
	s_mov_b32 s4, 0x60000
	s_nop 0
	v_addc_co_u32_e32 v7, vcc, 0, v5, vcc
	v_add_co_u32_e32 v8, vcc, s4, v4
	s_mov_b32 s4, 0xac000
	s_nop 0
	v_addc_co_u32_e32 v9, vcc, 0, v5, vcc
	global_load_dwordx4 v[52:55], v[6:7], off nt
	global_load_dwordx4 v[56:59], v[8:9], off offset:3072 nt
	v_add_co_u32_e32 v6, vcc, s4, v4
	s_mov_b32 s4, 0xb6000
	s_nop 0
	v_addc_co_u32_e32 v7, vcc, 0, v5, vcc
	v_add_co_u32_e32 v8, vcc, s4, v4
	s_mov_b32 s4, 0x102000
	s_nop 0
	v_addc_co_u32_e32 v9, vcc, 0, v5, vcc
	global_load_dwordx4 v[44:47], v[6:7], off nt
	global_load_dwordx4 v[48:51], v[8:9], off offset:3072 nt
	v_add_co_u32_e32 v6, vcc, s4, v4
	s_mov_b32 s4, 0x10c000
	s_nop 0
	v_addc_co_u32_e32 v7, vcc, 0, v5, vcc
	v_add_co_u32_e32 v8, vcc, s4, v4
	s_mov_b32 s4, 0x158000
	s_nop 0
	v_addc_co_u32_e32 v9, vcc, 0, v5, vcc
	global_load_dwordx4 v[36:39], v[6:7], off nt
	global_load_dwordx4 v[40:43], v[8:9], off offset:3072 nt
	v_add_co_u32_e32 v6, vcc, s4, v4
	s_mov_b32 s4, 0x162000
	s_nop 0
	v_addc_co_u32_e32 v7, vcc, 0, v5, vcc
	v_add_co_u32_e32 v8, vcc, s4, v4
	s_mov_b32 s4, 0x1ae000
	s_nop 0
	v_addc_co_u32_e32 v9, vcc, 0, v5, vcc
	global_load_dwordx4 v[20:23], v[6:7], off nt
	global_load_dwordx4 v[32:35], v[8:9], off offset:3072 nt
	v_add_co_u32_e32 v6, vcc, s4, v4
	s_mov_b32 s4, 0x1b8000
	s_nop 0
	v_addc_co_u32_e32 v7, vcc, 0, v5, vcc
	v_add_co_u32_e32 v8, vcc, s4, v4
	s_mov_b32 s4, 0x204000
	s_nop 0
	v_addc_co_u32_e32 v9, vcc, 0, v5, vcc
	global_load_dwordx4 v[16:19], v[6:7], off nt
	global_load_dwordx4 v[28:31], v[8:9], off offset:3072 nt
	v_add_co_u32_e32 v6, vcc, s4, v4
	v_readlane_b32 s4, v253, 7
	s_nop 0
	v_addc_co_u32_e32 v7, vcc, 0, v5, vcc
	v_add_co_u32_e32 v12, vcc, 0x20e000, v4
	v_readlane_b32 s5, v253, 8
	s_nop 0
	v_addc_co_u32_e32 v13, vcc, 0, v5, vcc
	global_load_dwordx4 v[8:11], v[6:7], off nt
	global_load_dwordx4 v[24:27], v[12:13], off offset:3072 nt
	v_add_co_u32_e32 v6, vcc, 0x25a000, v4
	v_readlane_b32 s37, v250, 1
	s_nop 0
	v_addc_co_u32_e32 v7, vcc, 0, v5, vcc
	v_add_co_u32_e32 v12, vcc, 0x264000, v4
	v_readlane_b32 s40, v250, 4
	s_nop 0
	v_addc_co_u32_e32 v13, vcc, 0, v5, vcc
	global_load_dwordx4 v[4:7], v[6:7], off nt
	s_nop 0
	global_load_dwordx4 v[12:15], v[12:13], off offset:3072 nt
	s_andn2_b64 vcc, exec, s[4:5]
	v_readlane_b32 s41, v250, 5
	v_readlane_b32 s42, v250, 6
	v_readlane_b32 s43, v250, 7
	s_cbranch_vccnz .LBB0_643
	s_lshl_b32 s4, s0, 12
	s_ashr_i32 s5, s4, 31
	s_lshl_b64 s[4:5], s[4:5], 2
	s_add_u32 s4, s36, s4
	s_addc_u32 s5, s37, s5
	s_lshl_b32 s6, s2, 2
	s_add_u32 s4, s4, s6
	s_addc_u32 s5, s5, 0
	v_lshlrev_b32_e32 v106, 2, v72
	global_load_dwordx2 v[104:105], v106, s[4:5]
	s_waitcnt vmcnt(0)
	v_pk_mul_f32 v[62:63], v[62:63], v[104:105] op_sel_hi:[1,0]
	v_pk_mul_f32 v[60:61], v[60:61], v[104:105] op_sel_hi:[1,0]
	v_pk_mul_f32 v[66:67], v[66:67], v[104:105] op_sel:[0,1]
	v_pk_mul_f32 v[64:65], v[64:65], v[104:105] op_sel:[0,1]
	global_load_dwordx2 v[104:105], v106, s[4:5] offset:32
	s_waitcnt vmcnt(0)
	v_pk_mul_f32 v[54:55], v[54:55], v[104:105] op_sel_hi:[1,0]
	v_pk_mul_f32 v[52:53], v[52:53], v[104:105] op_sel_hi:[1,0]
	v_pk_mul_f32 v[58:59], v[58:59], v[104:105] op_sel:[0,1]
	v_pk_mul_f32 v[56:57], v[56:57], v[104:105] op_sel:[0,1]
	global_load_dwordx2 v[104:105], v106, s[4:5] offset:64
	s_waitcnt vmcnt(0)
	v_pk_mul_f32 v[46:47], v[46:47], v[104:105] op_sel_hi:[1,0]
	v_pk_mul_f32 v[44:45], v[44:45], v[104:105] op_sel_hi:[1,0]
	v_pk_mul_f32 v[50:51], v[50:51], v[104:105] op_sel:[0,1]
	v_pk_mul_f32 v[48:49], v[48:49], v[104:105] op_sel:[0,1]
	global_load_dwordx2 v[104:105], v106, s[4:5] offset:96
	s_waitcnt vmcnt(0)
	v_pk_mul_f32 v[38:39], v[38:39], v[104:105] op_sel_hi:[1,0]
	v_pk_mul_f32 v[36:37], v[36:37], v[104:105] op_sel_hi:[1,0]
	v_pk_mul_f32 v[42:43], v[42:43], v[104:105] op_sel:[0,1]
	v_pk_mul_f32 v[40:41], v[40:41], v[104:105] op_sel:[0,1]
	global_load_dwordx2 v[104:105], v106, s[4:5] offset:128
	s_waitcnt vmcnt(0)
	v_pk_mul_f32 v[22:23], v[22:23], v[104:105] op_sel_hi:[1,0]
	v_pk_mul_f32 v[20:21], v[20:21], v[104:105] op_sel_hi:[1,0]
	v_pk_mul_f32 v[34:35], v[34:35], v[104:105] op_sel:[0,1]
	v_pk_mul_f32 v[32:33], v[32:33], v[104:105] op_sel:[0,1]
	global_load_dwordx2 v[104:105], v106, s[4:5] offset:160
	s_waitcnt vmcnt(0)
	v_pk_mul_f32 v[18:19], v[18:19], v[104:105] op_sel_hi:[1,0]
	v_pk_mul_f32 v[16:17], v[16:17], v[104:105] op_sel_hi:[1,0]
	v_pk_mul_f32 v[30:31], v[30:31], v[104:105] op_sel:[0,1]
	v_pk_mul_f32 v[28:29], v[28:29], v[104:105] op_sel:[0,1]
	global_load_dwordx2 v[104:105], v106, s[4:5] offset:192
	s_waitcnt vmcnt(0)
	v_pk_mul_f32 v[10:11], v[10:11], v[104:105] op_sel_hi:[1,0]
	v_pk_mul_f32 v[8:9], v[8:9], v[104:105] op_sel_hi:[1,0]
	v_pk_mul_f32 v[26:27], v[26:27], v[104:105] op_sel:[0,1]
	v_pk_mul_f32 v[24:25], v[24:25], v[104:105] op_sel:[0,1]
	global_load_dwordx2 v[104:105], v106, s[4:5] offset:224
	s_waitcnt vmcnt(0)
	v_pk_mul_f32 v[6:7], v[6:7], v[104:105] op_sel_hi:[1,0]
	v_pk_mul_f32 v[4:5], v[4:5], v[104:105] op_sel_hi:[1,0]
	v_pk_mul_f32 v[14:15], v[14:15], v[104:105] op_sel:[0,1]
	v_pk_mul_f32 v[12:13], v[12:13], v[104:105] op_sel:[0,1]

; #define LAS __attribute__((address_space(3)))
; __device__ __forceinline__ unsigned cvt_pk_bf16(float lo, float hi) { unsigned r; asm volatile("v_cvt_pk_bf16_f32 %0, %1, %2" : "=v"(r) : "v"(lo), "v"(hi)); return r; }
;     const int nblk = N / 64, kb = item / nblk, nb = item % nblk, k0 = 64 * kb, n0 = 64 * nb;
;     const int r16 = lane & 15, q = lane >> 4;
;     const float* src = W + (size_t)(k0 + 2 * q) * N + n0 + 4 * r16;
;     f32x4 v[16];
; #pragma unroll
;     for (int j = 0; j < 16; ++j) v[j] = *(const f32x4*)(src + (size_t)(8 * (j >> 1) + (j & 1)) * N);
;     if (nscale) { const f32x4 ns = *(const f32x4*)(nscale + n0 + 4 * r16);
; #pragma unroll
;         for (int j = 0; j < 16; ++j) v[j] = v[j] * ns; }
;     if (kscale) {
; #pragma unroll
;         for (int i = 0; i < 8; ++i) { const f32x2 g = *(const f32x2*)(kscale + k0 + 8 * i + 2 * q); v[2 * i] = v[2 * i] * g[0]; v[2 * i + 1] = v[2 * i + 1] * g[1]; } }
; #pragma unroll
;     for (int i = 0; i < 8; ++i)
; #pragma unroll
;         for (int e = 0; e < 4; ++e) *(LAS unsigned*)(scr + (4 * r16 + e) * 128 + ((i ^ (r16 & 7)) * 16) + q * 4) = cvt_pk_bf16(v[2 * i][e], v[2 * i + 1][e]);
.LBB0_645:
	s_andn2_b64 vcc, exec, s[4:5]
	s_cbranch_vccnz .LBB0_647
	v_readlane_b32 s36, v250, 46
	s_lshl_b64 s[2:3], s[0:1], 23
	v_readlane_b32 s50, v250, 60
	v_readlane_b32 s51, v250, 61
	s_add_u32 s4, s50, s2
	s_addc_u32 s5, s51, s3
	s_add_i32 s2, s20, 0xd800
	s_and_b32 s3, s2, 0xffc0
	s_lshl_b32 s2, s20, 6
	v_lshlrev_b32_e32 v4, 2, v69
	s_and_b32 s2, s2, 0xfc0
	v_lshl_or_b32 v4, s3, 14, v4
	v_mov_b32_e32 v5, v2
	v_lshl_add_u64 v[4:5], s[4:5], 0, v[4:5]
	s_lshl_b32 s14, s2, 2
	v_lshl_add_u64 v[4:5], v[4:5], 0, s[14:15]
	v_lshlrev_b32_e32 v6, 2, v68
	v_mov_b32_e32 v7, v2
	v_lshl_add_u64 v[60:61], v[4:5], 0, v[6:7]
	s_movk_i32 s4, 0x4000
	v_add_co_u32_e32 v8, vcc, s4, v60
	s_mov_b32 s4, 0x24000
	s_nop 0
	v_addc_co_u32_e32 v9, vcc, 0, v61, vcc
	global_load_dwordx4 v[4:7], v[60:61], off nt
	s_nop 0
	global_load_dwordx4 v[8:11], v[8:9], off nt
	v_add_co_u32_e32 v12, vcc, s22, v60
	s_lshl_b32 s3, s3, 1
	s_nop 0
	v_addc_co_u32_e32 v13, vcc, 0, v61, vcc
	v_add_co_u32_e32 v16, vcc, s4, v60
	s_mov_b32 s4, 0x40000
	s_nop 0
	v_addc_co_u32_e32 v17, vcc, 0, v61, vcc
	global_load_dwordx4 v[12:15], v[12:13], off nt
	s_nop 0
	global_load_dwordx4 v[16:19], v[16:17], off nt
	v_add_co_u32_e32 v20, vcc, s4, v60
	s_mov_b32 s4, 0x44000
	s_nop 0
	v_addc_co_u32_e32 v21, vcc, 0, v61, vcc
	v_add_co_u32_e32 v24, vcc, s4, v60
	s_mov_b32 s4, 0x60000
	s_nop 0
	v_addc_co_u32_e32 v25, vcc, 0, v61, vcc
	global_load_dwordx4 v[20:23], v[20:21], off nt
	s_nop 0
	global_load_dwordx4 v[24:27], v[24:25], off nt
	v_add_co_u32_e32 v28, vcc, s4, v60
	s_mov_b32 s4, 0x64000
	s_nop 0
	v_addc_co_u32_e32 v29, vcc, 0, v61, vcc
	v_add_co_u32_e32 v32, vcc, s4, v60
	s_mov_b32 s4, 0x80000
	s_nop 0
	v_addc_co_u32_e32 v33, vcc, 0, v61, vcc
	global_load_dwordx4 v[28:31], v[28:29], off nt
	s_nop 0
	global_load_dwordx4 v[32:35], v[32:33], off nt
	v_add_co_u32_e32 v36, vcc, s4, v60
	s_mov_b32 s4, 0x84000
	s_nop 0
	v_addc_co_u32_e32 v37, vcc, 0, v61, vcc
	v_add_co_u32_e32 v40, vcc, s4, v60
	s_mov_b32 s4, 0xa0000
	s_nop 0
	v_addc_co_u32_e32 v41, vcc, 0, v61, vcc
	global_load_dwordx4 v[36:39], v[36:37], off nt
	s_nop 0
	global_load_dwordx4 v[40:43], v[40:41], off nt
	v_add_co_u32_e32 v44, vcc, s4, v60
	s_mov_b32 s4, 0xa4000
	s_nop 0
	v_addc_co_u32_e32 v45, vcc, 0, v61, vcc
	v_add_co_u32_e32 v48, vcc, s4, v60
	s_mov_b32 s4, 0xc0000
	s_nop 0
	v_addc_co_u32_e32 v49, vcc, 0, v61, vcc
	global_load_dwordx4 v[44:47], v[44:45], off nt
	s_nop 0
	global_load_dwordx4 v[48:51], v[48:49], off nt
	v_add_co_u32_e32 v52, vcc, s4, v60
	s_mov_b32 s4, 0xc4000
	s_nop 0
	v_addc_co_u32_e32 v53, vcc, 0, v61, vcc
	v_add_co_u32_e32 v56, vcc, s4, v60
	s_mov_b32 s4, 0xe0000
	s_nop 0
	v_addc_co_u32_e32 v57, vcc, 0, v61, vcc
	global_load_dwordx4 v[52:55], v[52:53], off nt
	s_nop 0
	global_load_dwordx4 v[56:59], v[56:57], off nt
	v_add_co_u32_e32 v62, vcc, s4, v60
	s_mov_b32 s4, 0xe4000
	s_nop 0
	v_addc_co_u32_e32 v63, vcc, 0, v61, vcc
	v_add_co_u32_e32 v64, vcc, s4, v60
	s_add_u32 s4, s18, s3
	s_nop 0
	v_addc_co_u32_e32 v65, vcc, 0, v61, vcc
	global_load_dwordx4 v[60:63], v[62:63], off nt
	s_nop 0
	global_load_dwordx4 v[64:67], v[64:65], off nt
	s_waitcnt vmcnt(0)
; #define LAS __attribute__((address_space(3)))
; #define LDS_WAIT() asm volatile("s_waitcnt lgkmcnt(0)" ::: "memory")
; __device__ __forceinline__ unsigned cvt_pk_bf16(float lo, float hi) { unsigned r; asm volatile("v_cvt_pk_bf16_f32 %0, %1, %2" : "=v"(r) : "v"(lo), "v"(hi)); return r; }
;     ...
; #pragma unroll
;     for (int i = 0; i < 8; ++i)
; #pragma unroll
;         for (int e = 0; e < 4; ++e) *(LAS unsigned*)(scr + (4 * r16 + e) * 128 + ((i ^ (r16 & 7)) * 16) + q * 4) = cvt_pk_bf16(v[2 * i][e], v[2 * i + 1][e]);
;     LDS_WAIT(); asm volatile("" ::: "memory");
;     const int c = lane & 7;
; #pragma unroll
;     for (int j = 0; j < 8; ++j) { const int row = (lane >> 3) + 8 * j; const u32x4 o = *(const LAS u32x4*)(scr + row * 128 + ((c ^ ((row >> 2) & 7)) * 16));
;         const int lc = col_off + n0 + row; int dr;
;         if (MODE == 0) dr = lc;
;         else if (MODE == 1) dr = (lc & ~255) + 128 * ((lc >> 5) & 1) + 32 * ((lc >> 6) & 3) + (lc & 31);
;         else if (MODE == 2) dr = 256 * (lc >> 7) + (lc & 127);
;         else dr = 256 * (lc >> 7) + 128 + (lc & 127);
;         *(u32x4*)(WT + (size_t)dr * (ldt ? ldt : K) + k0 + 8 * c) = o; }
;     LDS_WAIT(); asm volatile("" ::: "memory");
	v_cvt_pk_bf16_f32 v4, v4, v8
	v_add_u32_e32 v8, v71, v73
	ds_write_b32 v8, v4
	v_cvt_pk_bf16_f32 v4, v5, v9
	ds_write_b32 v8, v4 offset:128
	v_cvt_pk_bf16_f32 v4, v6, v10
	ds_write_b32 v8, v4 offset:256
	v_cvt_pk_bf16_f32 v4, v7, v11
	ds_write_b32 v8, v4 offset:384
	v_cvt_pk_bf16_f32 v4, v12, v16
	v_add_u32_e32 v5, v74, v73
	ds_write_b32 v5, v4
	v_cvt_pk_bf16_f32 v4, v13, v17
	ds_write_b32 v5, v4 offset:128
	v_cvt_pk_bf16_f32 v4, v14, v18
	ds_write_b32 v5, v4 offset:256
	v_cvt_pk_bf16_f32 v4, v15, v19
	ds_write_b32 v5, v4 offset:384
	v_cvt_pk_bf16_f32 v4, v20, v24
	v_add_u32_e32 v5, v75, v73
	ds_write_b32 v5, v4
	v_cvt_pk_bf16_f32 v4, v21, v25
	ds_write_b32 v5, v4 offset:128
	v_cvt_pk_bf16_f32 v4, v22, v26
	ds_write_b32 v5, v4 offset:256
	v_cvt_pk_bf16_f32 v4, v23, v27
	ds_write_b32 v5, v4 offset:384
	v_cvt_pk_bf16_f32 v4, v28, v32
	v_add_u32_e32 v5, v76, v73
	ds_write_b32 v5, v4
	v_cvt_pk_bf16_f32 v4, v29, v33
	ds_write_b32 v5, v4 offset:128
	v_cvt_pk_bf16_f32 v4, v30, v34
	ds_write_b32 v5, v4 offset:256
	v_cvt_pk_bf16_f32 v4, v31, v35
	ds_write_b32 v5, v4 offset:384
	v_cvt_pk_bf16_f32 v4, v36, v40
	v_add_u32_e32 v5, v77, v73
	ds_write_b32 v5, v4
	v_cvt_pk_bf16_f32 v4, v37, v41
	ds_write_b32 v5, v4 offset:128
	v_cvt_pk_bf16_f32 v4, v38, v42
	ds_write_b32 v5, v4 offset:256
	v_cvt_pk_bf16_f32 v4, v39, v43
	ds_write_b32 v5, v4 offset:384
	v_cvt_pk_bf16_f32 v4, v44, v48
	v_add_u32_e32 v5, v78, v73
	ds_write_b32 v5, v4
	v_cvt_pk_bf16_f32 v4, v45, v49
	ds_write_b32 v5, v4 offset:128
	v_cvt_pk_bf16_f32 v4, v46, v50
	ds_write_b32 v5, v4 offset:256
	v_cvt_pk_bf16_f32 v4, v47, v51
	ds_write_b32 v5, v4 offset:384
	v_cvt_pk_bf16_f32 v4, v52, v56
	v_add_u32_e32 v5, v79, v73
	ds_write_b32 v5, v4
	v_cvt_pk_bf16_f32 v4, v53, v57
	ds_write_b32 v5, v4 offset:128
	v_cvt_pk_bf16_f32 v4, v54, v58
	ds_write_b32 v5, v4 offset:256
	v_cvt_pk_bf16_f32 v4, v55, v59
	ds_write_b32 v5, v4 offset:384
	v_cvt_pk_bf16_f32 v4, v60, v64
	v_add_u32_e32 v5, v80, v73
	ds_write_b32 v5, v4
	v_cvt_pk_bf16_f32 v4, v61, v65
	ds_write_b32 v5, v4 offset:128
	v_cvt_pk_bf16_f32 v4, v62, v66
	ds_write_b32 v5, v4 offset:256
	v_cvt_pk_bf16_f32 v4, v63, v67
	ds_write_b32 v5, v4 offset:384
	s_addc_u32 s5, s19, 0
	v_lshlrev_b32_e32 v4, 1, v70
	v_mov_b32_e32 v5, v2
	s_waitcnt lgkmcnt(0)
	v_lshl_add_u64 v[4:5], s[4:5], 0, v[4:5]
	s_mov_b64 s[4:5], 0x4a00000
	v_lshl_add_u64 v[12:13], v[4:5], 0, s[4:5]
	v_add_u32_e32 v4, v82, v83
	ds_read_b128 v[4:7], v4
	v_or_b32_e32 v8, s2, v81
	v_lshlrev_b32_e32 v8, 10, v8
	v_mov_b32_e32 v9, v2
	v_lshl_add_u64 v[14:15], v[12:13], 0, v[8:9]
	v_add_u32_e32 v8, v85, v86
	ds_read_b128 v[8:11], v8
	s_waitcnt lgkmcnt(1)
	global_store_dwordx4 v[14:15], v[4:7], off
	v_readlane_b32 s46, v250, 56
	v_readlane_b32 s47, v250, 57
	v_or_b32_e32 v4, s2, v84
	v_lshlrev_b32_e32 v4, 10, v4
	v_mov_b32_e32 v5, v2
	v_lshl_add_u64 v[4:5], v[12:13], 0, v[4:5]
	s_waitcnt lgkmcnt(0)
	global_store_dwordx4 v[4:5], v[8:11], off
	v_add_u32_e32 v4, v88, v89
	ds_read_b128 v[4:7], v4
	v_or_b32_e32 v8, s2, v87
	v_lshlrev_b32_e32 v8, 10, v8
	v_mov_b32_e32 v9, v2
	v_lshl_add_u64 v[14:15], v[12:13], 0, v[8:9]
	v_add_u32_e32 v8, v91, v92
	ds_read_b128 v[8:11], v8
	s_waitcnt lgkmcnt(1)
	global_store_dwordx4 v[14:15], v[4:7], off
	v_readlane_b32 s46, v255, 36
	v_readlane_b32 s47, v255, 37
	v_or_b32_e32 v4, s2, v90
	v_lshlrev_b32_e32 v4, 10, v4
	v_mov_b32_e32 v5, v2
	v_lshl_add_u64 v[4:5], v[12:13], 0, v[4:5]
	s_waitcnt lgkmcnt(0)
	global_store_dwordx4 v[4:5], v[8:11], off
	v_add_u32_e32 v4, v94, v83
	ds_read_b128 v[4:7], v4
	v_or_b32_e32 v8, s2, v93
	v_lshlrev_b32_e32 v8, 10, v8
	v_mov_b32_e32 v9, v2
	v_lshl_add_u64 v[14:15], v[12:13], 0, v[8:9]
	v_add_u32_e32 v8, v96, v97
	ds_read_b128 v[8:11], v8
	s_waitcnt lgkmcnt(1)
	global_store_dwordx4 v[14:15], v[4:7], off
	v_readlane_b32 s37, v250, 47
	v_readlane_b32 s38, v250, 48
	v_or_b32_e32 v4, s2, v95
	v_lshlrev_b32_e32 v4, 10, v4
	v_mov_b32_e32 v5, v2
	v_lshl_add_u64 v[4:5], v[12:13], 0, v[4:5]
	s_waitcnt lgkmcnt(0)
	global_store_dwordx4 v[4:5], v[8:11], off
	v_add_u32_e32 v4, v99, v100
	ds_read_b128 v[4:7], v4
	v_or_b32_e32 v8, s2, v98
	v_lshlrev_b32_e32 v8, 10, v8
	v_mov_b32_e32 v9, v2
	v_lshl_add_u64 v[14:15], v[12:13], 0, v[8:9]
	v_add_u32_e32 v8, v102, v103
	ds_read_b128 v[8:11], v8
	s_waitcnt lgkmcnt(1)
	global_store_dwordx4 v[14:15], v[4:7], off
	v_readlane_b32 s39, v250, 49
	v_readlane_b32 s40, v250, 50
	v_or_b32_e32 v4, s2, v101
	v_lshlrev_b32_e32 v4, 10, v4
	v_mov_b32_e32 v5, v2
	v_lshl_add_u64 v[4:5], v[12:13], 0, v[4:5]
	s_waitcnt lgkmcnt(0)
	global_store_dwordx4 v[4:5], v[8:11], off
	s_waitcnt lgkmcnt(0)
	v_readlane_b32 s41, v250, 51
	v_readlane_b32 s42, v250, 52
	v_readlane_b32 s43, v250, 53
	v_readlane_b32 s44, v250, 54
	v_readlane_b32 s45, v250, 55
	v_readlane_b32 s48, v250, 58
	v_readlane_b32 s49, v250, 59

;     const int nblk = N / 64, kb = item / nblk, nb = item % nblk, k0 = 64 * kb, n0 = 64 * nb;
;     const int r16 = lane & 15, q = lane >> 4;
;     const float* src = W + (size_t)(k0 + 2 * q) * N + n0 + 4 * r16;
;     f32x4 v[16];
; #pragma unroll
;     for (int j = 0; j < 16; ++j) v[j] = *(const f32x4*)(src + (size_t)(8 * (j >> 1) + (j & 1)) * N);
;     if (nscale) { const f32x4 ns = *(const f32x4*)(nscale + n0 + 4 * r16);
; #pragma unroll
;         for (int j = 0; j < 16; ++j) v[j] = v[j] * ns; }
;     if (kscale) {
; #pragma unroll
;         for (int i = 0; i < 8; ++i) { const f32x2 g = *(const f32x2*)(kscale + k0 + 8 * i + 2 * q); v[2 * i] = v[2 * i] * g[0]; v[2 * i + 1] = v[2 * i + 1] * g[1]; } }
.LBB0_648:
	s_andn2_b64 vcc, exec, s[4:5]
	s_cbranch_vccnz .LBB0_652
	v_readlane_b32 s36, v250, 46
	s_lshl_b64 s[4:5], s[0:1], 23
	v_readlane_b32 s44, v250, 54
	v_readlane_b32 s45, v250, 55
	s_add_u32 s6, s44, s4
	s_mul_i32 s2, s0, 0xfffaa800
	s_addc_u32 s7, s45, s5
	s_add_i32 s2, s9, s2
	s_addk_i32 s2, 0xe000
	s_and_b32 s2, s2, 0x7ffc0
	v_or_b32_e32 v4, s2, v72
	s_and_b32 s3, s16, 0x1c0
	v_lshlrev_b32_e32 v4, 11, v4
	v_mov_b32_e32 v5, v2
	v_lshl_add_u64 v[4:5], s[6:7], 0, v[4:5]
	s_lshl_b32 s14, s3, 2
	v_lshl_add_u64 v[4:5], v[4:5], 0, s[14:15]
	v_lshlrev_b32_e32 v6, 2, v68
	v_mov_b32_e32 v7, v2
	v_lshl_add_u64 v[4:5], v[4:5], 0, v[6:7]
	s_movk_i32 s6, 0x4000
	v_add_co_u32_e32 v6, vcc, s6, v4
	s_mov_b32 s6, 0x8000
	s_nop 0
	v_addc_co_u32_e32 v7, vcc, 0, v5, vcc
	global_load_dwordx4 v[60:63], v[4:5], off nt
	global_load_dwordx4 v[64:67], v[4:5], off offset:2048 nt
	global_load_dwordx4 v[52:55], v[6:7], off nt
	global_load_dwordx4 v[56:59], v[6:7], off offset:2048 nt
	v_add_co_u32_e32 v6, vcc, s6, v4
	s_mov_b32 s6, 0x10000
	s_nop 0
	v_addc_co_u32_e32 v7, vcc, 0, v5, vcc
	global_load_dwordx4 v[44:47], v[6:7], off nt
	global_load_dwordx4 v[48:51], v[6:7], off offset:2048 nt
	v_add_co_u32_e32 v6, vcc, 0xc000, v4
	v_readlane_b32 s38, v250, 48
	s_nop 0
	v_addc_co_u32_e32 v7, vcc, 0, v5, vcc
	global_load_dwordx4 v[36:39], v[6:7], off nt
	global_load_dwordx4 v[40:43], v[6:7], off offset:2048 nt
	v_add_co_u32_e32 v6, vcc, s6, v4
	s_mov_b32 s6, 0x14000
	s_nop 0
	v_addc_co_u32_e32 v7, vcc, 0, v5, vcc
	global_load_dwordx4 v[28:31], v[6:7], off nt
	global_load_dwordx4 v[32:35], v[6:7], off offset:2048 nt
	v_add_co_u32_e32 v6, vcc, s6, v4
	v_readlane_b32 s6, v253, 9
	s_nop 0
	v_addc_co_u32_e32 v7, vcc, 0, v5, vcc
	global_load_dwordx4 v[20:23], v[6:7], off nt
	global_load_dwordx4 v[24:27], v[6:7], off offset:2048 nt
	v_add_co_u32_e32 v6, vcc, 0x18000, v4
	v_readlane_b32 s7, v253, 10
	s_nop 0
	v_addc_co_u32_e32 v7, vcc, 0, v5, vcc
	v_add_co_u32_e32 v8, vcc, 0x1c000, v4
	global_load_dwordx4 v[12:15], v[6:7], off nt
	global_load_dwordx4 v[16:19], v[6:7], off offset:2048 nt
	v_addc_co_u32_e32 v9, vcc, 0, v5, vcc
	global_load_dwordx4 v[4:7], v[8:9], off nt
	s_nop 0
	global_load_dwordx4 v[8:11], v[8:9], off offset:2048 nt
	v_readlane_b32 s39, v250, 49
	s_andn2_b64 vcc, exec, s[6:7]
	v_readlane_b32 s37, v250, 47
	v_readlane_b32 s40, v250, 50
	v_readlane_b32 s41, v250, 51
	v_readlane_b32 s42, v250, 52
	v_readlane_b32 s43, v250, 53
	v_readlane_b32 s46, v250, 56
	v_readlane_b32 s47, v250, 57
	v_readlane_b32 s48, v250, 58
	v_readlane_b32 s49, v250, 59
	v_readlane_b32 s50, v250, 60
	v_readlane_b32 s51, v250, 61
	s_cbranch_vccnz .LBB0_651
	s_lshl_b32 s6, s0, 12
	s_ashr_i32 s7, s6, 31
	s_lshl_b64 s[6:7], s[6:7], 2
	s_add_u32 s6, s38, s6
	s_addc_u32 s7, s39, s7
	s_lshl_b32 s14, s2, 2
	s_add_u32 s6, s6, s14
	s_addc_u32 s7, s7, 0
	v_lshlrev_b32_e32 v106, 2, v72
	global_load_dwordx2 v[104:105], v106, s[6:7]
	s_waitcnt vmcnt(0)
	v_pk_mul_f32 v[62:63], v[62:63], v[104:105] op_sel_hi:[1,0]
	v_pk_mul_f32 v[60:61], v[60:61], v[104:105] op_sel_hi:[1,0]
	v_pk_mul_f32 v[66:67], v[66:67], v[104:105] op_sel:[0,1]
	v_pk_mul_f32 v[64:65], v[64:65], v[104:105] op_sel:[0,1]
	global_load_dwordx2 v[104:105], v106, s[6:7] offset:32
	s_waitcnt vmcnt(0)
	v_pk_mul_f32 v[54:55], v[54:55], v[104:105] op_sel_hi:[1,0]
	v_pk_mul_f32 v[52:53], v[52:53], v[104:105] op_sel_hi:[1,0]
	v_pk_mul_f32 v[58:59], v[58:59], v[104:105] op_sel:[0,1]
	v_pk_mul_f32 v[56:57], v[56:57], v[104:105] op_sel:[0,1]
	global_load_dwordx2 v[104:105], v106, s[6:7] offset:64
	s_waitcnt vmcnt(0)
	v_pk_mul_f32 v[46:47], v[46:47], v[104:105] op_sel_hi:[1,0]
	v_pk_mul_f32 v[44:45], v[44:45], v[104:105] op_sel_hi:[1,0]
	v_pk_mul_f32 v[50:51], v[50:51], v[104:105] op_sel:[0,1]
	v_pk_mul_f32 v[48:49], v[48:49], v[104:105] op_sel:[0,1]
	global_load_dwordx2 v[104:105], v106, s[6:7] offset:96
	s_waitcnt vmcnt(0)
	v_pk_mul_f32 v[38:39], v[38:39], v[104:105] op_sel_hi:[1,0]
	v_pk_mul_f32 v[36:37], v[36:37], v[104:105] op_sel_hi:[1,0]
	v_pk_mul_f32 v[42:43], v[42:43], v[104:105] op_sel:[0,1]
	v_pk_mul_f32 v[40:41], v[40:41], v[104:105] op_sel:[0,1]
	global_load_dwordx2 v[104:105], v106, s[6:7] offset:128
	s_waitcnt vmcnt(0)
	v_pk_mul_f32 v[30:31], v[30:31], v[104:105] op_sel_hi:[1,0]
	v_pk_mul_f32 v[28:29], v[28:29], v[104:105] op_sel_hi:[1,0]
	v_pk_mul_f32 v[34:35], v[34:35], v[104:105] op_sel:[0,1]
	v_pk_mul_f32 v[32:33], v[32:33], v[104:105] op_sel:[0,1]
	global_load_dwordx2 v[104:105], v106, s[6:7] offset:160
	s_waitcnt vmcnt(0)
	v_pk_mul_f32 v[22:23], v[22:23], v[104:105] op_sel_hi:[1,0]
	v_pk_mul_f32 v[20:21], v[20:21], v[104:105] op_sel_hi:[1,0]
	v_pk_mul_f32 v[26:27], v[26:27], v[104:105] op_sel:[0,1]
	v_pk_mul_f32 v[24:25], v[24:25], v[104:105] op_sel:[0,1]
	global_load_dwordx2 v[104:105], v106, s[6:7] offset:192
	s_waitcnt vmcnt(0)
	v_pk_mul_f32 v[14:15], v[14:15], v[104:105] op_sel_hi:[1,0]
	v_pk_mul_f32 v[12:13], v[12:13], v[104:105] op_sel_hi:[1,0]
	v_pk_mul_f32 v[18:19], v[18:19], v[104:105] op_sel:[0,1]
	v_pk_mul_f32 v[16:17], v[16:17], v[104:105] op_sel:[0,1]
	global_load_dwordx2 v[104:105], v106, s[6:7] offset:224
	s_waitcnt vmcnt(0)
	v_pk_mul_f32 v[6:7], v[6:7], v[104:105] op_sel_hi:[1,0]
	v_pk_mul_f32 v[4:5], v[4:5], v[104:105] op_sel_hi:[1,0]
	v_pk_mul_f32 v[10:11], v[10:11], v[104:105] op_sel:[0,1]
	v_pk_mul_f32 v[8:9], v[8:9], v[104:105] op_sel:[0,1]

;     const int nblk = N / 64, kb = item / nblk, nb = item % nblk, k0 = 64 * kb, n0 = 64 * nb;
;     const int r16 = lane & 15, q = lane >> 4;
;     const float* src = W + (size_t)(k0 + 2 * q) * N + n0 + 4 * r16;
;     f32x4 v[16];
; #pragma unroll
;     for (int j = 0; j < 16; ++j) v[j] = *(const f32x4*)(src + (size_t)(8 * (j >> 1) + (j & 1)) * N);
;     if (nscale) { const f32x4 ns = *(const f32x4*)(nscale + n0 + 4 * r16);
; #pragma unroll
;         for (int j = 0; j < 16; ++j) v[j] = v[j] * ns; }
;     if (kscale) {
; #pragma unroll
;         for (int i = 0; i < 8; ++i) { const f32x2 g = *(const f32x2*)(kscale + k0 + 8 * i + 2 * q); v[2 * i] = v[2 * i] * g[0]; v[2 * i + 1] = v[2 * i + 1] * g[1]; } }
.LBB0_653:
	s_andn2_b64 vcc, exec, s[4:5]
	s_cbranch_vccnz .LBB0_657
	v_readlane_b32 s36, v250, 46
	s_lshl_b64 s[4:5], s[0:1], 23
	v_readlane_b32 s42, v250, 52
	v_readlane_b32 s43, v250, 53
	s_add_u32 s6, s42, s4
	s_mul_i32 s2, s0, 0xfffaa800
	s_addc_u32 s7, s43, s5
	s_add_i32 s2, s9, s2
	s_addk_i32 s2, 0xf000
	s_and_b32 s3, s2, 0x7ffc0
	s_mul_i32 s2, s0, 0xffd54000
	s_add_i32 s2, s16, s2
	v_or_b32_e32 v4, s3, v72
	s_and_b32 s14, s2, 0x1c0
	v_lshlrev_b32_e32 v4, 11, v4
	v_mov_b32_e32 v5, v2
	v_lshl_add_u64 v[4:5], s[6:7], 0, v[4:5]
	s_lshl_b32 s14, s14, 2
	v_lshl_add_u64 v[4:5], v[4:5], 0, s[14:15]
	v_lshlrev_b32_e32 v6, 2, v68
	v_mov_b32_e32 v7, v2
	v_lshl_add_u64 v[4:5], v[4:5], 0, v[6:7]
	s_movk_i32 s6, 0x4000
	v_add_co_u32_e32 v6, vcc, s6, v4
	s_mov_b32 s6, 0x8000
	s_nop 0
	v_addc_co_u32_e32 v7, vcc, 0, v5, vcc
	global_load_dwordx4 v[60:63], v[4:5], off nt
	global_load_dwordx4 v[64:67], v[4:5], off offset:2048 nt
	global_load_dwordx4 v[52:55], v[6:7], off nt
	global_load_dwordx4 v[56:59], v[6:7], off offset:2048 nt
	v_add_co_u32_e32 v6, vcc, s6, v4
	s_mov_b32 s6, 0x10000
	s_nop 0
	v_addc_co_u32_e32 v7, vcc, 0, v5, vcc
	global_load_dwordx4 v[44:47], v[6:7], off nt
	global_load_dwordx4 v[48:51], v[6:7], off offset:2048 nt
	v_add_co_u32_e32 v6, vcc, 0xc000, v4
	v_readlane_b32 s38, v250, 48
	s_nop 0
	v_addc_co_u32_e32 v7, vcc, 0, v5, vcc
	global_load_dwordx4 v[36:39], v[6:7], off nt
	global_load_dwordx4 v[40:43], v[6:7], off offset:2048 nt
	v_add_co_u32_e32 v6, vcc, s6, v4
	s_mov_b32 s6, 0x14000
	s_nop 0
	v_addc_co_u32_e32 v7, vcc, 0, v5, vcc
	global_load_dwordx4 v[28:31], v[6:7], off nt
	global_load_dwordx4 v[32:35], v[6:7], off offset:2048 nt
	v_add_co_u32_e32 v6, vcc, s6, v4
	v_readlane_b32 s6, v253, 9
	s_nop 0
	v_addc_co_u32_e32 v7, vcc, 0, v5, vcc
	global_load_dwordx4 v[20:23], v[6:7], off nt
	global_load_dwordx4 v[24:27], v[6:7], off offset:2048 nt
	v_add_co_u32_e32 v6, vcc, 0x18000, v4
	v_readlane_b32 s7, v253, 10
	s_nop 0
	v_addc_co_u32_e32 v7, vcc, 0, v5, vcc
	v_add_co_u32_e32 v8, vcc, 0x1c000, v4
	global_load_dwordx4 v[12:15], v[6:7], off nt
	global_load_dwordx4 v[16:19], v[6:7], off offset:2048 nt
	v_addc_co_u32_e32 v9, vcc, 0, v5, vcc
	global_load_dwordx4 v[4:7], v[8:9], off nt
	s_nop 0
	global_load_dwordx4 v[8:11], v[8:9], off offset:2048 nt
	v_readlane_b32 s39, v250, 49
	s_andn2_b64 vcc, exec, s[6:7]
	v_readlane_b32 s37, v250, 47
	v_readlane_b32 s40, v250, 50
	v_readlane_b32 s41, v250, 51
	v_readlane_b32 s44, v250, 54
	v_readlane_b32 s45, v250, 55
	v_readlane_b32 s46, v250, 56
	v_readlane_b32 s47, v250, 57
	v_readlane_b32 s48, v250, 58
	v_readlane_b32 s49, v250, 59
	v_readlane_b32 s50, v250, 60
	v_readlane_b32 s51, v250, 61
	s_cbranch_vccnz .LBB0_656
	s_lshl_b32 s6, s0, 12
	s_ashr_i32 s7, s6, 31
	s_lshl_b64 s[6:7], s[6:7], 2
	s_add_u32 s6, s38, s6
	s_addc_u32 s7, s39, s7
	s_lshl_b32 s14, s3, 2
	s_add_u32 s6, s6, s14
	s_addc_u32 s7, s7, 0
	v_lshlrev_b32_e32 v106, 2, v72
	global_load_dwordx2 v[104:105], v106, s[6:7]
	s_waitcnt vmcnt(0)
	v_pk_mul_f32 v[62:63], v[62:63], v[104:105] op_sel_hi:[1,0]
	v_pk_mul_f32 v[60:61], v[60:61], v[104:105] op_sel_hi:[1,0]
	v_pk_mul_f32 v[66:67], v[66:67], v[104:105] op_sel:[0,1]
	v_pk_mul_f32 v[64:65], v[64:65], v[104:105] op_sel:[0,1]
	global_load_dwordx2 v[104:105], v106, s[6:7] offset:32
	s_waitcnt vmcnt(0)
	v_pk_mul_f32 v[54:55], v[54:55], v[104:105] op_sel_hi:[1,0]
	v_pk_mul_f32 v[52:53], v[52:53], v[104:105] op_sel_hi:[1,0]
	v_pk_mul_f32 v[58:59], v[58:59], v[104:105] op_sel:[0,1]
	v_pk_mul_f32 v[56:57], v[56:57], v[104:105] op_sel:[0,1]
	global_load_dwordx2 v[104:105], v106, s[6:7] offset:64
	s_waitcnt vmcnt(0)
	v_pk_mul_f32 v[46:47], v[46:47], v[104:105] op_sel_hi:[1,0]
	v_pk_mul_f32 v[44:45], v[44:45], v[104:105] op_sel_hi:[1,0]
	v_pk_mul_f32 v[50:51], v[50:51], v[104:105] op_sel:[0,1]
	v_pk_mul_f32 v[48:49], v[48:49], v[104:105] op_sel:[0,1]
	global_load_dwordx2 v[104:105], v106, s[6:7] offset:96
	s_waitcnt vmcnt(0)
	v_pk_mul_f32 v[38:39], v[38:39], v[104:105] op_sel_hi:[1,0]
	v_pk_mul_f32 v[36:37], v[36:37], v[104:105] op_sel_hi:[1,0]
	v_pk_mul_f32 v[42:43], v[42:43], v[104:105] op_sel:[0,1]
	v_pk_mul_f32 v[40:41], v[40:41], v[104:105] op_sel:[0,1]
	global_load_dwordx2 v[104:105], v106, s[6:7] offset:128
	s_waitcnt vmcnt(0)
	v_pk_mul_f32 v[30:31], v[30:31], v[104:105] op_sel_hi:[1,0]
	v_pk_mul_f32 v[28:29], v[28:29], v[104:105] op_sel_hi:[1,0]
	v_pk_mul_f32 v[34:35], v[34:35], v[104:105] op_sel:[0,1]
	v_pk_mul_f32 v[32:33], v[32:33], v[104:105] op_sel:[0,1]
	global_load_dwordx2 v[104:105], v106, s[6:7] offset:160
	s_waitcnt vmcnt(0)
	v_pk_mul_f32 v[22:23], v[22:23], v[104:105] op_sel_hi:[1,0]
	v_pk_mul_f32 v[20:21], v[20:21], v[104:105] op_sel_hi:[1,0]
	v_pk_mul_f32 v[26:27], v[26:27], v[104:105] op_sel:[0,1]
	v_pk_mul_f32 v[24:25], v[24:25], v[104:105] op_sel:[0,1]
	global_load_dwordx2 v[104:105], v106, s[6:7] offset:192
	s_waitcnt vmcnt(0)
	v_pk_mul_f32 v[14:15], v[14:15], v[104:105] op_sel_hi:[1,0]
	v_pk_mul_f32 v[12:13], v[12:13], v[104:105] op_sel_hi:[1,0]
	v_pk_mul_f32 v[18:19], v[18:19], v[104:105] op_sel:[0,1]
	v_pk_mul_f32 v[16:17], v[16:17], v[104:105] op_sel:[0,1]
	global_load_dwordx2 v[104:105], v106, s[6:7] offset:224
	s_waitcnt vmcnt(0)
	v_pk_mul_f32 v[6:7], v[6:7], v[104:105] op_sel_hi:[1,0]
	v_pk_mul_f32 v[4:5], v[4:5], v[104:105] op_sel_hi:[1,0]
	v_pk_mul_f32 v[10:11], v[10:11], v[104:105] op_sel:[0,1]
	v_pk_mul_f32 v[8:9], v[8:9], v[104:105] op_sel:[0,1]

;     const int nblk = N / 64, kb = item / nblk, nb = item % nblk, k0 = 64 * kb, n0 = 64 * nb;
;     const int r16 = lane & 15, q = lane >> 4;
;     const float* src = W + (size_t)(k0 + 2 * q) * N + n0 + 4 * r16;
;     f32x4 v[16];
; #pragma unroll
;     for (int j = 0; j < 16; ++j) v[j] = *(const f32x4*)(src + (size_t)(8 * (j >> 1) + (j & 1)) * N);
;     if (nscale) { const f32x4 ns = *(const f32x4*)(nscale + n0 + 4 * r16);
; #pragma unroll
;         for (int j = 0; j < 16; ++j) v[j] = v[j] * ns; }
;     if (kscale) {
; #pragma unroll
;         for (int i = 0; i < 8; ++i) { const f32x2 g = *(const f32x2*)(kscale + k0 + 8 * i + 2 * q); v[2 * i] = v[2 * i] * g[0]; v[2 * i + 1] = v[2 * i + 1] * g[1]; } }
.LBB0_658:
	s_andn2_b64 vcc, exec, s[4:5]
	s_cbranch_vccnz .LBB0_662
	v_readlane_b32 s36, v250, 46
	s_lshl_b64 s[2:3], s[0:1], 23
	v_readlane_b32 s40, v250, 50
	v_readlane_b32 s41, v250, 51
	s_add_u32 s4, s40, s2
	s_mul_i32 s2, s0, 0xfffaa800
	s_addc_u32 s5, s41, s3
	s_add_i32 s2, s9, s2
	s_and_b32 s2, s2, 0x7ffc0
	s_lshl_b32 s3, s20, 6
	v_or_b32_e32 v4, s2, v72
	s_and_b32 s3, s3, 0x1c0
	v_lshlrev_b32_e32 v4, 11, v4
	v_mov_b32_e32 v5, v2
	v_lshl_add_u64 v[4:5], s[4:5], 0, v[4:5]
	s_lshl_b32 s14, s3, 2
	v_lshl_add_u64 v[4:5], v[4:5], 0, s[14:15]
	v_lshlrev_b32_e32 v6, 2, v68
	v_mov_b32_e32 v7, v2
	v_lshl_add_u64 v[4:5], v[4:5], 0, v[6:7]
	s_movk_i32 s4, 0x4000
	v_add_co_u32_e32 v6, vcc, s4, v4
	s_mov_b32 s4, 0x8000
	s_nop 0
	v_addc_co_u32_e32 v7, vcc, 0, v5, vcc
	global_load_dwordx4 v[60:63], v[4:5], off nt
	global_load_dwordx4 v[64:67], v[4:5], off offset:2048 nt
	global_load_dwordx4 v[52:55], v[6:7], off nt
	global_load_dwordx4 v[56:59], v[6:7], off offset:2048 nt
	v_add_co_u32_e32 v6, vcc, s4, v4
	s_mov_b32 s4, 0x10000
	s_nop 0
	v_addc_co_u32_e32 v7, vcc, 0, v5, vcc
	global_load_dwordx4 v[44:47], v[6:7], off nt
	global_load_dwordx4 v[48:51], v[6:7], off offset:2048 nt
	v_add_co_u32_e32 v6, vcc, 0xc000, v4
	v_readlane_b32 s37, v250, 47
	s_nop 0
	v_addc_co_u32_e32 v7, vcc, 0, v5, vcc
	global_load_dwordx4 v[36:39], v[6:7], off nt
	global_load_dwordx4 v[40:43], v[6:7], off offset:2048 nt
	v_add_co_u32_e32 v6, vcc, s4, v4
	s_mov_b32 s4, 0x14000
	s_nop 0
	v_addc_co_u32_e32 v7, vcc, 0, v5, vcc
	global_load_dwordx4 v[28:31], v[6:7], off nt
	global_load_dwordx4 v[32:35], v[6:7], off offset:2048 nt
	v_add_co_u32_e32 v6, vcc, s4, v4
	v_readlane_b32 s4, v253, 11
	s_nop 0
	v_addc_co_u32_e32 v7, vcc, 0, v5, vcc
	global_load_dwordx4 v[20:23], v[6:7], off nt
	global_load_dwordx4 v[24:27], v[6:7], off offset:2048 nt
	v_add_co_u32_e32 v6, vcc, 0x18000, v4
	v_readlane_b32 s5, v253, 12
	s_nop 0
	v_addc_co_u32_e32 v7, vcc, 0, v5, vcc
	v_add_co_u32_e32 v8, vcc, 0x1c000, v4
	global_load_dwordx4 v[12:15], v[6:7], off nt
	global_load_dwordx4 v[16:19], v[6:7], off offset:2048 nt
	v_addc_co_u32_e32 v9, vcc, 0, v5, vcc
	global_load_dwordx4 v[4:7], v[8:9], off nt
	s_nop 0
	global_load_dwordx4 v[8:11], v[8:9], off offset:2048 nt
	s_andn2_b64 vcc, exec, s[4:5]
	v_readlane_b32 s38, v250, 48
	v_readlane_b32 s39, v250, 49
	v_readlane_b32 s42, v250, 52
	v_readlane_b32 s43, v250, 53
	v_readlane_b32 s44, v250, 54
	v_readlane_b32 s45, v250, 55
	v_readlane_b32 s46, v250, 56
	v_readlane_b32 s47, v250, 57
	v_readlane_b32 s48, v250, 58
	v_readlane_b32 s49, v250, 59
	v_readlane_b32 s50, v250, 60
	v_readlane_b32 s51, v250, 61
	s_cbranch_vccnz .LBB0_661
	s_lshl_b32 s4, s0, 12
	s_ashr_i32 s5, s4, 31
	s_lshl_b64 s[4:5], s[4:5], 2
	s_add_u32 s4, s36, s4
	s_addc_u32 s5, s37, s5
	s_lshl_b32 s6, s2, 2
	s_add_u32 s4, s4, s6
	s_addc_u32 s5, s5, 0
	v_lshlrev_b32_e32 v106, 2, v72
	global_load_dwordx2 v[104:105], v106, s[4:5]
	s_waitcnt vmcnt(0)
	v_pk_mul_f32 v[62:63], v[62:63], v[104:105] op_sel_hi:[1,0]
	v_pk_mul_f32 v[60:61], v[60:61], v[104:105] op_sel_hi:[1,0]
	v_pk_mul_f32 v[66:67], v[66:67], v[104:105] op_sel:[0,1]
	v_pk_mul_f32 v[64:65], v[64:65], v[104:105] op_sel:[0,1]
	global_load_dwordx2 v[104:105], v106, s[4:5] offset:32
	s_waitcnt vmcnt(0)
	v_pk_mul_f32 v[54:55], v[54:55], v[104:105] op_sel_hi:[1,0]
	v_pk_mul_f32 v[52:53], v[52:53], v[104:105] op_sel_hi:[1,0]
	v_pk_mul_f32 v[58:59], v[58:59], v[104:105] op_sel:[0,1]
	v_pk_mul_f32 v[56:57], v[56:57], v[104:105] op_sel:[0,1]
	global_load_dwordx2 v[104:105], v106, s[4:5] offset:64
	s_waitcnt vmcnt(0)
	v_pk_mul_f32 v[46:47], v[46:47], v[104:105] op_sel_hi:[1,0]
	v_pk_mul_f32 v[44:45], v[44:45], v[104:105] op_sel_hi:[1,0]
	v_pk_mul_f32 v[50:51], v[50:51], v[104:105] op_sel:[0,1]
	v_pk_mul_f32 v[48:49], v[48:49], v[104:105] op_sel:[0,1]
	global_load_dwordx2 v[104:105], v106, s[4:5] offset:96
	s_waitcnt vmcnt(0)
	v_pk_mul_f32 v[38:39], v[38:39], v[104:105] op_sel_hi:[1,0]
	v_pk_mul_f32 v[36:37], v[36:37], v[104:105] op_sel_hi:[1,0]
	v_pk_mul_f32 v[42:43], v[42:43], v[104:105] op_sel:[0,1]
	v_pk_mul_f32 v[40:41], v[40:41], v[104:105] op_sel:[0,1]
	global_load_dwordx2 v[104:105], v106, s[4:5] offset:128
	s_waitcnt vmcnt(0)
	v_pk_mul_f32 v[30:31], v[30:31], v[104:105] op_sel_hi:[1,0]
	v_pk_mul_f32 v[28:29], v[28:29], v[104:105] op_sel_hi:[1,0]
	v_pk_mul_f32 v[34:35], v[34:35], v[104:105] op_sel:[0,1]
	v_pk_mul_f32 v[32:33], v[32:33], v[104:105] op_sel:[0,1]
	global_load_dwordx2 v[104:105], v106, s[4:5] offset:160
	s_waitcnt vmcnt(0)
	v_pk_mul_f32 v[22:23], v[22:23], v[104:105] op_sel_hi:[1,0]
	v_pk_mul_f32 v[20:21], v[20:21], v[104:105] op_sel_hi:[1,0]
	v_pk_mul_f32 v[26:27], v[26:27], v[104:105] op_sel:[0,1]
	v_pk_mul_f32 v[24:25], v[24:25], v[104:105] op_sel:[0,1]
	global_load_dwordx2 v[104:105], v106, s[4:5] offset:192
	s_waitcnt vmcnt(0)
	v_pk_mul_f32 v[14:15], v[14:15], v[104:105] op_sel_hi:[1,0]
	v_pk_mul_f32 v[12:13], v[12:13], v[104:105] op_sel_hi:[1,0]
	v_pk_mul_f32 v[18:19], v[18:19], v[104:105] op_sel:[0,1]
	v_pk_mul_f32 v[16:17], v[16:17], v[104:105] op_sel:[0,1]
	global_load_dwordx2 v[104:105], v106, s[4:5] offset:224
	s_waitcnt vmcnt(0)
	v_pk_mul_f32 v[6:7], v[6:7], v[104:105] op_sel_hi:[1,0]
	v_pk_mul_f32 v[4:5], v[4:5], v[104:105] op_sel_hi:[1,0]
	v_pk_mul_f32 v[10:11], v[10:11], v[104:105] op_sel:[0,1]
	v_pk_mul_f32 v[8:9], v[8:9], v[104:105] op_sel:[0,1]

; #define LAS __attribute__((address_space(3)))
; __device__ __forceinline__ unsigned cvt_pk_bf16(float lo, float hi) { unsigned r; asm volatile("v_cvt_pk_bf16_f32 %0, %1, %2" : "=v"(r) : "v"(lo), "v"(hi)); return r; }
;     const int nblk = N / 64, kb = item / nblk, nb = item % nblk, k0 = 64 * kb, n0 = 64 * nb;
;     const int r16 = lane & 15, q = lane >> 4;
;     const float* src = W + (size_t)(k0 + 2 * q) * N + n0 + 4 * r16;
;     f32x4 v[16];
; #pragma unroll
;     for (int j = 0; j < 16; ++j) v[j] = *(const f32x4*)(src + (size_t)(8 * (j >> 1) + (j & 1)) * N);
;     if (nscale) { const f32x4 ns = *(const f32x4*)(nscale + n0 + 4 * r16);
; #pragma unroll
;         for (int j = 0; j < 16; ++j) v[j] = v[j] * ns; }
;     if (kscale) {
; #pragma unroll
;         for (int i = 0; i < 8; ++i) { const f32x2 g = *(const f32x2*)(kscale + k0 + 8 * i + 2 * q); v[2 * i] = v[2 * i] * g[0]; v[2 * i + 1] = v[2 * i + 1] * g[1]; } }
; #pragma unroll
;     for (int i = 0; i < 8; ++i)
; #pragma unroll
;         for (int e = 0; e < 4; ++e) *(LAS unsigned*)(scr + (4 * r16 + e) * 128 + ((i ^ (r16 & 7)) * 16) + q * 4) = cvt_pk_bf16(v[2 * i][e], v[2 * i + 1][e]);
.LBB0_663:
	s_andn2_b64 vcc, exec, s[4:5]
	s_cbranch_vccnz .LBB0_665
	s_lshl_b64 s[2:3], s[0:1], 26
	s_add_u32 s6, s74, s2
	s_addc_u32 s7, s75, s3
	s_lshl_b64 s[4:5], s[0:1], 24
	v_readlane_b32 s2, v252, 53
	s_add_u32 s3, s2, s4
	v_readlane_b32 s2, v252, 54
	s_addc_u32 s4, s2, s5
	s_and_b32 s5, s21, 0xffc0
	s_lshl_b32 s2, s20, 6
	v_lshlrev_b32_e32 v4, 2, v69
	s_and_b32 s2, s2, 0xfc0
	v_lshl_or_b32 v4, s5, 14, v4
	v_mov_b32_e32 v5, v2
	v_lshl_add_u64 v[4:5], s[6:7], 0, v[4:5]
	s_lshl_b32 s14, s2, 2
	v_lshl_add_u64 v[4:5], v[4:5], 0, s[14:15]
	v_lshlrev_b32_e32 v6, 2, v68
	v_mov_b32_e32 v7, v2
	v_lshl_add_u64 v[60:61], v[4:5], 0, v[6:7]
	s_brev_b32 s6, 64
	v_add_co_u32_e32 v4, vcc, s6, v60
	s_mov_b32 s6, 0x2004000
	s_nop 0
	v_addc_co_u32_e32 v5, vcc, 0, v61, vcc
	v_add_co_u32_e32 v8, vcc, s6, v60
	s_mov_b32 s6, 0x2020000
	s_nop 0
	v_addc_co_u32_e32 v9, vcc, 0, v61, vcc
	global_load_dwordx4 v[4:7], v[4:5], off nt
	s_nop 0
	global_load_dwordx4 v[8:11], v[8:9], off nt
	v_add_co_u32_e32 v12, vcc, s6, v60
	s_mov_b32 s6, 0x2024000
	s_nop 0
	v_addc_co_u32_e32 v13, vcc, 0, v61, vcc
	v_add_co_u32_e32 v16, vcc, s6, v60
	s_mov_b32 s6, 0x2040000
	s_nop 0
	v_addc_co_u32_e32 v17, vcc, 0, v61, vcc
	global_load_dwordx4 v[12:15], v[12:13], off nt
	s_nop 0
	global_load_dwordx4 v[16:19], v[16:17], off nt
	v_add_co_u32_e32 v20, vcc, s6, v60
	s_mov_b32 s6, 0x2044000
	s_nop 0
	v_addc_co_u32_e32 v21, vcc, 0, v61, vcc
	v_add_co_u32_e32 v24, vcc, s6, v60
	s_mov_b32 s6, 0x2060000
	s_nop 0
	v_addc_co_u32_e32 v25, vcc, 0, v61, vcc
	global_load_dwordx4 v[20:23], v[20:21], off nt
	s_nop 0
	global_load_dwordx4 v[24:27], v[24:25], off nt
	v_add_co_u32_e32 v28, vcc, s6, v60
	s_mov_b32 s6, 0x2064000
	s_nop 0
	v_addc_co_u32_e32 v29, vcc, 0, v61, vcc
	v_add_co_u32_e32 v32, vcc, s6, v60
	s_mov_b32 s6, 0x2080000
	s_nop 0
	v_addc_co_u32_e32 v33, vcc, 0, v61, vcc
	global_load_dwordx4 v[28:31], v[28:29], off nt
	s_nop 0
	global_load_dwordx4 v[32:35], v[32:33], off nt
	v_add_co_u32_e32 v36, vcc, s6, v60
	s_mov_b32 s6, 0x2084000
	s_nop 0
	v_addc_co_u32_e32 v37, vcc, 0, v61, vcc
	v_add_co_u32_e32 v40, vcc, s6, v60
	s_mov_b32 s6, 0x20a0000
	s_nop 0
	v_addc_co_u32_e32 v41, vcc, 0, v61, vcc
	global_load_dwordx4 v[36:39], v[36:37], off nt
	s_nop 0
	global_load_dwordx4 v[40:43], v[40:41], off nt
	v_add_co_u32_e32 v44, vcc, s6, v60
	s_mov_b32 s6, 0x20a4000
	s_nop 0
	v_addc_co_u32_e32 v45, vcc, 0, v61, vcc
	v_add_co_u32_e32 v48, vcc, s6, v60
	s_mov_b32 s6, 0x20c0000
	s_nop 0
	v_addc_co_u32_e32 v49, vcc, 0, v61, vcc
	global_load_dwordx4 v[44:47], v[44:45], off nt
	s_nop 0
	global_load_dwordx4 v[48:51], v[48:49], off nt
	v_add_co_u32_e32 v52, vcc, s6, v60
	s_mov_b32 s6, 0x20c4000
	s_nop 0
	v_addc_co_u32_e32 v53, vcc, 0, v61, vcc
	v_add_co_u32_e32 v56, vcc, s6, v60
	s_mov_b32 s6, 0x20e0000
	s_nop 0
	v_addc_co_u32_e32 v57, vcc, 0, v61, vcc
	global_load_dwordx4 v[52:55], v[52:53], off nt
	s_nop 0
	global_load_dwordx4 v[56:59], v[56:57], off nt
	v_add_co_u32_e32 v62, vcc, s6, v60
	s_mov_b32 s6, 0x20e4000
	s_nop 0
	v_addc_co_u32_e32 v63, vcc, 0, v61, vcc
	v_add_co_u32_e32 v64, vcc, s6, v60
	s_lshl_b32 s5, s5, 1
	s_nop 0
	v_addc_co_u32_e32 v65, vcc, 0, v61, vcc
	global_load_dwordx4 v[60:63], v[62:63], off nt
	s_nop 0
	global_load_dwordx4 v[64:67], v[64:65], off nt
	s_waitcnt vmcnt(0)
; #define LAS __attribute__((address_space(3)))
; #define LDS_WAIT() asm volatile("s_waitcnt lgkmcnt(0)" ::: "memory")
; __device__ __forceinline__ unsigned cvt_pk_bf16(float lo, float hi) { unsigned r; asm volatile("v_cvt_pk_bf16_f32 %0, %1, %2" : "=v"(r) : "v"(lo), "v"(hi)); return r; }
;     ...
; #pragma unroll
;     for (int i = 0; i < 8; ++i)
; #pragma unroll
;         for (int e = 0; e < 4; ++e) *(LAS unsigned*)(scr + (4 * r16 + e) * 128 + ((i ^ (r16 & 7)) * 16) + q * 4) = cvt_pk_bf16(v[2 * i][e], v[2 * i + 1][e]);
;     LDS_WAIT(); asm volatile("" ::: "memory");
;     const int c = lane & 7;
; #pragma unroll
;     for (int j = 0; j < 8; ++j) { const int row = (lane >> 3) + 8 * j; const u32x4 o = *(const LAS u32x4*)(scr + row * 128 + ((c ^ ((row >> 2) & 7)) * 16));
;         const int lc = col_off + n0 + row; int dr;
;         if (MODE == 0) dr = lc;
;         else if (MODE == 1) dr = (lc & ~255) + 128 * ((lc >> 5) & 1) + 32 * ((lc >> 6) & 3) + (lc & 31);
;         else if (MODE == 2) dr = 256 * (lc >> 7) + (lc & 127);
;         else dr = 256 * (lc >> 7) + 128 + (lc & 127);
;         *(u32x4*)(WT + (size_t)dr * (ldt ? ldt : K) + k0 + 8 * c) = o; }
;     LDS_WAIT(); asm volatile("" ::: "memory");
	v_cvt_pk_bf16_f32 v4, v4, v8
	v_add_u32_e32 v8, v71, v73
	ds_write_b32 v8, v4
	v_cvt_pk_bf16_f32 v4, v5, v9
	ds_write_b32 v8, v4 offset:128
	v_cvt_pk_bf16_f32 v4, v6, v10
	ds_write_b32 v8, v4 offset:256
	v_cvt_pk_bf16_f32 v4, v7, v11
	ds_write_b32 v8, v4 offset:384
	v_cvt_pk_bf16_f32 v4, v12, v16
	v_add_u32_e32 v5, v74, v73
	ds_write_b32 v5, v4
	v_cvt_pk_bf16_f32 v4, v13, v17
	ds_write_b32 v5, v4 offset:128
	v_cvt_pk_bf16_f32 v4, v14, v18
	ds_write_b32 v5, v4 offset:256
	v_cvt_pk_bf16_f32 v4, v15, v19
	ds_write_b32 v5, v4 offset:384
	v_cvt_pk_bf16_f32 v4, v20, v24
	v_add_u32_e32 v5, v75, v73
	ds_write_b32 v5, v4
	v_cvt_pk_bf16_f32 v4, v21, v25
	ds_write_b32 v5, v4 offset:128
	v_cvt_pk_bf16_f32 v4, v22, v26
	ds_write_b32 v5, v4 offset:256
	v_cvt_pk_bf16_f32 v4, v23, v27
	ds_write_b32 v5, v4 offset:384
	v_cvt_pk_bf16_f32 v4, v28, v32
	v_add_u32_e32 v5, v76, v73
	ds_write_b32 v5, v4
	v_cvt_pk_bf16_f32 v4, v29, v33
	ds_write_b32 v5, v4 offset:128
	v_cvt_pk_bf16_f32 v4, v30, v34
	ds_write_b32 v5, v4 offset:256
	v_cvt_pk_bf16_f32 v4, v31, v35
	ds_write_b32 v5, v4 offset:384
	v_cvt_pk_bf16_f32 v4, v36, v40
	v_add_u32_e32 v5, v77, v73
	ds_write_b32 v5, v4
	v_cvt_pk_bf16_f32 v4, v37, v41
	ds_write_b32 v5, v4 offset:128
	v_cvt_pk_bf16_f32 v4, v38, v42
	ds_write_b32 v5, v4 offset:256
	v_cvt_pk_bf16_f32 v4, v39, v43
	ds_write_b32 v5, v4 offset:384
	v_cvt_pk_bf16_f32 v4, v44, v48
	v_add_u32_e32 v5, v78, v73
	ds_write_b32 v5, v4
	v_cvt_pk_bf16_f32 v4, v45, v49
	ds_write_b32 v5, v4 offset:128
	v_cvt_pk_bf16_f32 v4, v46, v50
	ds_write_b32 v5, v4 offset:256
	v_cvt_pk_bf16_f32 v4, v47, v51
	ds_write_b32 v5, v4 offset:384
	v_cvt_pk_bf16_f32 v4, v52, v56
	v_add_u32_e32 v5, v79, v73
	ds_write_b32 v5, v4
	v_cvt_pk_bf16_f32 v4, v53, v57
	ds_write_b32 v5, v4 offset:128
	v_cvt_pk_bf16_f32 v4, v54, v58
	ds_write_b32 v5, v4 offset:256
	v_cvt_pk_bf16_f32 v4, v55, v59
	ds_write_b32 v5, v4 offset:384
	v_cvt_pk_bf16_f32 v4, v60, v64
	v_add_u32_e32 v5, v80, v73
	ds_write_b32 v5, v4
	v_cvt_pk_bf16_f32 v4, v61, v65
	ds_write_b32 v5, v4 offset:128
	v_cvt_pk_bf16_f32 v4, v62, v66
	ds_write_b32 v5, v4 offset:256
	v_cvt_pk_bf16_f32 v4, v63, v67
	ds_write_b32 v5, v4 offset:384
	s_add_u32 s6, s3, s5
	s_waitcnt lgkmcnt(0)
	s_addc_u32 s7, s4, 0
	v_lshlrev_b32_e32 v4, 1, v70
	v_mov_b32_e32 v5, v2
	v_lshl_add_u64 v[12:13], s[6:7], 0, v[4:5]
	v_add_u32_e32 v4, v82, v83
	ds_read_b128 v[4:7], v4
	v_or_b32_e32 v8, s2, v81
	v_lshlrev_b32_e32 v8, 12, v8
	v_mov_b32_e32 v9, v2
	v_lshl_add_u64 v[14:15], v[12:13], 0, v[8:9]
	v_add_u32_e32 v8, v85, v86
	ds_read_b128 v[8:11], v8
	s_waitcnt lgkmcnt(1)
	global_store_dwordx4 v[14:15], v[4:7], off
	s_nop 1
	v_or_b32_e32 v4, s2, v84
	v_lshlrev_b32_e32 v4, 12, v4
	v_mov_b32_e32 v5, v2
	v_lshl_add_u64 v[4:5], v[12:13], 0, v[4:5]
	s_waitcnt lgkmcnt(0)
	global_store_dwordx4 v[4:5], v[8:11], off
	v_add_u32_e32 v4, v88, v89
	ds_read_b128 v[4:7], v4
	v_or_b32_e32 v8, s2, v87
	v_lshlrev_b32_e32 v8, 12, v8
	v_mov_b32_e32 v9, v2
	v_lshl_add_u64 v[14:15], v[12:13], 0, v[8:9]
	v_add_u32_e32 v8, v91, v92
	ds_read_b128 v[8:11], v8
	s_waitcnt lgkmcnt(1)
	global_store_dwordx4 v[14:15], v[4:7], off
	s_nop 1
	v_or_b32_e32 v4, s2, v90
	v_lshlrev_b32_e32 v4, 12, v4
	v_mov_b32_e32 v5, v2
	v_lshl_add_u64 v[4:5], v[12:13], 0, v[4:5]
	s_waitcnt lgkmcnt(0)
	global_store_dwordx4 v[4:5], v[8:11], off
	v_add_u32_e32 v4, v94, v83
	ds_read_b128 v[4:7], v4
	v_or_b32_e32 v8, s2, v93
	v_lshlrev_b32_e32 v8, 12, v8
	v_mov_b32_e32 v9, v2
	v_lshl_add_u64 v[14:15], v[12:13], 0, v[8:9]
	v_add_u32_e32 v8, v96, v97
	ds_read_b128 v[8:11], v8
	s_waitcnt lgkmcnt(1)
	global_store_dwordx4 v[14:15], v[4:7], off
	s_nop 1
	v_or_b32_e32 v4, s2, v95
	v_lshlrev_b32_e32 v4, 12, v4
	v_mov_b32_e32 v5, v2
	v_lshl_add_u64 v[4:5], v[12:13], 0, v[4:5]
	s_waitcnt lgkmcnt(0)
	global_store_dwordx4 v[4:5], v[8:11], off
	v_add_u32_e32 v4, v99, v100
	ds_read_b128 v[4:7], v4
	v_or_b32_e32 v8, s2, v98
	v_lshlrev_b32_e32 v8, 12, v8
	v_mov_b32_e32 v9, v2
	v_lshl_add_u64 v[14:15], v[12:13], 0, v[8:9]
	v_add_u32_e32 v8, v102, v103
	ds_read_b128 v[8:11], v8
	s_waitcnt lgkmcnt(1)
	global_store_dwordx4 v[14:15], v[4:7], off
	s_nop 1
	v_or_b32_e32 v4, s2, v101
	v_lshlrev_b32_e32 v4, 12, v4
	v_mov_b32_e32 v5, v2
	v_lshl_add_u64 v[4:5], v[12:13], 0, v[4:5]
	s_waitcnt lgkmcnt(0)
	global_store_dwordx4 v[4:5], v[8:11], off
	s_waitcnt lgkmcnt(0)

; #define LAS __attribute__((address_space(3)))
; __device__ __forceinline__ unsigned cvt_pk_bf16(float lo, float hi) { unsigned r; asm volatile("v_cvt_pk_bf16_f32 %0, %1, %2" : "=v"(r) : "v"(lo), "v"(hi)); return r; }
;     const int nblk = N / 64, kb = item / nblk, nb = item % nblk, k0 = 64 * kb, n0 = 64 * nb;
;     const int r16 = lane & 15, q = lane >> 4;
;     const float* src = W + (size_t)(k0 + 2 * q) * N + n0 + 4 * r16;
;     f32x4 v[16];
; #pragma unroll
;     for (int j = 0; j < 16; ++j) v[j] = *(const f32x4*)(src + (size_t)(8 * (j >> 1) + (j & 1)) * N);
;     if (nscale) { const f32x4 ns = *(const f32x4*)(nscale + n0 + 4 * r16);
; #pragma unroll
;         for (int j = 0; j < 16; ++j) v[j] = v[j] * ns; }
;     if (kscale) {
; #pragma unroll
;         for (int i = 0; i < 8; ++i) { const f32x2 g = *(const f32x2*)(kscale + k0 + 8 * i + 2 * q); v[2 * i] = v[2 * i] * g[0]; v[2 * i + 1] = v[2 * i + 1] * g[1]; } }
; #pragma unroll
;     for (int i = 0; i < 8; ++i)
; #pragma unroll
;         for (int e = 0; e < 4; ++e) *(LAS unsigned*)(scr + (4 * r16 + e) * 128 + ((i ^ (r16 & 7)) * 16) + q * 4) = cvt_pk_bf16(v[2 * i][e], v[2 * i + 1][e]);
.LBB0_666:
	s_andn2_b64 vcc, exec, s[4:5]
	s_cbranch_vccnz .LBB0_624
	s_lshl_b64 s[0:1], s[0:1], 26
	s_add_u32 s2, s74, s0
	s_addc_u32 s3, s75, s1
	s_add_i32 s0, s20, 0xee00
	s_and_b32 s1, s0, 0xffc0
	s_lshl_b32 s0, s20, 6
	v_lshlrev_b32_e32 v4, 2, v69
	s_and_b32 s0, s0, 0xfc0
	v_lshl_or_b32 v4, s1, 14, v4
	v_mov_b32_e32 v5, v2
	v_lshl_add_u64 v[4:5], s[2:3], 0, v[4:5]
	s_lshl_b32 s14, s0, 2
	v_lshl_add_u64 v[4:5], v[4:5], 0, s[14:15]
	v_lshlrev_b32_e32 v6, 2, v68
	v_mov_b32_e32 v7, v2
	v_lshl_add_u64 v[60:61], v[4:5], 0, v[6:7]
	s_movk_i32 s2, 0x4000
	v_add_co_u32_e32 v8, vcc, s2, v60
	s_mov_b32 s2, 0x24000
	s_nop 0
	v_addc_co_u32_e32 v9, vcc, 0, v61, vcc
	global_load_dwordx4 v[4:7], v[60:61], off nt
	s_nop 0
	global_load_dwordx4 v[8:11], v[8:9], off nt
	v_add_co_u32_e32 v12, vcc, s22, v60
	s_lshl_b32 s1, s1, 1
	s_nop 0
	v_addc_co_u32_e32 v13, vcc, 0, v61, vcc
	v_add_co_u32_e32 v16, vcc, s2, v60
	s_mov_b32 s2, 0x40000
	s_nop 0
	v_addc_co_u32_e32 v17, vcc, 0, v61, vcc
	global_load_dwordx4 v[12:15], v[12:13], off nt
	s_nop 0
	global_load_dwordx4 v[16:19], v[16:17], off nt
	v_add_co_u32_e32 v20, vcc, s2, v60
	s_mov_b32 s2, 0x44000
	s_nop 0
	v_addc_co_u32_e32 v21, vcc, 0, v61, vcc
	v_add_co_u32_e32 v24, vcc, s2, v60
	s_mov_b32 s2, 0x60000
	s_nop 0
	v_addc_co_u32_e32 v25, vcc, 0, v61, vcc
	global_load_dwordx4 v[20:23], v[20:21], off nt
	s_nop 0
	global_load_dwordx4 v[24:27], v[24:25], off nt
	v_add_co_u32_e32 v28, vcc, s2, v60
	s_mov_b32 s2, 0x64000
	s_nop 0
	v_addc_co_u32_e32 v29, vcc, 0, v61, vcc
	v_add_co_u32_e32 v32, vcc, s2, v60
	s_mov_b32 s2, 0x80000
	s_nop 0
	v_addc_co_u32_e32 v33, vcc, 0, v61, vcc
	global_load_dwordx4 v[28:31], v[28:29], off nt
	s_nop 0
	global_load_dwordx4 v[32:35], v[32:33], off nt
	v_add_co_u32_e32 v36, vcc, s2, v60
	s_mov_b32 s2, 0x84000
	s_nop 0
	v_addc_co_u32_e32 v37, vcc, 0, v61, vcc
	v_add_co_u32_e32 v40, vcc, s2, v60
	s_mov_b32 s2, 0xa0000
	s_nop 0
	v_addc_co_u32_e32 v41, vcc, 0, v61, vcc
	global_load_dwordx4 v[36:39], v[36:37], off nt
	s_nop 0
	global_load_dwordx4 v[40:43], v[40:41], off nt
	v_add_co_u32_e32 v44, vcc, s2, v60
	s_mov_b32 s2, 0xa4000
	s_nop 0
	v_addc_co_u32_e32 v45, vcc, 0, v61, vcc
	v_add_co_u32_e32 v48, vcc, s2, v60
	s_mov_b32 s2, 0xc0000
	s_nop 0
	v_addc_co_u32_e32 v49, vcc, 0, v61, vcc
	global_load_dwordx4 v[44:47], v[44:45], off nt
	s_nop 0
	global_load_dwordx4 v[48:51], v[48:49], off nt
	v_add_co_u32_e32 v52, vcc, s2, v60
	s_mov_b32 s2, 0xc4000
	s_nop 0
	v_addc_co_u32_e32 v53, vcc, 0, v61, vcc
	v_add_co_u32_e32 v56, vcc, s2, v60
	s_mov_b32 s2, 0xe0000
	s_nop 0
	v_addc_co_u32_e32 v57, vcc, 0, v61, vcc
	global_load_dwordx4 v[52:55], v[52:53], off nt
	s_nop 0
	global_load_dwordx4 v[56:59], v[56:57], off nt
	v_add_co_u32_e32 v62, vcc, s2, v60
	s_mov_b32 s2, 0xe4000
	s_nop 0
	v_addc_co_u32_e32 v63, vcc, 0, v61, vcc
	v_add_co_u32_e32 v64, vcc, s2, v60
	s_add_u32 s2, s18, s1
	s_nop 0
	v_addc_co_u32_e32 v65, vcc, 0, v61, vcc
	global_load_dwordx4 v[60:63], v[62:63], off nt
	s_nop 0
	global_load_dwordx4 v[64:67], v[64:65], off nt
	s_waitcnt vmcnt(0)
; #define LAS __attribute__((address_space(3)))
; #define LDS_WAIT() asm volatile("s_waitcnt lgkmcnt(0)" ::: "memory")
; __device__ __forceinline__ unsigned cvt_pk_bf16(float lo, float hi) { unsigned r; asm volatile("v_cvt_pk_bf16_f32 %0, %1, %2" : "=v"(r) : "v"(lo), "v"(hi)); return r; }
;     ...
; #pragma unroll
;     for (int i = 0; i < 8; ++i)
; #pragma unroll
;         for (int e = 0; e < 4; ++e) *(LAS unsigned*)(scr + (4 * r16 + e) * 128 + ((i ^ (r16 & 7)) * 16) + q * 4) = cvt_pk_bf16(v[2 * i][e], v[2 * i + 1][e]);
;     LDS_WAIT(); asm volatile("" ::: "memory");
;     const int c = lane & 7;
; #pragma unroll
;     for (int j = 0; j < 8; ++j) { const int row = (lane >> 3) + 8 * j; const u32x4 o = *(const LAS u32x4*)(scr + row * 128 + ((c ^ ((row >> 2) & 7)) * 16));
;         const int lc = col_off + n0 + row; int dr;
;         if (MODE == 0) dr = lc;
;         else if (MODE == 1) dr = (lc & ~255) + 128 * ((lc >> 5) & 1) + 32 * ((lc >> 6) & 3) + (lc & 31);
;         else if (MODE == 2) dr = 256 * (lc >> 7) + (lc & 127);
;         else dr = 256 * (lc >> 7) + 128 + (lc & 127);
;         *(u32x4*)(WT + (size_t)dr * (ldt ? ldt : K) + k0 + 8 * c) = o; }
;     LDS_WAIT(); asm volatile("" ::: "memory");
	v_cvt_pk_bf16_f32 v4, v4, v8
	v_add_u32_e32 v8, v71, v73
	ds_write_b32 v8, v4
	v_cvt_pk_bf16_f32 v4, v5, v9
	ds_write_b32 v8, v4 offset:128
	v_cvt_pk_bf16_f32 v4, v6, v10
	ds_write_b32 v8, v4 offset:256
	v_cvt_pk_bf16_f32 v4, v7, v11
	ds_write_b32 v8, v4 offset:384
	v_cvt_pk_bf16_f32 v4, v12, v16
	v_add_u32_e32 v5, v74, v73
	ds_write_b32 v5, v4
	v_cvt_pk_bf16_f32 v4, v13, v17
	ds_write_b32 v5, v4 offset:128
	v_cvt_pk_bf16_f32 v4, v14, v18
	ds_write_b32 v5, v4 offset:256
	v_cvt_pk_bf16_f32 v4, v15, v19
	ds_write_b32 v5, v4 offset:384
	v_cvt_pk_bf16_f32 v4, v20, v24
	v_add_u32_e32 v5, v75, v73
	ds_write_b32 v5, v4
	v_cvt_pk_bf16_f32 v4, v21, v25
	ds_write_b32 v5, v4 offset:128
	v_cvt_pk_bf16_f32 v4, v22, v26
	ds_write_b32 v5, v4 offset:256
	v_cvt_pk_bf16_f32 v4, v23, v27
	ds_write_b32 v5, v4 offset:384
	v_cvt_pk_bf16_f32 v4, v28, v32
	v_add_u32_e32 v5, v76, v73
	ds_write_b32 v5, v4
	v_cvt_pk_bf16_f32 v4, v29, v33
	ds_write_b32 v5, v4 offset:128
	v_cvt_pk_bf16_f32 v4, v30, v34
	ds_write_b32 v5, v4 offset:256
	v_cvt_pk_bf16_f32 v4, v31, v35
	ds_write_b32 v5, v4 offset:384
	v_cvt_pk_bf16_f32 v4, v36, v40
	v_add_u32_e32 v5, v77, v73
	ds_write_b32 v5, v4
	v_cvt_pk_bf16_f32 v4, v37, v41
	ds_write_b32 v5, v4 offset:128
	v_cvt_pk_bf16_f32 v4, v38, v42
	ds_write_b32 v5, v4 offset:256
	v_cvt_pk_bf16_f32 v4, v39, v43
	ds_write_b32 v5, v4 offset:384
	v_cvt_pk_bf16_f32 v4, v44, v48
	v_add_u32_e32 v5, v78, v73
	ds_write_b32 v5, v4
	v_cvt_pk_bf16_f32 v4, v45, v49
	ds_write_b32 v5, v4 offset:128
	v_cvt_pk_bf16_f32 v4, v46, v50
	ds_write_b32 v5, v4 offset:256
	v_cvt_pk_bf16_f32 v4, v47, v51
	ds_write_b32 v5, v4 offset:384
	v_cvt_pk_bf16_f32 v4, v52, v56
	v_add_u32_e32 v5, v79, v73
	ds_write_b32 v5, v4
	v_cvt_pk_bf16_f32 v4, v53, v57
	ds_write_b32 v5, v4 offset:128
	v_cvt_pk_bf16_f32 v4, v54, v58
	ds_write_b32 v5, v4 offset:256
	v_cvt_pk_bf16_f32 v4, v55, v59
	ds_write_b32 v5, v4 offset:384
	v_cvt_pk_bf16_f32 v4, v60, v64
	v_add_u32_e32 v5, v80, v73
	ds_write_b32 v5, v4
	v_cvt_pk_bf16_f32 v4, v61, v65
	ds_write_b32 v5, v4 offset:128
	v_cvt_pk_bf16_f32 v4, v62, v66
	ds_write_b32 v5, v4 offset:256
	v_cvt_pk_bf16_f32 v4, v63, v67
	ds_write_b32 v5, v4 offset:384
	s_addc_u32 s3, s19, 0
	v_lshlrev_b32_e32 v4, 1, v70
	v_mov_b32_e32 v5, v2
	s_waitcnt lgkmcnt(0)
	v_lshl_add_u64 v[4:5], s[2:3], 0, v[4:5]
	s_mov_b64 s[2:3], 0x2600000
	v_lshl_add_u64 v[12:13], v[4:5], 0, s[2:3]
	v_add_u32_e32 v4, v82, v83
	ds_read_b128 v[4:7], v4
	v_or_b32_e32 v8, s0, v81
	v_lshlrev_b32_e32 v8, 13, v8
	v_mov_b32_e32 v9, v2
	v_lshl_add_u64 v[14:15], v[12:13], 0, v[8:9]
	v_add_u32_e32 v8, v85, v86
	ds_read_b128 v[8:11], v8
	s_waitcnt lgkmcnt(1)
	global_store_dwordx4 v[14:15], v[4:7], off
	s_nop 1
	v_or_b32_e32 v4, s0, v84
	v_lshlrev_b32_e32 v4, 13, v4
	v_mov_b32_e32 v5, v2
	v_lshl_add_u64 v[4:5], v[12:13], 0, v[4:5]
	s_waitcnt lgkmcnt(0)
	global_store_dwordx4 v[4:5], v[8:11], off
	v_add_u32_e32 v4, v88, v89
	ds_read_b128 v[4:7], v4
	v_or_b32_e32 v8, s0, v87
	v_lshlrev_b32_e32 v8, 13, v8
	v_mov_b32_e32 v9, v2
	v_lshl_add_u64 v[14:15], v[12:13], 0, v[8:9]
	v_add_u32_e32 v8, v91, v92
	ds_read_b128 v[8:11], v8
	s_waitcnt lgkmcnt(1)
	global_store_dwordx4 v[14:15], v[4:7], off
	s_nop 1
	v_or_b32_e32 v4, s0, v90
	v_lshlrev_b32_e32 v4, 13, v4
	v_mov_b32_e32 v5, v2
	v_lshl_add_u64 v[4:5], v[12:13], 0, v[4:5]
	s_waitcnt lgkmcnt(0)
	global_store_dwordx4 v[4:5], v[8:11], off
	v_add_u32_e32 v4, v94, v83
	ds_read_b128 v[4:7], v4
	v_or_b32_e32 v8, s0, v93
	v_lshlrev_b32_e32 v8, 13, v8
	v_mov_b32_e32 v9, v2
	v_lshl_add_u64 v[14:15], v[12:13], 0, v[8:9]
	v_add_u32_e32 v8, v96, v97
	ds_read_b128 v[8:11], v8
	s_waitcnt lgkmcnt(1)
	global_store_dwordx4 v[14:15], v[4:7], off
	s_nop 1
	v_or_b32_e32 v4, s0, v95
	v_lshlrev_b32_e32 v4, 13, v4
	v_mov_b32_e32 v5, v2
	v_lshl_add_u64 v[4:5], v[12:13], 0, v[4:5]
	s_waitcnt lgkmcnt(0)
	global_store_dwordx4 v[4:5], v[8:11], off
	v_add_u32_e32 v4, v99, v100
	ds_read_b128 v[4:7], v4
	v_or_b32_e32 v8, s0, v98
	v_lshlrev_b32_e32 v8, 13, v8
	v_mov_b32_e32 v9, v2
	v_lshl_add_u64 v[14:15], v[12:13], 0, v[8:9]
	v_add_u32_e32 v8, v102, v103
	ds_read_b128 v[8:11], v8
	s_waitcnt lgkmcnt(1)
	global_store_dwordx4 v[14:15], v[4:7], off
	s_nop 1
	v_or_b32_e32 v4, s0, v101
	v_lshlrev_b32_e32 v4, 13, v4
	v_mov_b32_e32 v5, v2
	v_lshl_add_u64 v[4:5], v[12:13], 0, v[4:5]
	s_waitcnt lgkmcnt(0)
	global_store_dwordx4 v[4:5], v[8:11], off
	s_waitcnt lgkmcnt(0)
	s_branch .LBB0_624

; __device__ __forceinline__ void weights_pass(const Args& a, LAS unsigned char* scr, int gw, int NGW, int lane, int pass) {
;     ...
;     for (int it = gw + (pass == 1 ? PER_LAYER : 0); it < (pass == 2 ? PER_LAYER : 2 * PER_LAYER); it += NGW) {
;         const int l = it / PER_LAYER; int r = it % PER_LAYER;
;         { const bool shared = (r >= I_IN + I_OUT / 2 && r < I_IN + I_OUT) || (r >= I_IN + I_OUT + I_QM && r < I_IN + I_OUT + 3 * I_QM);
;           const int ip = (shared || (l == 0 && r < I_IN)) ? 0 : (l == 0 ? 2 : 1);
;           if (ip != pass) continue; }
;         unsigned char* wl = ws + WS_W + (size_t)l * WL_SIZE;
;         if (r < I_IN) { transpose_item<1>(a.in[I_WIN] + (size_t)l * DM * INW, DM, INW, (bf16_t*)(wl + WL_IN), a.in[I_GMIX] + l * DM, nullptr, 0, scr, r, lane); continue; } r -= I_IN;
;         if (r < I_OUT / 2) { transpose_item<0>(a.in[I_WOUT] + (size_t)l * DM * DM, 2048, DM, (bf16_t*)(wl + WL_OUT), nullptr, nullptr, 0, scr, r, lane, DM); continue; } r -= I_OUT / 2;
;         if (r < I_OUT / 2) { transpose_item<0>(a.in[I_WOUT] + (size_t)l * DM * DM + (size_t)2048 * DM, 2048, DM, (bf16_t*)(ws + WS_WLOW) + (size_t)l * DM * 2048, nullptr, nullptr, 0, scr, r, lane); continue; } r -= I_OUT / 2;
;         if (r < I_QM) { transpose_item<0>(a.in[I_WQM] + (size_t)l * DM * MW, DM, MW, (bf16_t*)(wl + WL_Q), a.in[I_GCROSS] + l * DM, nullptr, 0, scr, r, lane); continue; } r -= I_QM;
;         if (r < I_QM) { transpose_item<1>(a.in[I_WKM] + (size_t)l * DM * MW, DM, MW, (bf16_t*)(ws + WS_WKV) + (size_t)l * 1024 * DM, a.in[I_GMEM] + l * DM, nullptr, 0, scr, r, lane); continue; } r -= I_QM;
;         if (r < I_QM) { transpose_item<1>(a.in[I_WVM] + (size_t)l * DM * MW, DM, MW, (bf16_t*)(ws + WS_WKV) + (size_t)l * 1024 * DM, a.in[I_GMEM] + l * DM, nullptr, 512, scr, r, lane); continue; } r -= I_QM;
;         if (r < I_OMI) { transpose_item<0>(a.in[I_WOM] + (size_t)l * MW * DM, MW, DM, (bf16_t*)(wl + WL_OM), nullptr, nullptr, 0, scr, r, lane); continue; } r -= I_OMI;
;         if (r < I_G) { transpose_item<2>(a.in[I_WGATE] + (size_t)l * DM * DFF, DM, DFF, (bf16_t*)(wl + WL_GU), a.in[I_GFFN] + l * DM, nullptr, 0, scr, r, lane); continue; } r -= I_G;
;         if (r < I_G) { transpose_item<3>(a.in[I_WUP] + (size_t)l * DM * DFF, DM, DFF, (bf16_t*)(wl + WL_GU), a.in[I_GFFN] + l * DM, nullptr, 0, scr, r, lane); continue; } r -= I_G;
.LBB0_1668:
	s_mul_hi_i32 s0, s10, 0xbfa02fe9
	s_add_i32 s0, s0, s10
	s_lshr_b32 s1, s0, 31
	s_ashr_i32 s0, s0, 15
	s_add_i32 s0, s0, s1
	s_mul_i32 s1, s0, 0xffff5500
	s_add_i32 s21, s10, s1
	s_add_i32 s23, s21, 0xffffe600
	s_cmpk_lt_u32 s23, 0x800
	s_cselect_b64 s[2:3], -1, 0
	s_and_b32 s1, s21, 0xfffffc00
	s_cmpk_eq_i32 s1, 0x2400
	s_cselect_b64 s[6:7], -1, 0
	s_or_b64 s[2:3], s[2:3], s[6:7]
	s_add_i32 s1, s10, 0xffff5500
	s_cmp_gt_u32 s1, 0xfffeaa00
	s_cselect_b64 s[6:7], -1, 0
	s_or_b64 s[2:3], s[6:7], s[2:3]
	s_and_b64 vcc, exec, s[2:3]
	s_cbranch_vccnz .LBB0_1667
	s_ashr_i32 s1, s0, 31
	s_mul_i32 s3, s0, 0x15000000
	v_readlane_b32 s6, v251, 12
	s_mul_hi_i32 s2, s0, 0x15000000
	s_add_u32 s19, s6, s3
	v_readlane_b32 s3, v251, 13
	s_addc_u32 s20, s3, s2
	s_cmpk_gt_i32 s21, 0x11ff
	s_mov_b64 s[6:7], -1
	s_cbranch_scc0 .LBB0_1713
	s_cmpk_gt_u32 s21, 0x19ff
	s_cbranch_scc0 .LBB0_1710
	s_cmpk_gt_u32 s21, 0x21ff
	s_cbranch_scc0 .LBB0_1707
	s_cmpk_gt_u32 s21, 0x23ff
	s_cbranch_scc0 .LBB0_1702
	s_cmpk_gt_u32 s21, 0x25ff
	s_cbranch_scc0 .LBB0_1697
	s_cmpk_gt_u32 s21, 0x27ff
	s_cbranch_scc0 .LBB0_1692
	s_cmpk_gt_u32 s21, 0x29ff
	s_cbranch_scc0 .LBB0_1689
	s_cmpk_gt_u32 s21, 0x54ff
	s_mul_hi_i32 s2, s0, 0xac00000
	s_mul_i32 s3, s0, 0xac00000
	s_cbranch_scc0 .LBB0_1684
	s_cmpk_gt_u32 s21, 0x7fff
	s_cbranch_scc0 .LBB0_1679
	v_readlane_b32 s36, v250, 0
	v_readlane_b32 s42, v250, 6
	v_readlane_b32 s43, v250, 7
	s_add_u32 s8, s42, s3
	s_addc_u32 s9, s43, s2
	s_and_b32 s6, s21, 0xffc0
	s_xor_b32 s7, s6, 0x8000
	s_lshl_b32 s6, s21, 6
	v_lshlrev_b32_e32 v4, 2, v3
	s_and_b32 s6, s6, 0xfc0
	v_lshl_or_b32 v4, s7, 14, v4
	v_mov_b32_e32 v5, v2
	v_lshl_add_u64 v[4:5], s[8:9], 0, v[4:5]
	s_lshl_b32 s14, s6, 2
	v_lshl_add_u64 v[4:5], v[4:5], 0, s[14:15]
	v_lshlrev_b32_e32 v6, 2, v68
	v_mov_b32_e32 v7, v2
	v_lshl_add_u64 v[60:61], v[4:5], 0, v[6:7]
	s_movk_i32 s8, 0x4000
	v_add_co_u32_e32 v8, vcc, s8, v60
	s_mov_b32 s8, 0x24000
	s_nop 0
	v_addc_co_u32_e32 v9, vcc, 0, v61, vcc
	global_load_dwordx4 v[4:7], v[60:61], off nt
	s_nop 0
	global_load_dwordx4 v[8:11], v[8:9], off nt
	v_add_co_u32_e32 v12, vcc, s22, v60
	s_lshl_b32 s7, s7, 1
	s_nop 0
	v_addc_co_u32_e32 v13, vcc, 0, v61, vcc
	v_add_co_u32_e32 v16, vcc, s8, v60
	s_mov_b32 s8, 0x40000
	s_nop 0
	v_addc_co_u32_e32 v17, vcc, 0, v61, vcc
	global_load_dwordx4 v[12:15], v[12:13], off nt
	s_nop 0
	global_load_dwordx4 v[16:19], v[16:17], off nt
	v_add_co_u32_e32 v20, vcc, s8, v60
	s_mov_b32 s8, 0x44000
	s_nop 0
	v_addc_co_u32_e32 v21, vcc, 0, v61, vcc
	v_add_co_u32_e32 v24, vcc, s8, v60
	s_mov_b32 s8, 0x60000
	s_nop 0
	v_addc_co_u32_e32 v25, vcc, 0, v61, vcc
	global_load_dwordx4 v[20:23], v[20:21], off nt
	s_nop 0
	global_load_dwordx4 v[24:27], v[24:25], off nt
	v_add_co_u32_e32 v28, vcc, s8, v60
	s_mov_b32 s8, 0x64000
	s_nop 0
	v_addc_co_u32_e32 v29, vcc, 0, v61, vcc
	v_add_co_u32_e32 v32, vcc, s8, v60
	s_mov_b32 s8, 0x80000
	s_nop 0
	v_addc_co_u32_e32 v33, vcc, 0, v61, vcc
	global_load_dwordx4 v[28:31], v[28:29], off nt
	s_nop 0
	global_load_dwordx4 v[32:35], v[32:33], off nt
	v_add_co_u32_e32 v36, vcc, s8, v60
	s_mov_b32 s8, 0x84000
	s_nop 0
	v_addc_co_u32_e32 v37, vcc, 0, v61, vcc
	v_add_co_u32_e32 v40, vcc, s8, v60
	s_mov_b32 s8, 0xa0000
	s_nop 0
	v_addc_co_u32_e32 v41, vcc, 0, v61, vcc
	global_load_dwordx4 v[36:39], v[36:37], off nt
	s_nop 0
	global_load_dwordx4 v[40:43], v[40:41], off nt
	v_add_co_u32_e32 v44, vcc, s8, v60
	s_mov_b32 s8, 0xa4000
	s_nop 0
	v_addc_co_u32_e32 v45, vcc, 0, v61, vcc
	v_add_co_u32_e32 v48, vcc, s8, v60
	s_mov_b32 s8, 0xc0000
	s_nop 0
	v_addc_co_u32_e32 v49, vcc, 0, v61, vcc
	global_load_dwordx4 v[44:47], v[44:45], off nt
	s_nop 0
	global_load_dwordx4 v[48:51], v[48:49], off nt
	v_add_co_u32_e32 v52, vcc, s8, v60
	s_mov_b32 s8, 0xc4000
	s_nop 0
	v_addc_co_u32_e32 v53, vcc, 0, v61, vcc
	v_add_co_u32_e32 v56, vcc, s8, v60
	s_mov_b32 s8, 0xe0000
	s_nop 0
	v_addc_co_u32_e32 v57, vcc, 0, v61, vcc
	global_load_dwordx4 v[52:55], v[52:53], off nt
	s_nop 0
	global_load_dwordx4 v[56:59], v[56:57], off nt
	v_add_co_u32_e32 v62, vcc, s8, v60
	s_mov_b32 s8, 0xe4000
	s_nop 0
	v_addc_co_u32_e32 v63, vcc, 0, v61, vcc
	v_add_co_u32_e32 v64, vcc, s8, v60
	s_add_u32 s8, s19, s7
	s_nop 0
	v_addc_co_u32_e32 v65, vcc, 0, v61, vcc
	global_load_dwordx4 v[60:63], v[62:63], off nt
	s_nop 0
	global_load_dwordx4 v[64:67], v[64:65], off nt
	s_waitcnt vmcnt(0)
	v_cvt_pk_bf16_f32 v4, v4, v8
	v_add_u32_e32 v8, v69, v71
	ds_write_b32 v8, v4
	v_cvt_pk_bf16_f32 v4, v5, v9
	ds_write_b32 v8, v4 offset:128
	v_cvt_pk_bf16_f32 v4, v6, v10
	ds_write_b32 v8, v4 offset:256
	v_cvt_pk_bf16_f32 v4, v7, v11
	ds_write_b32 v8, v4 offset:384
	v_cvt_pk_bf16_f32 v4, v12, v16
	v_add_u32_e32 v5, v73, v71
	ds_write_b32 v5, v4
	v_cvt_pk_bf16_f32 v4, v13, v17
	ds_write_b32 v5, v4 offset:128
	v_cvt_pk_bf16_f32 v4, v14, v18
	ds_write_b32 v5, v4 offset:256
	v_cvt_pk_bf16_f32 v4, v15, v19
	ds_write_b32 v5, v4 offset:384
	v_cvt_pk_bf16_f32 v4, v20, v24
	v_add_u32_e32 v5, v74, v71
	ds_write_b32 v5, v4
	v_cvt_pk_bf16_f32 v4, v21, v25
	ds_write_b32 v5, v4 offset:128
	v_cvt_pk_bf16_f32 v4, v22, v26
	ds_write_b32 v5, v4 offset:256
	v_cvt_pk_bf16_f32 v4, v23, v27
	ds_write_b32 v5, v4 offset:384
	v_cvt_pk_bf16_f32 v4, v28, v32
	v_add_u32_e32 v5, v75, v71
	ds_write_b32 v5, v4
	v_cvt_pk_bf16_f32 v4, v29, v33
	ds_write_b32 v5, v4 offset:128
	v_cvt_pk_bf16_f32 v4, v30, v34
	ds_write_b32 v5, v4 offset:256
	v_cvt_pk_bf16_f32 v4, v31, v35
	ds_write_b32 v5, v4 offset:384
	v_cvt_pk_bf16_f32 v4, v36, v40
	v_add_u32_e32 v5, v76, v71
	ds_write_b32 v5, v4
	v_cvt_pk_bf16_f32 v4, v37, v41
	ds_write_b32 v5, v4 offset:128
	v_cvt_pk_bf16_f32 v4, v38, v42
	ds_write_b32 v5, v4 offset:256
	v_cvt_pk_bf16_f32 v4, v39, v43
	ds_write_b32 v5, v4 offset:384
	v_cvt_pk_bf16_f32 v4, v44, v48
	v_add_u32_e32 v5, v77, v71
	ds_write_b32 v5, v4
	v_cvt_pk_bf16_f32 v4, v45, v49
	ds_write_b32 v5, v4 offset:128
	v_cvt_pk_bf16_f32 v4, v46, v50
	ds_write_b32 v5, v4 offset:256
	v_cvt_pk_bf16_f32 v4, v47, v51
	ds_write_b32 v5, v4 offset:384
	v_cvt_pk_bf16_f32 v4, v52, v56
	v_add_u32_e32 v5, v78, v71
	ds_write_b32 v5, v4
	v_cvt_pk_bf16_f32 v4, v53, v57
	ds_write_b32 v5, v4 offset:128
	v_cvt_pk_bf16_f32 v4, v54, v58
	ds_write_b32 v5, v4 offset:256
	v_cvt_pk_bf16_f32 v4, v55, v59
	ds_write_b32 v5, v4 offset:384
	v_cvt_pk_bf16_f32 v4, v60, v64
	v_add_u32_e32 v5, v79, v71
	ds_write_b32 v5, v4
	v_cvt_pk_bf16_f32 v4, v61, v65
	ds_write_b32 v5, v4 offset:128
	v_cvt_pk_bf16_f32 v4, v62, v66
	ds_write_b32 v5, v4 offset:256
	v_cvt_pk_bf16_f32 v4, v63, v67
	ds_write_b32 v5, v4 offset:384
	s_addc_u32 s9, s20, 0
	v_lshlrev_b32_e32 v4, 1, v70
	v_mov_b32_e32 v5, v2
	s_waitcnt lgkmcnt(0)
; #define LAS __attribute__((address_space(3)))
; #define LDS_WAIT() asm volatile("s_waitcnt lgkmcnt(0)" ::: "memory")
;     ...
;     LDS_WAIT(); asm volatile("" ::: "memory");
;     const int c = lane & 7;
; #pragma unroll
;     for (int j = 0; j < 8; ++j) { const int row = (lane >> 3) + 8 * j; const u32x4 o = *(const LAS u32x4*)(scr + row * 128 + ((c ^ ((row >> 2) & 7)) * 16));
;         const int lc = col_off + n0 + row; int dr;
;         if (MODE == 0) dr = lc;
;         else if (MODE == 1) dr = (lc & ~255) + 128 * ((lc >> 5) & 1) + 32 * ((lc >> 6) & 3) + (lc & 31);
;         else if (MODE == 2) dr = 256 * (lc >> 7) + (lc & 127);
;         else dr = 256 * (lc >> 7) + 128 + (lc & 127);
;         *(u32x4*)(WT + (size_t)dr * (ldt ? ldt : K) + k0 + 8 * c) = o; }
;     LDS_WAIT(); asm volatile("" ::: "memory");
	v_lshl_add_u64 v[4:5], s[8:9], 0, v[4:5]
	s_mov_b64 s[8:9], 0xfa00000
	v_lshl_add_u64 v[12:13], v[4:5], 0, s[8:9]
	v_add_u32_e32 v4, v81, v82
	ds_read_b128 v[4:7], v4
	v_or_b32_e32 v8, s6, v80
	v_mul_u32_u24_e32 v8, 0x2b00, v8
	v_lshlrev_b32_e32 v8, 1, v8
	v_mov_b32_e32 v9, v2
	v_lshl_add_u64 v[14:15], v[12:13], 0, v[8:9]
	v_add_u32_e32 v8, v84, v85
	ds_read_b128 v[8:11], v8
	s_waitcnt lgkmcnt(1)
	global_store_dwordx4 v[14:15], v[4:7], off
	v_readlane_b32 s37, v250, 1
	v_readlane_b32 s38, v250, 2
	v_or_b32_e32 v4, s6, v83
	v_mul_u32_u24_e32 v4, 0x2b00, v4
	v_lshlrev_b32_e32 v4, 1, v4
	v_mov_b32_e32 v5, v2
	v_lshl_add_u64 v[4:5], v[12:13], 0, v[4:5]
	s_waitcnt lgkmcnt(0)
	global_store_dwordx4 v[4:5], v[8:11], off
	v_add_u32_e32 v4, v87, v88
	ds_read_b128 v[4:7], v4
	v_or_b32_e32 v8, s6, v86
	v_mul_u32_u24_e32 v8, 0x2b00, v8
	v_lshlrev_b32_e32 v8, 1, v8
	v_mov_b32_e32 v9, v2
	v_lshl_add_u64 v[14:15], v[12:13], 0, v[8:9]
	v_add_u32_e32 v8, v90, v91
	ds_read_b128 v[8:11], v8
	s_waitcnt lgkmcnt(1)
	global_store_dwordx4 v[14:15], v[4:7], off
	v_readlane_b32 s39, v250, 3
	v_readlane_b32 s40, v250, 4
	v_or_b32_e32 v4, s6, v89
	v_mul_u32_u24_e32 v4, 0x2b00, v4
	v_lshlrev_b32_e32 v4, 1, v4
	v_mov_b32_e32 v5, v2
	v_lshl_add_u64 v[4:5], v[12:13], 0, v[4:5]
	s_waitcnt lgkmcnt(0)
	global_store_dwordx4 v[4:5], v[8:11], off
	v_add_u32_e32 v4, v93, v82
	ds_read_b128 v[4:7], v4
	v_or_b32_e32 v8, s6, v92
	v_mul_u32_u24_e32 v8, 0x2b00, v8
	v_lshlrev_b32_e32 v8, 1, v8
	v_mov_b32_e32 v9, v2
	v_lshl_add_u64 v[14:15], v[12:13], 0, v[8:9]
	v_add_u32_e32 v8, v95, v96
	ds_read_b128 v[8:11], v8
	s_waitcnt lgkmcnt(1)
	global_store_dwordx4 v[14:15], v[4:7], off
	v_readlane_b32 s41, v250, 5
	s_nop 0
	v_or_b32_e32 v4, s6, v94
	v_mul_u32_u24_e32 v4, 0x2b00, v4
	v_lshlrev_b32_e32 v4, 1, v4
	v_mov_b32_e32 v5, v2
	v_lshl_add_u64 v[4:5], v[12:13], 0, v[4:5]
	s_waitcnt lgkmcnt(0)
	global_store_dwordx4 v[4:5], v[8:11], off
	v_add_u32_e32 v4, v98, v99
	ds_read_b128 v[4:7], v4
	v_or_b32_e32 v8, s6, v97
	v_mul_u32_u24_e32 v8, 0x2b00, v8
	v_lshlrev_b32_e32 v8, 1, v8
	v_mov_b32_e32 v9, v2
	v_lshl_add_u64 v[14:15], v[12:13], 0, v[8:9]
	v_add_u32_e32 v8, v101, v102
	ds_read_b128 v[8:11], v8
	s_waitcnt lgkmcnt(1)
	global_store_dwordx4 v[14:15], v[4:7], off
	s_nop 1
	v_or_b32_e32 v4, s6, v100
	v_mul_u32_u24_e32 v4, 0x2b00, v4
	v_lshlrev_b32_e32 v4, 1, v4
	v_mov_b32_e32 v5, v2
	v_lshl_add_u64 v[4:5], v[12:13], 0, v[4:5]
	s_waitcnt lgkmcnt(0)
	global_store_dwordx4 v[4:5], v[8:11], off
	s_waitcnt lgkmcnt(0)
	s_mov_b64 s[6:7], 0
;     const int nblk = N / 64, kb = item / nblk, nb = item % nblk, k0 = 64 * kb, n0 = 64 * nb;
;     const int r16 = lane & 15, q = lane >> 4;
;     const float* src = W + (size_t)(k0 + 2 * q) * N + n0 + 4 * r16;
;     f32x4 v[16];
; #pragma unroll
;     for (int j = 0; j < 16; ++j) v[j] = *(const f32x4*)(src + (size_t)(8 * (j >> 1) + (j & 1)) * N);
;     if (nscale) { const f32x4 ns = *(const f32x4*)(nscale + n0 + 4 * r16);
; #pragma unroll
;         for (int j = 0; j < 16; ++j) v[j] = v[j] * ns; }
;     if (kscale) {
; #pragma unroll
;         for (int i = 0; i < 8; ++i) { const f32x2 g = *(const f32x2*)(kscale + k0 + 8 * i + 2 * q); v[2 * i] = v[2 * i] * g[0]; v[2 * i + 1] = v[2 * i + 1] * g[1]; } }
.LBB0_1679:
	s_andn2_b64 vcc, exec, s[6:7]
	s_cbranch_vccnz .LBB0_1683
	v_readlane_b32 s36, v250, 0
	v_readlane_b32 s40, v250, 4
	v_readlane_b32 s41, v250, 5
	s_add_u32 s6, s40, s3
	s_addc_u32 s7, s41, s2
	s_add_i32 s8, s21, 0xab00
	s_and_b32 s9, s8, 0xffff
	s_mul_i32 s9, s9, 0xbe83
	s_lshr_b32 s14, s9, 23
	s_mul_i32 s9, s14, 0xac
	s_sub_i32 s8, s8, s9
	s_and_b32 s9, s8, 0xffff
	s_lshl_b32 s8, s14, 6
	v_or_b32_e32 v4, s8, v72
	v_mul_u32_u24_e32 v4, 0x2b00, v4
	v_lshlrev_b32_e32 v4, 2, v4
	v_mov_b32_e32 v5, v2
	v_lshl_add_u64 v[4:5], s[6:7], 0, v[4:5]
	s_lshl_b32 s14, s9, 8
	v_lshl_add_u64 v[4:5], v[4:5], 0, s[14:15]
	v_lshlrev_b32_e32 v6, 2, v68
	v_mov_b32_e32 v7, v2
	v_lshl_add_u64 v[4:5], v[4:5], 0, v[6:7]
	s_mov_b32 s6, 0xa000
	v_add_co_u32_e32 v6, vcc, s6, v4
	s_mov_b32 s6, 0x56000
	s_nop 0
	v_addc_co_u32_e32 v7, vcc, 0, v5, vcc
	global_load_dwordx4 v[60:63], v[4:5], off nt
	global_load_dwordx4 v[64:67], v[6:7], off offset:3072 nt
	v_add_co_u32_e32 v6, vcc, s6, v4
	s_mov_b32 s6, 0x60000
	s_nop 0
	v_addc_co_u32_e32 v7, vcc, 0, v5, vcc
	v_add_co_u32_e32 v8, vcc, s6, v4
	s_mov_b32 s6, 0xac000
	s_nop 0
	v_addc_co_u32_e32 v9, vcc, 0, v5, vcc
	global_load_dwordx4 v[52:55], v[6:7], off nt
	global_load_dwordx4 v[56:59], v[8:9], off offset:3072 nt
	v_add_co_u32_e32 v6, vcc, s6, v4
	s_mov_b32 s6, 0xb6000
	s_nop 0
	v_addc_co_u32_e32 v7, vcc, 0, v5, vcc
	v_add_co_u32_e32 v8, vcc, s6, v4
	s_mov_b32 s6, 0x102000
	s_nop 0
	v_addc_co_u32_e32 v9, vcc, 0, v5, vcc
	global_load_dwordx4 v[44:47], v[6:7], off nt
	global_load_dwordx4 v[48:51], v[8:9], off offset:3072 nt
	v_add_co_u32_e32 v6, vcc, s6, v4
	s_mov_b32 s6, 0x10c000
	s_nop 0
	v_addc_co_u32_e32 v7, vcc, 0, v5, vcc
	v_add_co_u32_e32 v8, vcc, s6, v4
	s_mov_b32 s6, 0x158000
	s_nop 0
	v_addc_co_u32_e32 v9, vcc, 0, v5, vcc
	global_load_dwordx4 v[36:39], v[6:7], off nt
	global_load_dwordx4 v[40:43], v[8:9], off offset:3072 nt
	v_add_co_u32_e32 v6, vcc, s6, v4
	s_mov_b32 s6, 0x162000
	s_nop 0
	v_addc_co_u32_e32 v7, vcc, 0, v5, vcc
	v_add_co_u32_e32 v8, vcc, s6, v4
	s_mov_b32 s6, 0x1ae000
	s_nop 0
	v_addc_co_u32_e32 v9, vcc, 0, v5, vcc
	global_load_dwordx4 v[20:23], v[6:7], off nt
	global_load_dwordx4 v[32:35], v[8:9], off offset:3072 nt
	v_add_co_u32_e32 v6, vcc, s6, v4
	s_mov_b32 s6, 0x1b8000
	s_nop 0
	v_addc_co_u32_e32 v7, vcc, 0, v5, vcc
	v_add_co_u32_e32 v8, vcc, s6, v4
	s_mov_b32 s6, 0x204000
	s_nop 0
	v_addc_co_u32_e32 v9, vcc, 0, v5, vcc
	global_load_dwordx4 v[16:19], v[6:7], off nt
	global_load_dwordx4 v[28:31], v[8:9], off offset:3072 nt
	v_add_co_u32_e32 v6, vcc, s6, v4
	v_readlane_b32 s6, v253, 7
	s_nop 0
	v_addc_co_u32_e32 v7, vcc, 0, v5, vcc
	v_add_co_u32_e32 v12, vcc, 0x20e000, v4
	v_readlane_b32 s7, v253, 8
	s_nop 0
	v_addc_co_u32_e32 v13, vcc, 0, v5, vcc
	global_load_dwordx4 v[8:11], v[6:7], off nt
	global_load_dwordx4 v[24:27], v[12:13], off offset:3072 nt
	v_add_co_u32_e32 v6, vcc, 0x25a000, v4
	v_readlane_b32 s37, v250, 1
	s_nop 0
	v_addc_co_u32_e32 v7, vcc, 0, v5, vcc
	v_add_co_u32_e32 v12, vcc, 0x264000, v4
	v_readlane_b32 s38, v250, 2
	s_nop 0
	v_addc_co_u32_e32 v13, vcc, 0, v5, vcc
	global_load_dwordx4 v[4:7], v[6:7], off nt
	s_nop 0
	global_load_dwordx4 v[12:15], v[12:13], off offset:3072 nt
	s_andn2_b64 vcc, exec, s[6:7]
	v_readlane_b32 s39, v250, 3
	v_readlane_b32 s42, v250, 6
	v_readlane_b32 s43, v250, 7
	s_cbranch_vccnz .LBB0_1682
	s_lshl_b32 s6, s0, 12
	s_ashr_i32 s7, s6, 31
	s_lshl_b64 s[6:7], s[6:7], 2
	s_add_u32 s6, s36, s6
	s_addc_u32 s7, s37, s7
	s_lshl_b32 s14, s8, 2
	s_add_u32 s6, s6, s14
	s_addc_u32 s7, s7, 0
	v_lshlrev_b32_e32 v103, 2, v72
	global_load_dwordx2 v[104:105], v103, s[6:7]
	s_waitcnt vmcnt(0)
	v_pk_mul_f32 v[62:63], v[62:63], v[104:105] op_sel_hi:[1,0]
	v_pk_mul_f32 v[60:61], v[60:61], v[104:105] op_sel_hi:[1,0]
	v_pk_mul_f32 v[66:67], v[66:67], v[104:105] op_sel:[0,1]
	v_pk_mul_f32 v[64:65], v[64:65], v[104:105] op_sel:[0,1]
	global_load_dwordx2 v[104:105], v103, s[6:7] offset:32
	s_waitcnt vmcnt(0)
	v_pk_mul_f32 v[54:55], v[54:55], v[104:105] op_sel_hi:[1,0]
	v_pk_mul_f32 v[52:53], v[52:53], v[104:105] op_sel_hi:[1,0]
	v_pk_mul_f32 v[58:59], v[58:59], v[104:105] op_sel:[0,1]
	v_pk_mul_f32 v[56:57], v[56:57], v[104:105] op_sel:[0,1]
	global_load_dwordx2 v[104:105], v103, s[6:7] offset:64
	s_waitcnt vmcnt(0)
	v_pk_mul_f32 v[46:47], v[46:47], v[104:105] op_sel_hi:[1,0]
	v_pk_mul_f32 v[44:45], v[44:45], v[104:105] op_sel_hi:[1,0]
	v_pk_mul_f32 v[50:51], v[50:51], v[104:105] op_sel:[0,1]
	v_pk_mul_f32 v[48:49], v[48:49], v[104:105] op_sel:[0,1]
	global_load_dwordx2 v[104:105], v103, s[6:7] offset:96
	s_waitcnt vmcnt(0)
	v_pk_mul_f32 v[38:39], v[38:39], v[104:105] op_sel_hi:[1,0]
	v_pk_mul_f32 v[36:37], v[36:37], v[104:105] op_sel_hi:[1,0]
	v_pk_mul_f32 v[42:43], v[42:43], v[104:105] op_sel:[0,1]
	v_pk_mul_f32 v[40:41], v[40:41], v[104:105] op_sel:[0,1]
	global_load_dwordx2 v[104:105], v103, s[6:7] offset:128
	s_waitcnt vmcnt(0)
	v_pk_mul_f32 v[22:23], v[22:23], v[104:105] op_sel_hi:[1,0]
	v_pk_mul_f32 v[20:21], v[20:21], v[104:105] op_sel_hi:[1,0]
	v_pk_mul_f32 v[34:35], v[34:35], v[104:105] op_sel:[0,1]
	v_pk_mul_f32 v[32:33], v[32:33], v[104:105] op_sel:[0,1]
	global_load_dwordx2 v[104:105], v103, s[6:7] offset:160
	s_waitcnt vmcnt(0)
	v_pk_mul_f32 v[18:19], v[18:19], v[104:105] op_sel_hi:[1,0]
	v_pk_mul_f32 v[16:17], v[16:17], v[104:105] op_sel_hi:[1,0]
	v_pk_mul_f32 v[30:31], v[30:31], v[104:105] op_sel:[0,1]
	v_pk_mul_f32 v[28:29], v[28:29], v[104:105] op_sel:[0,1]
	global_load_dwordx2 v[104:105], v103, s[6:7] offset:192
	s_waitcnt vmcnt(0)
	v_pk_mul_f32 v[10:11], v[10:11], v[104:105] op_sel_hi:[1,0]
	v_pk_mul_f32 v[8:9], v[8:9], v[104:105] op_sel_hi:[1,0]
	v_pk_mul_f32 v[26:27], v[26:27], v[104:105] op_sel:[0,1]
	v_pk_mul_f32 v[24:25], v[24:25], v[104:105] op_sel:[0,1]
	global_load_dwordx2 v[104:105], v103, s[6:7] offset:224
	s_waitcnt vmcnt(0)
	v_pk_mul_f32 v[6:7], v[6:7], v[104:105] op_sel_hi:[1,0]
	v_pk_mul_f32 v[4:5], v[4:5], v[104:105] op_sel_hi:[1,0]
	v_pk_mul_f32 v[14:15], v[14:15], v[104:105] op_sel:[0,1]
	v_pk_mul_f32 v[12:13], v[12:13], v[104:105] op_sel:[0,1]

;     const int nblk = N / 64, kb = item / nblk, nb = item % nblk, k0 = 64 * kb, n0 = 64 * nb;
;     const int r16 = lane & 15, q = lane >> 4;
;     const float* src = W + (size_t)(k0 + 2 * q) * N + n0 + 4 * r16;
;     f32x4 v[16];
; #pragma unroll
;     for (int j = 0; j < 16; ++j) v[j] = *(const f32x4*)(src + (size_t)(8 * (j >> 1) + (j & 1)) * N);
;     if (nscale) { const f32x4 ns = *(const f32x4*)(nscale + n0 + 4 * r16);
; #pragma unroll
;         for (int j = 0; j < 16; ++j) v[j] = v[j] * ns; }
;     if (kscale) {
; #pragma unroll
;         for (int i = 0; i < 8; ++i) { const f32x2 g = *(const f32x2*)(kscale + k0 + 8 * i + 2 * q); v[2 * i] = v[2 * i] * g[0]; v[2 * i + 1] = v[2 * i + 1] * g[1]; } }
.LBB0_1684:
	s_andn2_b64 vcc, exec, s[6:7]
	s_cbranch_vccnz .LBB0_1688
	v_readlane_b32 s36, v250, 0
	v_readlane_b32 s38, v250, 2
	v_readlane_b32 s39, v250, 3
	s_add_u32 s6, s38, s3
	s_addc_u32 s7, s39, s2
	s_add_i32 s2, s21, 0xd600
	s_and_b32 s3, s2, 0xffff
	s_mul_i32 s3, s3, 0xbe83
	s_lshr_b32 s8, s3, 23
	s_mul_i32 s3, s8, 0xac
	s_sub_i32 s2, s2, s3
	s_and_b32 s3, s2, 0xffff
	s_lshl_b32 s2, s8, 6
	v_or_b32_e32 v4, s2, v72
	v_mul_u32_u24_e32 v4, 0x2b00, v4
	v_lshlrev_b32_e32 v4, 2, v4
	v_mov_b32_e32 v5, v2
	v_lshl_add_u64 v[4:5], s[6:7], 0, v[4:5]
	s_lshl_b32 s14, s3, 8
	v_lshl_add_u64 v[4:5], v[4:5], 0, s[14:15]
	v_lshlrev_b32_e32 v6, 2, v68
	v_mov_b32_e32 v7, v2
	v_lshl_add_u64 v[4:5], v[4:5], 0, v[6:7]
	s_mov_b32 s6, 0xa000
	v_add_co_u32_e32 v6, vcc, s6, v4
	s_mov_b32 s6, 0x56000
	s_nop 0
	v_addc_co_u32_e32 v7, vcc, 0, v5, vcc
	global_load_dwordx4 v[60:63], v[4:5], off nt
	global_load_dwordx4 v[64:67], v[6:7], off offset:3072 nt
	v_add_co_u32_e32 v6, vcc, s6, v4
	s_mov_b32 s6, 0x60000
	s_nop 0
	v_addc_co_u32_e32 v7, vcc, 0, v5, vcc
	v_add_co_u32_e32 v8, vcc, s6, v4
	s_mov_b32 s6, 0xac000
	s_nop 0
	v_addc_co_u32_e32 v9, vcc, 0, v5, vcc
	global_load_dwordx4 v[52:55], v[6:7], off nt
	global_load_dwordx4 v[56:59], v[8:9], off offset:3072 nt
	v_add_co_u32_e32 v6, vcc, s6, v4
	s_mov_b32 s6, 0xb6000
	s_nop 0
	v_addc_co_u32_e32 v7, vcc, 0, v5, vcc
	v_add_co_u32_e32 v8, vcc, s6, v4
	s_mov_b32 s6, 0x102000
	s_nop 0
	v_addc_co_u32_e32 v9, vcc, 0, v5, vcc
	global_load_dwordx4 v[44:47], v[6:7], off nt
	global_load_dwordx4 v[48:51], v[8:9], off offset:3072 nt
	v_add_co_u32_e32 v6, vcc, s6, v4
	s_mov_b32 s6, 0x10c000
	s_nop 0
	v_addc_co_u32_e32 v7, vcc, 0, v5, vcc
	v_add_co_u32_e32 v8, vcc, s6, v4
	s_mov_b32 s6, 0x158000
	s_nop 0
	v_addc_co_u32_e32 v9, vcc, 0, v5, vcc
	global_load_dwordx4 v[36:39], v[6:7], off nt
	global_load_dwordx4 v[40:43], v[8:9], off offset:3072 nt
	v_add_co_u32_e32 v6, vcc, s6, v4
	s_mov_b32 s6, 0x162000
	s_nop 0
	v_addc_co_u32_e32 v7, vcc, 0, v5, vcc
	v_add_co_u32_e32 v8, vcc, s6, v4
	s_mov_b32 s6, 0x1ae000
	s_nop 0
	v_addc_co_u32_e32 v9, vcc, 0, v5, vcc
	global_load_dwordx4 v[20:23], v[6:7], off nt
	global_load_dwordx4 v[32:35], v[8:9], off offset:3072 nt
	v_add_co_u32_e32 v6, vcc, s6, v4
	s_mov_b32 s6, 0x1b8000
	s_nop 0
	v_addc_co_u32_e32 v7, vcc, 0, v5, vcc
	v_add_co_u32_e32 v8, vcc, s6, v4
	s_mov_b32 s6, 0x204000
	s_nop 0
	v_addc_co_u32_e32 v9, vcc, 0, v5, vcc
	global_load_dwordx4 v[16:19], v[6:7], off nt
	global_load_dwordx4 v[28:31], v[8:9], off offset:3072 nt
	v_add_co_u32_e32 v6, vcc, s6, v4
	v_readlane_b32 s6, v253, 7
	s_nop 0
	v_addc_co_u32_e32 v7, vcc, 0, v5, vcc
	v_add_co_u32_e32 v12, vcc, 0x20e000, v4
	v_readlane_b32 s7, v253, 8
	s_nop 0
	v_addc_co_u32_e32 v13, vcc, 0, v5, vcc
	global_load_dwordx4 v[8:11], v[6:7], off nt
	global_load_dwordx4 v[24:27], v[12:13], off offset:3072 nt
	v_add_co_u32_e32 v6, vcc, 0x25a000, v4
	v_readlane_b32 s37, v250, 1
	s_nop 0
	v_addc_co_u32_e32 v7, vcc, 0, v5, vcc
	v_add_co_u32_e32 v12, vcc, 0x264000, v4
	v_readlane_b32 s40, v250, 4
	s_nop 0
	v_addc_co_u32_e32 v13, vcc, 0, v5, vcc
	global_load_dwordx4 v[4:7], v[6:7], off nt
	s_nop 0
	global_load_dwordx4 v[12:15], v[12:13], off offset:3072 nt
	s_andn2_b64 vcc, exec, s[6:7]
	v_readlane_b32 s41, v250, 5
	v_readlane_b32 s42, v250, 6
	v_readlane_b32 s43, v250, 7
	s_cbranch_vccnz .LBB0_1687
	s_lshl_b32 s6, s0, 12
	s_ashr_i32 s7, s6, 31
	s_lshl_b64 s[6:7], s[6:7], 2
	s_add_u32 s6, s36, s6
	s_addc_u32 s7, s37, s7
	s_lshl_b32 s8, s2, 2
	s_add_u32 s6, s6, s8
	s_addc_u32 s7, s7, 0
	v_lshlrev_b32_e32 v103, 2, v72
	global_load_dwordx2 v[104:105], v103, s[6:7]
	s_waitcnt vmcnt(0)
	v_pk_mul_f32 v[62:63], v[62:63], v[104:105] op_sel_hi:[1,0]
	v_pk_mul_f32 v[60:61], v[60:61], v[104:105] op_sel_hi:[1,0]
	v_pk_mul_f32 v[66:67], v[66:67], v[104:105] op_sel:[0,1]
	v_pk_mul_f32 v[64:65], v[64:65], v[104:105] op_sel:[0,1]
	global_load_dwordx2 v[104:105], v103, s[6:7] offset:32
	s_waitcnt vmcnt(0)
	v_pk_mul_f32 v[54:55], v[54:55], v[104:105] op_sel_hi:[1,0]
	v_pk_mul_f32 v[52:53], v[52:53], v[104:105] op_sel_hi:[1,0]
	v_pk_mul_f32 v[58:59], v[58:59], v[104:105] op_sel:[0,1]
	v_pk_mul_f32 v[56:57], v[56:57], v[104:105] op_sel:[0,1]
	global_load_dwordx2 v[104:105], v103, s[6:7] offset:64
	s_waitcnt vmcnt(0)
	v_pk_mul_f32 v[46:47], v[46:47], v[104:105] op_sel_hi:[1,0]
	v_pk_mul_f32 v[44:45], v[44:45], v[104:105] op_sel_hi:[1,0]
	v_pk_mul_f32 v[50:51], v[50:51], v[104:105] op_sel:[0,1]
	v_pk_mul_f32 v[48:49], v[48:49], v[104:105] op_sel:[0,1]
	global_load_dwordx2 v[104:105], v103, s[6:7] offset:96
	s_waitcnt vmcnt(0)
	v_pk_mul_f32 v[38:39], v[38:39], v[104:105] op_sel_hi:[1,0]
	v_pk_mul_f32 v[36:37], v[36:37], v[104:105] op_sel_hi:[1,0]
	v_pk_mul_f32 v[42:43], v[42:43], v[104:105] op_sel:[0,1]
	v_pk_mul_f32 v[40:41], v[40:41], v[104:105] op_sel:[0,1]
	global_load_dwordx2 v[104:105], v103, s[6:7] offset:128
	s_waitcnt vmcnt(0)
	v_pk_mul_f32 v[22:23], v[22:23], v[104:105] op_sel_hi:[1,0]
	v_pk_mul_f32 v[20:21], v[20:21], v[104:105] op_sel_hi:[1,0]
	v_pk_mul_f32 v[34:35], v[34:35], v[104:105] op_sel:[0,1]
	v_pk_mul_f32 v[32:33], v[32:33], v[104:105] op_sel:[0,1]
	global_load_dwordx2 v[104:105], v103, s[6:7] offset:160
	s_waitcnt vmcnt(0)
	v_pk_mul_f32 v[18:19], v[18:19], v[104:105] op_sel_hi:[1,0]
	v_pk_mul_f32 v[16:17], v[16:17], v[104:105] op_sel_hi:[1,0]
	v_pk_mul_f32 v[30:31], v[30:31], v[104:105] op_sel:[0,1]
	v_pk_mul_f32 v[28:29], v[28:29], v[104:105] op_sel:[0,1]
	global_load_dwordx2 v[104:105], v103, s[6:7] offset:192
	s_waitcnt vmcnt(0)
	v_pk_mul_f32 v[10:11], v[10:11], v[104:105] op_sel_hi:[1,0]
	v_pk_mul_f32 v[8:9], v[8:9], v[104:105] op_sel_hi:[1,0]
	v_pk_mul_f32 v[26:27], v[26:27], v[104:105] op_sel:[0,1]
	v_pk_mul_f32 v[24:25], v[24:25], v[104:105] op_sel:[0,1]
	global_load_dwordx2 v[104:105], v103, s[6:7] offset:224
	s_waitcnt vmcnt(0)
	v_pk_mul_f32 v[6:7], v[6:7], v[104:105] op_sel_hi:[1,0]
	v_pk_mul_f32 v[4:5], v[4:5], v[104:105] op_sel_hi:[1,0]
	v_pk_mul_f32 v[14:15], v[14:15], v[104:105] op_sel:[0,1]
	v_pk_mul_f32 v[12:13], v[12:13], v[104:105] op_sel:[0,1]

;     const int nblk = N / 64, kb = item / nblk, nb = item % nblk, k0 = 64 * kb, n0 = 64 * nb;
;     const int r16 = lane & 15, q = lane >> 4;
;     const float* src = W + (size_t)(k0 + 2 * q) * N + n0 + 4 * r16;
;     f32x4 v[16];
; #pragma unroll
;     for (int j = 0; j < 16; ++j) v[j] = *(const f32x4*)(src + (size_t)(8 * (j >> 1) + (j & 1)) * N);
; __device__ __forceinline__ void weights_pass(const Args& a, LAS unsigned char* scr, int gw, int NGW, int lane, int pass) {
;     ...
;         if (r < I_OMI) { transpose_item<0>(a.in[I_WOM] + (size_t)l * MW * DM, MW, DM, (bf16_t*)(wl + WL_OM), nullptr, nullptr, 0, scr, r, lane); continue; } r -= I_OMI;
.LBB0_1689:
	s_andn2_b64 vcc, exec, s[6:7]
	s_cbranch_vccnz .LBB0_1691
	v_readlane_b32 s36, v250, 46
	s_lshl_b64 s[2:3], s[0:1], 23
	v_readlane_b32 s50, v250, 60
	v_readlane_b32 s51, v250, 61
	s_add_u32 s6, s50, s2
	s_addc_u32 s7, s51, s3
	s_add_i32 s2, s21, 0xd800
	s_and_b32 s3, s2, 0xffc0
	s_lshl_b32 s2, s21, 6
	v_lshlrev_b32_e32 v4, 2, v3
	s_and_b32 s2, s2, 0xfc0
	v_lshl_or_b32 v4, s3, 14, v4
	v_mov_b32_e32 v5, v2
	v_lshl_add_u64 v[4:5], s[6:7], 0, v[4:5]
	s_lshl_b32 s14, s2, 2
	v_lshl_add_u64 v[4:5], v[4:5], 0, s[14:15]
	v_lshlrev_b32_e32 v6, 2, v68
	v_mov_b32_e32 v7, v2
	v_lshl_add_u64 v[60:61], v[4:5], 0, v[6:7]
	s_movk_i32 s6, 0x4000
	v_add_co_u32_e32 v8, vcc, s6, v60
	s_mov_b32 s6, 0x24000
	s_nop 0
	v_addc_co_u32_e32 v9, vcc, 0, v61, vcc
	global_load_dwordx4 v[4:7], v[60:61], off nt
	s_nop 0
	global_load_dwordx4 v[8:11], v[8:9], off nt
	v_add_co_u32_e32 v12, vcc, s22, v60
	s_lshl_b32 s3, s3, 1
	s_nop 0
	v_addc_co_u32_e32 v13, vcc, 0, v61, vcc
	v_add_co_u32_e32 v16, vcc, s6, v60
	s_mov_b32 s6, 0x40000
	s_nop 0
	v_addc_co_u32_e32 v17, vcc, 0, v61, vcc
	global_load_dwordx4 v[12:15], v[12:13], off nt
	s_nop 0
	global_load_dwordx4 v[16:19], v[16:17], off nt
	v_add_co_u32_e32 v20, vcc, s6, v60
	s_mov_b32 s6, 0x44000
	s_nop 0
	v_addc_co_u32_e32 v21, vcc, 0, v61, vcc
	v_add_co_u32_e32 v24, vcc, s6, v60
	s_mov_b32 s6, 0x60000
	s_nop 0
	v_addc_co_u32_e32 v25, vcc, 0, v61, vcc
	global_load_dwordx4 v[20:23], v[20:21], off nt
	s_nop 0
	global_load_dwordx4 v[24:27], v[24:25], off nt
	v_add_co_u32_e32 v28, vcc, s6, v60
	s_mov_b32 s6, 0x64000
	s_nop 0
	v_addc_co_u32_e32 v29, vcc, 0, v61, vcc
	v_add_co_u32_e32 v32, vcc, s6, v60
	s_mov_b32 s6, 0x80000
	s_nop 0
	v_addc_co_u32_e32 v33, vcc, 0, v61, vcc
	global_load_dwordx4 v[28:31], v[28:29], off nt
	s_nop 0
	global_load_dwordx4 v[32:35], v[32:33], off nt
	v_add_co_u32_e32 v36, vcc, s6, v60
	s_mov_b32 s6, 0x84000
	s_nop 0
	v_addc_co_u32_e32 v37, vcc, 0, v61, vcc
	v_add_co_u32_e32 v40, vcc, s6, v60
	s_mov_b32 s6, 0xa0000
	s_nop 0
	v_addc_co_u32_e32 v41, vcc, 0, v61, vcc
	global_load_dwordx4 v[36:39], v[36:37], off nt
	s_nop 0
	global_load_dwordx4 v[40:43], v[40:41], off nt
	v_add_co_u32_e32 v44, vcc, s6, v60
	s_mov_b32 s6, 0xa4000
	s_nop 0
	v_addc_co_u32_e32 v45, vcc, 0, v61, vcc
	v_add_co_u32_e32 v48, vcc, s6, v60
	s_mov_b32 s6, 0xc0000
	s_nop 0
	v_addc_co_u32_e32 v49, vcc, 0, v61, vcc
	global_load_dwordx4 v[44:47], v[44:45], off nt
	s_nop 0
	global_load_dwordx4 v[48:51], v[48:49], off nt
	v_add_co_u32_e32 v52, vcc, s6, v60
	s_mov_b32 s6, 0xc4000
	s_nop 0
	v_addc_co_u32_e32 v53, vcc, 0, v61, vcc
	v_add_co_u32_e32 v56, vcc, s6, v60
	s_mov_b32 s6, 0xe0000
	s_nop 0
	v_addc_co_u32_e32 v57, vcc, 0, v61, vcc
	global_load_dwordx4 v[52:55], v[52:53], off nt
	s_nop 0
	global_load_dwordx4 v[56:59], v[56:57], off nt
	v_add_co_u32_e32 v62, vcc, s6, v60
	s_mov_b32 s6, 0xe4000
	s_nop 0
	v_addc_co_u32_e32 v63, vcc, 0, v61, vcc
	v_add_co_u32_e32 v64, vcc, s6, v60
	s_add_u32 s6, s19, s3
	s_nop 0
	v_addc_co_u32_e32 v65, vcc, 0, v61, vcc
	global_load_dwordx4 v[60:63], v[62:63], off nt
	s_nop 0
	global_load_dwordx4 v[64:67], v[64:65], off nt
	s_waitcnt vmcnt(0)
; #define LAS __attribute__((address_space(3)))
; #define LDS_WAIT() asm volatile("s_waitcnt lgkmcnt(0)" ::: "memory")
; __device__ __forceinline__ unsigned cvt_pk_bf16(float lo, float hi) { unsigned r; asm volatile("v_cvt_pk_bf16_f32 %0, %1, %2" : "=v"(r) : "v"(lo), "v"(hi)); return r; }
;     ...
; #pragma unroll
;     for (int i = 0; i < 8; ++i)
; #pragma unroll
;         for (int e = 0; e < 4; ++e) *(LAS unsigned*)(scr + (4 * r16 + e) * 128 + ((i ^ (r16 & 7)) * 16) + q * 4) = cvt_pk_bf16(v[2 * i][e], v[2 * i + 1][e]);
;     LDS_WAIT(); asm volatile("" ::: "memory");
;     const int c = lane & 7;
; #pragma unroll
;     for (int j = 0; j < 8; ++j) { const int row = (lane >> 3) + 8 * j; const u32x4 o = *(const LAS u32x4*)(scr + row * 128 + ((c ^ ((row >> 2) & 7)) * 16));
;         const int lc = col_off + n0 + row; int dr;
;         if (MODE == 0) dr = lc;
;         else if (MODE == 1) dr = (lc & ~255) + 128 * ((lc >> 5) & 1) + 32 * ((lc >> 6) & 3) + (lc & 31);
;         else if (MODE == 2) dr = 256 * (lc >> 7) + (lc & 127);
;         else dr = 256 * (lc >> 7) + 128 + (lc & 127);
;         *(u32x4*)(WT + (size_t)dr * (ldt ? ldt : K) + k0 + 8 * c) = o; }
;     LDS_WAIT(); asm volatile("" ::: "memory");
	v_cvt_pk_bf16_f32 v4, v4, v8
	v_add_u32_e32 v8, v69, v71
	ds_write_b32 v8, v4
	v_cvt_pk_bf16_f32 v4, v5, v9
	ds_write_b32 v8, v4 offset:128
	v_cvt_pk_bf16_f32 v4, v6, v10
	ds_write_b32 v8, v4 offset:256
	v_cvt_pk_bf16_f32 v4, v7, v11
	ds_write_b32 v8, v4 offset:384
	v_cvt_pk_bf16_f32 v4, v12, v16
	v_add_u32_e32 v5, v73, v71
	ds_write_b32 v5, v4
	v_cvt_pk_bf16_f32 v4, v13, v17
	ds_write_b32 v5, v4 offset:128
	v_cvt_pk_bf16_f32 v4, v14, v18
	ds_write_b32 v5, v4 offset:256
	v_cvt_pk_bf16_f32 v4, v15, v19
	ds_write_b32 v5, v4 offset:384
	v_cvt_pk_bf16_f32 v4, v20, v24
	v_add_u32_e32 v5, v74, v71
	ds_write_b32 v5, v4
	v_cvt_pk_bf16_f32 v4, v21, v25
	ds_write_b32 v5, v4 offset:128
	v_cvt_pk_bf16_f32 v4, v22, v26
	ds_write_b32 v5, v4 offset:256
	v_cvt_pk_bf16_f32 v4, v23, v27
	ds_write_b32 v5, v4 offset:384
	v_cvt_pk_bf16_f32 v4, v28, v32
	v_add_u32_e32 v5, v75, v71
	ds_write_b32 v5, v4
	v_cvt_pk_bf16_f32 v4, v29, v33
	ds_write_b32 v5, v4 offset:128
	v_cvt_pk_bf16_f32 v4, v30, v34
	ds_write_b32 v5, v4 offset:256
	v_cvt_pk_bf16_f32 v4, v31, v35
	ds_write_b32 v5, v4 offset:384
	v_cvt_pk_bf16_f32 v4, v36, v40
	v_add_u32_e32 v5, v76, v71
	ds_write_b32 v5, v4
	v_cvt_pk_bf16_f32 v4, v37, v41
	ds_write_b32 v5, v4 offset:128
	v_cvt_pk_bf16_f32 v4, v38, v42
	ds_write_b32 v5, v4 offset:256
	v_cvt_pk_bf16_f32 v4, v39, v43
	ds_write_b32 v5, v4 offset:384
	v_cvt_pk_bf16_f32 v4, v44, v48
	v_add_u32_e32 v5, v77, v71
	ds_write_b32 v5, v4
	v_cvt_pk_bf16_f32 v4, v45, v49
	ds_write_b32 v5, v4 offset:128
	v_cvt_pk_bf16_f32 v4, v46, v50
	ds_write_b32 v5, v4 offset:256
	v_cvt_pk_bf16_f32 v4, v47, v51
	ds_write_b32 v5, v4 offset:384
	v_cvt_pk_bf16_f32 v4, v52, v56
	v_add_u32_e32 v5, v78, v71
	ds_write_b32 v5, v4
	v_cvt_pk_bf16_f32 v4, v53, v57
	ds_write_b32 v5, v4 offset:128
	v_cvt_pk_bf16_f32 v4, v54, v58
	ds_write_b32 v5, v4 offset:256
	v_cvt_pk_bf16_f32 v4, v55, v59
	ds_write_b32 v5, v4 offset:384
	v_cvt_pk_bf16_f32 v4, v60, v64
	v_add_u32_e32 v5, v79, v71
	ds_write_b32 v5, v4
	v_cvt_pk_bf16_f32 v4, v61, v65
	ds_write_b32 v5, v4 offset:128
	v_cvt_pk_bf16_f32 v4, v62, v66
	ds_write_b32 v5, v4 offset:256
	v_cvt_pk_bf16_f32 v4, v63, v67
	ds_write_b32 v5, v4 offset:384
	s_addc_u32 s7, s20, 0
	v_lshlrev_b32_e32 v4, 1, v70
	v_mov_b32_e32 v5, v2
	s_waitcnt lgkmcnt(0)
	v_lshl_add_u64 v[4:5], s[6:7], 0, v[4:5]
	s_mov_b64 s[6:7], 0x4a00000
	v_lshl_add_u64 v[12:13], v[4:5], 0, s[6:7]
	v_add_u32_e32 v4, v81, v82
	ds_read_b128 v[4:7], v4
	v_or_b32_e32 v8, s2, v80
	v_lshlrev_b32_e32 v8, 10, v8
	v_mov_b32_e32 v9, v2
	v_lshl_add_u64 v[14:15], v[12:13], 0, v[8:9]
	v_add_u32_e32 v8, v84, v85
	ds_read_b128 v[8:11], v8
	s_waitcnt lgkmcnt(1)
	global_store_dwordx4 v[14:15], v[4:7], off
	v_readlane_b32 s46, v250, 56
	v_readlane_b32 s47, v250, 57
	v_or_b32_e32 v4, s2, v83
	v_lshlrev_b32_e32 v4, 10, v4
	v_mov_b32_e32 v5, v2
	v_lshl_add_u64 v[4:5], v[12:13], 0, v[4:5]
	s_waitcnt lgkmcnt(0)
	global_store_dwordx4 v[4:5], v[8:11], off
	v_add_u32_e32 v4, v87, v88
	ds_read_b128 v[4:7], v4
	v_or_b32_e32 v8, s2, v86
	v_lshlrev_b32_e32 v8, 10, v8
	v_mov_b32_e32 v9, v2
	v_lshl_add_u64 v[14:15], v[12:13], 0, v[8:9]
	v_add_u32_e32 v8, v90, v91
	ds_read_b128 v[8:11], v8
	s_waitcnt lgkmcnt(1)
	global_store_dwordx4 v[14:15], v[4:7], off
	v_readlane_b32 s46, v255, 36
	v_readlane_b32 s37, v250, 47
	v_or_b32_e32 v4, s2, v89
	v_lshlrev_b32_e32 v4, 10, v4
	v_mov_b32_e32 v5, v2
	v_lshl_add_u64 v[4:5], v[12:13], 0, v[4:5]
	s_waitcnt lgkmcnt(0)
	global_store_dwordx4 v[4:5], v[8:11], off
	v_add_u32_e32 v4, v93, v82
	ds_read_b128 v[4:7], v4
	v_or_b32_e32 v8, s2, v92
	v_lshlrev_b32_e32 v8, 10, v8
	v_mov_b32_e32 v9, v2
	v_lshl_add_u64 v[14:15], v[12:13], 0, v[8:9]
	v_add_u32_e32 v8, v95, v96
	ds_read_b128 v[8:11], v8
	s_waitcnt lgkmcnt(1)
	global_store_dwordx4 v[14:15], v[4:7], off
	v_readlane_b32 s38, v250, 48
	v_readlane_b32 s39, v250, 49
	v_or_b32_e32 v4, s2, v94
	v_lshlrev_b32_e32 v4, 10, v4
	v_mov_b32_e32 v5, v2
	v_lshl_add_u64 v[4:5], v[12:13], 0, v[4:5]
	s_waitcnt lgkmcnt(0)
	global_store_dwordx4 v[4:5], v[8:11], off
	v_add_u32_e32 v4, v98, v99
	ds_read_b128 v[4:7], v4
	v_or_b32_e32 v8, s2, v97
	v_lshlrev_b32_e32 v8, 10, v8
	v_mov_b32_e32 v9, v2
	v_lshl_add_u64 v[14:15], v[12:13], 0, v[8:9]
	v_add_u32_e32 v8, v101, v102
	ds_read_b128 v[8:11], v8
	s_waitcnt lgkmcnt(1)
	global_store_dwordx4 v[14:15], v[4:7], off
	v_readlane_b32 s40, v250, 50
	v_readlane_b32 s41, v250, 51
	v_or_b32_e32 v4, s2, v100
	v_lshlrev_b32_e32 v4, 10, v4
	v_mov_b32_e32 v5, v2
	v_lshl_add_u64 v[4:5], v[12:13], 0, v[4:5]
	s_waitcnt lgkmcnt(0)
	global_store_dwordx4 v[4:5], v[8:11], off
	s_waitcnt lgkmcnt(0)
	v_readlane_b32 s42, v250, 52
	v_readlane_b32 s43, v250, 53
	v_readlane_b32 s44, v250, 54
	v_readlane_b32 s45, v250, 55
	v_readlane_b32 s48, v250, 58
	v_readlane_b32 s49, v250, 59
	v_readlane_b32 s47, v255, 37

;     const int nblk = N / 64, kb = item / nblk, nb = item % nblk, k0 = 64 * kb, n0 = 64 * nb;
;     const int r16 = lane & 15, q = lane >> 4;
;     const float* src = W + (size_t)(k0 + 2 * q) * N + n0 + 4 * r16;
;     f32x4 v[16];
; #pragma unroll
;     for (int j = 0; j < 16; ++j) v[j] = *(const f32x4*)(src + (size_t)(8 * (j >> 1) + (j & 1)) * N);
;     if (nscale) { const f32x4 ns = *(const f32x4*)(nscale + n0 + 4 * r16);
; #pragma unroll
;         for (int j = 0; j < 16; ++j) v[j] = v[j] * ns; }
;     if (kscale) {
; #pragma unroll
;         for (int i = 0; i < 8; ++i) { const f32x2 g = *(const f32x2*)(kscale + k0 + 8 * i + 2 * q); v[2 * i] = v[2 * i] * g[0]; v[2 * i + 1] = v[2 * i + 1] * g[1]; } }
; __device__ __forceinline__ void weights_pass(const Args& a, LAS unsigned char* scr, int gw, int NGW, int lane, int pass) {
;     ...
;         if (r < I_QM) { transpose_item<1>(a.in[I_WVM] + (size_t)l * DM * MW, DM, MW, (bf16_t*)(ws + WS_WKV) + (size_t)l * 1024 * DM, a.in[I_GMEM] + l * DM, nullptr, 512, scr, r, lane); continue; } r -= I_QM;
.LBB0_1692:
	s_andn2_b64 vcc, exec, s[6:7]
	s_cbranch_vccnz .LBB0_1696
	v_readlane_b32 s36, v250, 46
	s_lshl_b64 s[6:7], s[0:1], 23
	v_readlane_b32 s44, v250, 54
	v_readlane_b32 s45, v250, 55
	s_add_u32 s8, s44, s6
	s_mul_i32 s2, s0, 0xfffaa800
	s_addc_u32 s9, s45, s7
	s_add_i32 s2, s11, s2
	s_addk_i32 s2, 0xe000
	s_and_b32 s2, s2, 0x7ffc0
	v_or_b32_e32 v4, s2, v72
	s_and_b32 s3, s17, 0x1c0
	v_lshlrev_b32_e32 v4, 11, v4
	v_mov_b32_e32 v5, v2
	v_lshl_add_u64 v[4:5], s[8:9], 0, v[4:5]
	s_lshl_b32 s14, s3, 2
	v_lshl_add_u64 v[4:5], v[4:5], 0, s[14:15]
	v_lshlrev_b32_e32 v6, 2, v68
	v_mov_b32_e32 v7, v2
	v_lshl_add_u64 v[4:5], v[4:5], 0, v[6:7]
	s_movk_i32 s8, 0x4000
	v_add_co_u32_e32 v6, vcc, s8, v4
	s_mov_b32 s8, 0x8000
	s_nop 0
	v_addc_co_u32_e32 v7, vcc, 0, v5, vcc
	global_load_dwordx4 v[60:63], v[4:5], off nt
	global_load_dwordx4 v[64:67], v[4:5], off offset:2048 nt
	global_load_dwordx4 v[52:55], v[6:7], off nt
	global_load_dwordx4 v[56:59], v[6:7], off offset:2048 nt
	v_add_co_u32_e32 v6, vcc, s8, v4
	s_mov_b32 s8, 0x10000
	s_nop 0
	v_addc_co_u32_e32 v7, vcc, 0, v5, vcc
	global_load_dwordx4 v[44:47], v[6:7], off nt
	global_load_dwordx4 v[48:51], v[6:7], off offset:2048 nt
	v_add_co_u32_e32 v6, vcc, 0xc000, v4
	v_readlane_b32 s38, v250, 48
	s_nop 0
	v_addc_co_u32_e32 v7, vcc, 0, v5, vcc
	global_load_dwordx4 v[36:39], v[6:7], off nt
	global_load_dwordx4 v[40:43], v[6:7], off offset:2048 nt
	v_add_co_u32_e32 v6, vcc, s8, v4
	s_mov_b32 s8, 0x14000
	s_nop 0
	v_addc_co_u32_e32 v7, vcc, 0, v5, vcc
	global_load_dwordx4 v[28:31], v[6:7], off nt
	global_load_dwordx4 v[32:35], v[6:7], off offset:2048 nt
	v_add_co_u32_e32 v6, vcc, s8, v4
	v_readlane_b32 s8, v253, 9
	s_nop 0
	v_addc_co_u32_e32 v7, vcc, 0, v5, vcc
	global_load_dwordx4 v[20:23], v[6:7], off nt
	global_load_dwordx4 v[24:27], v[6:7], off offset:2048 nt
	v_add_co_u32_e32 v6, vcc, 0x18000, v4
	v_readlane_b32 s9, v253, 10
	s_nop 0
	v_addc_co_u32_e32 v7, vcc, 0, v5, vcc
	v_add_co_u32_e32 v8, vcc, 0x1c000, v4
	global_load_dwordx4 v[12:15], v[6:7], off nt
	global_load_dwordx4 v[16:19], v[6:7], off offset:2048 nt
	v_addc_co_u32_e32 v9, vcc, 0, v5, vcc
	global_load_dwordx4 v[4:7], v[8:9], off nt
	s_nop 0
	global_load_dwordx4 v[8:11], v[8:9], off offset:2048 nt
	v_readlane_b32 s39, v250, 49
	s_andn2_b64 vcc, exec, s[8:9]
	v_readlane_b32 s37, v250, 47
	v_readlane_b32 s40, v250, 50
	v_readlane_b32 s41, v250, 51
	v_readlane_b32 s42, v250, 52
	v_readlane_b32 s43, v250, 53
	v_readlane_b32 s46, v250, 56
	v_readlane_b32 s47, v250, 57
	v_readlane_b32 s48, v250, 58
	v_readlane_b32 s49, v250, 59
	v_readlane_b32 s50, v250, 60
	v_readlane_b32 s51, v250, 61
	s_cbranch_vccnz .LBB0_1695
	s_lshl_b32 s8, s0, 12
	s_ashr_i32 s9, s8, 31
	s_lshl_b64 s[8:9], s[8:9], 2
	s_add_u32 s8, s38, s8
	s_addc_u32 s9, s39, s9
	s_lshl_b32 s14, s2, 2
	s_add_u32 s8, s8, s14
	s_addc_u32 s9, s9, 0
	v_lshlrev_b32_e32 v103, 2, v72
	global_load_dwordx2 v[104:105], v103, s[8:9]
	s_waitcnt vmcnt(0)
	v_pk_mul_f32 v[62:63], v[62:63], v[104:105] op_sel_hi:[1,0]
	v_pk_mul_f32 v[60:61], v[60:61], v[104:105] op_sel_hi:[1,0]
	v_pk_mul_f32 v[66:67], v[66:67], v[104:105] op_sel:[0,1]
	v_pk_mul_f32 v[64:65], v[64:65], v[104:105] op_sel:[0,1]
	global_load_dwordx2 v[104:105], v103, s[8:9] offset:32
	s_waitcnt vmcnt(0)
	v_pk_mul_f32 v[54:55], v[54:55], v[104:105] op_sel_hi:[1,0]
	v_pk_mul_f32 v[52:53], v[52:53], v[104:105] op_sel_hi:[1,0]
	v_pk_mul_f32 v[58:59], v[58:59], v[104:105] op_sel:[0,1]
	v_pk_mul_f32 v[56:57], v[56:57], v[104:105] op_sel:[0,1]
	global_load_dwordx2 v[104:105], v103, s[8:9] offset:64
	s_waitcnt vmcnt(0)
	v_pk_mul_f32 v[46:47], v[46:47], v[104:105] op_sel_hi:[1,0]
	v_pk_mul_f32 v[44:45], v[44:45], v[104:105] op_sel_hi:[1,0]
	v_pk_mul_f32 v[50:51], v[50:51], v[104:105] op_sel:[0,1]
	v_pk_mul_f32 v[48:49], v[48:49], v[104:105] op_sel:[0,1]
	global_load_dwordx2 v[104:105], v103, s[8:9] offset:96
	s_waitcnt vmcnt(0)
	v_pk_mul_f32 v[38:39], v[38:39], v[104:105] op_sel_hi:[1,0]
	v_pk_mul_f32 v[36:37], v[36:37], v[104:105] op_sel_hi:[1,0]
	v_pk_mul_f32 v[42:43], v[42:43], v[104:105] op_sel:[0,1]
	v_pk_mul_f32 v[40:41], v[40:41], v[104:105] op_sel:[0,1]
	global_load_dwordx2 v[104:105], v103, s[8:9] offset:128
	s_waitcnt vmcnt(0)
	v_pk_mul_f32 v[30:31], v[30:31], v[104:105] op_sel_hi:[1,0]
	v_pk_mul_f32 v[28:29], v[28:29], v[104:105] op_sel_hi:[1,0]
	v_pk_mul_f32 v[34:35], v[34:35], v[104:105] op_sel:[0,1]
	v_pk_mul_f32 v[32:33], v[32:33], v[104:105] op_sel:[0,1]
	global_load_dwordx2 v[104:105], v103, s[8:9] offset:160
	s_waitcnt vmcnt(0)
	v_pk_mul_f32 v[22:23], v[22:23], v[104:105] op_sel_hi:[1,0]
	v_pk_mul_f32 v[20:21], v[20:21], v[104:105] op_sel_hi:[1,0]
	v_pk_mul_f32 v[26:27], v[26:27], v[104:105] op_sel:[0,1]
	v_pk_mul_f32 v[24:25], v[24:25], v[104:105] op_sel:[0,1]
	global_load_dwordx2 v[104:105], v103, s[8:9] offset:192
	s_waitcnt vmcnt(0)
	v_pk_mul_f32 v[14:15], v[14:15], v[104:105] op_sel_hi:[1,0]
	v_pk_mul_f32 v[12:13], v[12:13], v[104:105] op_sel_hi:[1,0]
	v_pk_mul_f32 v[18:19], v[18:19], v[104:105] op_sel:[0,1]
	v_pk_mul_f32 v[16:17], v[16:17], v[104:105] op_sel:[0,1]
	global_load_dwordx2 v[104:105], v103, s[8:9] offset:224
	s_waitcnt vmcnt(0)
	v_pk_mul_f32 v[6:7], v[6:7], v[104:105] op_sel_hi:[1,0]
	v_pk_mul_f32 v[4:5], v[4:5], v[104:105] op_sel_hi:[1,0]
	v_pk_mul_f32 v[10:11], v[10:11], v[104:105] op_sel:[0,1]
	v_pk_mul_f32 v[8:9], v[8:9], v[104:105] op_sel:[0,1]

;     const int nblk = N / 64, kb = item / nblk, nb = item % nblk, k0 = 64 * kb, n0 = 64 * nb;
;     const int r16 = lane & 15, q = lane >> 4;
;     const float* src = W + (size_t)(k0 + 2 * q) * N + n0 + 4 * r16;
;     f32x4 v[16];
; #pragma unroll
;     for (int j = 0; j < 16; ++j) v[j] = *(const f32x4*)(src + (size_t)(8 * (j >> 1) + (j & 1)) * N);
;     if (nscale) { const f32x4 ns = *(const f32x4*)(nscale + n0 + 4 * r16);
; #pragma unroll
;         for (int j = 0; j < 16; ++j) v[j] = v[j] * ns; }
;     if (kscale) {
; #pragma unroll
;         for (int i = 0; i < 8; ++i) { const f32x2 g = *(const f32x2*)(kscale + k0 + 8 * i + 2 * q); v[2 * i] = v[2 * i] * g[0]; v[2 * i + 1] = v[2 * i + 1] * g[1]; } }
; __device__ __forceinline__ void weights_pass(const Args& a, LAS unsigned char* scr, int gw, int NGW, int lane, int pass) {
;     ...
;         if (r < I_QM) { transpose_item<1>(a.in[I_WKM] + (size_t)l * DM * MW, DM, MW, (bf16_t*)(ws + WS_WKV) + (size_t)l * 1024 * DM, a.in[I_GMEM] + l * DM, nullptr, 0, scr, r, lane); continue; } r -= I_QM;
.LBB0_1697:
	s_andn2_b64 vcc, exec, s[6:7]
	s_cbranch_vccnz .LBB0_1701
	v_readlane_b32 s36, v250, 46
	s_lshl_b64 s[6:7], s[0:1], 23
	v_readlane_b32 s42, v250, 52
	v_readlane_b32 s43, v250, 53
	s_add_u32 s8, s42, s6
	s_mul_i32 s2, s0, 0xfffaa800
	s_addc_u32 s9, s43, s7
	s_add_i32 s2, s11, s2
	s_addk_i32 s2, 0xf000
	s_and_b32 s3, s2, 0x7ffc0
	s_mul_i32 s2, s0, 0xffd54000
	s_add_i32 s2, s17, s2
	v_or_b32_e32 v4, s3, v72
	s_and_b32 s14, s2, 0x1c0
	v_lshlrev_b32_e32 v4, 11, v4
	v_mov_b32_e32 v5, v2
	v_lshl_add_u64 v[4:5], s[8:9], 0, v[4:5]
	s_lshl_b32 s14, s14, 2
	v_lshl_add_u64 v[4:5], v[4:5], 0, s[14:15]
	v_lshlrev_b32_e32 v6, 2, v68
	v_mov_b32_e32 v7, v2
	v_lshl_add_u64 v[4:5], v[4:5], 0, v[6:7]
	s_movk_i32 s8, 0x4000
	v_add_co_u32_e32 v6, vcc, s8, v4
	s_mov_b32 s8, 0x8000
	s_nop 0
	v_addc_co_u32_e32 v7, vcc, 0, v5, vcc
	global_load_dwordx4 v[60:63], v[4:5], off nt
	global_load_dwordx4 v[64:67], v[4:5], off offset:2048 nt
	global_load_dwordx4 v[52:55], v[6:7], off nt
	global_load_dwordx4 v[56:59], v[6:7], off offset:2048 nt
	v_add_co_u32_e32 v6, vcc, s8, v4
	s_mov_b32 s8, 0x10000
	s_nop 0
	v_addc_co_u32_e32 v7, vcc, 0, v5, vcc
	global_load_dwordx4 v[44:47], v[6:7], off nt
	global_load_dwordx4 v[48:51], v[6:7], off offset:2048 nt
	v_add_co_u32_e32 v6, vcc, 0xc000, v4
	v_readlane_b32 s38, v250, 48
	s_nop 0
	v_addc_co_u32_e32 v7, vcc, 0, v5, vcc
	global_load_dwordx4 v[36:39], v[6:7], off nt
	global_load_dwordx4 v[40:43], v[6:7], off offset:2048 nt
	v_add_co_u32_e32 v6, vcc, s8, v4
	s_mov_b32 s8, 0x14000
	s_nop 0
	v_addc_co_u32_e32 v7, vcc, 0, v5, vcc
	global_load_dwordx4 v[28:31], v[6:7], off nt
	global_load_dwordx4 v[32:35], v[6:7], off offset:2048 nt
	v_add_co_u32_e32 v6, vcc, s8, v4
	v_readlane_b32 s8, v253, 9
	s_nop 0
	v_addc_co_u32_e32 v7, vcc, 0, v5, vcc
	global_load_dwordx4 v[20:23], v[6:7], off nt
	global_load_dwordx4 v[24:27], v[6:7], off offset:2048 nt
	v_add_co_u32_e32 v6, vcc, 0x18000, v4
	v_readlane_b32 s9, v253, 10
	s_nop 0
	v_addc_co_u32_e32 v7, vcc, 0, v5, vcc
	v_add_co_u32_e32 v8, vcc, 0x1c000, v4
	global_load_dwordx4 v[12:15], v[6:7], off nt
	global_load_dwordx4 v[16:19], v[6:7], off offset:2048 nt
	v_addc_co_u32_e32 v9, vcc, 0, v5, vcc
	global_load_dwordx4 v[4:7], v[8:9], off nt
	s_nop 0
	global_load_dwordx4 v[8:11], v[8:9], off offset:2048 nt
	v_readlane_b32 s39, v250, 49
	s_andn2_b64 vcc, exec, s[8:9]
	v_readlane_b32 s37, v250, 47
	v_readlane_b32 s40, v250, 50
	v_readlane_b32 s41, v250, 51
	v_readlane_b32 s44, v250, 54
	v_readlane_b32 s45, v250, 55
	v_readlane_b32 s46, v250, 56
	v_readlane_b32 s47, v250, 57
	v_readlane_b32 s48, v250, 58
	v_readlane_b32 s49, v250, 59
	v_readlane_b32 s50, v250, 60
	v_readlane_b32 s51, v250, 61
	s_cbranch_vccnz .LBB0_1700
	s_lshl_b32 s8, s0, 12
	s_ashr_i32 s9, s8, 31
	s_lshl_b64 s[8:9], s[8:9], 2
	s_add_u32 s8, s38, s8
	s_addc_u32 s9, s39, s9
	s_lshl_b32 s14, s3, 2
	s_add_u32 s8, s8, s14
	s_addc_u32 s9, s9, 0
	v_lshlrev_b32_e32 v103, 2, v72
	global_load_dwordx2 v[104:105], v103, s[8:9]
	s_waitcnt vmcnt(0)
	v_pk_mul_f32 v[62:63], v[62:63], v[104:105] op_sel_hi:[1,0]
	v_pk_mul_f32 v[60:61], v[60:61], v[104:105] op_sel_hi:[1,0]
	v_pk_mul_f32 v[66:67], v[66:67], v[104:105] op_sel:[0,1]
	v_pk_mul_f32 v[64:65], v[64:65], v[104:105] op_sel:[0,1]
	global_load_dwordx2 v[104:105], v103, s[8:9] offset:32
	s_waitcnt vmcnt(0)
	v_pk_mul_f32 v[54:55], v[54:55], v[104:105] op_sel_hi:[1,0]
	v_pk_mul_f32 v[52:53], v[52:53], v[104:105] op_sel_hi:[1,0]
	v_pk_mul_f32 v[58:59], v[58:59], v[104:105] op_sel:[0,1]
	v_pk_mul_f32 v[56:57], v[56:57], v[104:105] op_sel:[0,1]
	global_load_dwordx2 v[104:105], v103, s[8:9] offset:64
	s_waitcnt vmcnt(0)
	v_pk_mul_f32 v[46:47], v[46:47], v[104:105] op_sel_hi:[1,0]
	v_pk_mul_f32 v[44:45], v[44:45], v[104:105] op_sel_hi:[1,0]
	v_pk_mul_f32 v[50:51], v[50:51], v[104:105] op_sel:[0,1]
	v_pk_mul_f32 v[48:49], v[48:49], v[104:105] op_sel:[0,1]
	global_load_dwordx2 v[104:105], v103, s[8:9] offset:96
	s_waitcnt vmcnt(0)
	v_pk_mul_f32 v[38:39], v[38:39], v[104:105] op_sel_hi:[1,0]
	v_pk_mul_f32 v[36:37], v[36:37], v[104:105] op_sel_hi:[1,0]
	v_pk_mul_f32 v[42:43], v[42:43], v[104:105] op_sel:[0,1]
	v_pk_mul_f32 v[40:41], v[40:41], v[104:105] op_sel:[0,1]
	global_load_dwordx2 v[104:105], v103, s[8:9] offset:128
	s_waitcnt vmcnt(0)
	v_pk_mul_f32 v[30:31], v[30:31], v[104:105] op_sel_hi:[1,0]
	v_pk_mul_f32 v[28:29], v[28:29], v[104:105] op_sel_hi:[1,0]
	v_pk_mul_f32 v[34:35], v[34:35], v[104:105] op_sel:[0,1]
	v_pk_mul_f32 v[32:33], v[32:33], v[104:105] op_sel:[0,1]
	global_load_dwordx2 v[104:105], v103, s[8:9] offset:160
	s_waitcnt vmcnt(0)
	v_pk_mul_f32 v[22:23], v[22:23], v[104:105] op_sel_hi:[1,0]
	v_pk_mul_f32 v[20:21], v[20:21], v[104:105] op_sel_hi:[1,0]
	v_pk_mul_f32 v[26:27], v[26:27], v[104:105] op_sel:[0,1]
	v_pk_mul_f32 v[24:25], v[24:25], v[104:105] op_sel:[0,1]
	global_load_dwordx2 v[104:105], v103, s[8:9] offset:192
	s_waitcnt vmcnt(0)
	v_pk_mul_f32 v[14:15], v[14:15], v[104:105] op_sel_hi:[1,0]
	v_pk_mul_f32 v[12:13], v[12:13], v[104:105] op_sel_hi:[1,0]
	v_pk_mul_f32 v[18:19], v[18:19], v[104:105] op_sel:[0,1]
	v_pk_mul_f32 v[16:17], v[16:17], v[104:105] op_sel:[0,1]
	global_load_dwordx2 v[104:105], v103, s[8:9] offset:224
	s_waitcnt vmcnt(0)
	v_pk_mul_f32 v[6:7], v[6:7], v[104:105] op_sel_hi:[1,0]
	v_pk_mul_f32 v[4:5], v[4:5], v[104:105] op_sel_hi:[1,0]
	v_pk_mul_f32 v[10:11], v[10:11], v[104:105] op_sel:[0,1]
	v_pk_mul_f32 v[8:9], v[8:9], v[104:105] op_sel:[0,1]

;     const int nblk = N / 64, kb = item / nblk, nb = item % nblk, k0 = 64 * kb, n0 = 64 * nb;
;     const int r16 = lane & 15, q = lane >> 4;
;     const float* src = W + (size_t)(k0 + 2 * q) * N + n0 + 4 * r16;
;     f32x4 v[16];
; #pragma unroll
;     for (int j = 0; j < 16; ++j) v[j] = *(const f32x4*)(src + (size_t)(8 * (j >> 1) + (j & 1)) * N);
;     if (nscale) { const f32x4 ns = *(const f32x4*)(nscale + n0 + 4 * r16);
; #pragma unroll
;         for (int j = 0; j < 16; ++j) v[j] = v[j] * ns; }
;     if (kscale) {
; #pragma unroll
;         for (int i = 0; i < 8; ++i) { const f32x2 g = *(const f32x2*)(kscale + k0 + 8 * i + 2 * q); v[2 * i] = v[2 * i] * g[0]; v[2 * i + 1] = v[2 * i + 1] * g[1]; } }
; __device__ __forceinline__ void weights_pass(const Args& a, LAS unsigned char* scr, int gw, int NGW, int lane, int pass) {
;     ...
;         if (r < I_QM) { transpose_item<0>(a.in[I_WQM] + (size_t)l * DM * MW, DM, MW, (bf16_t*)(wl + WL_Q), a.in[I_GCROSS] + l * DM, nullptr, 0, scr, r, lane); continue; } r -= I_QM;
.LBB0_1702:
	s_andn2_b64 vcc, exec, s[6:7]
	s_cbranch_vccnz .LBB0_1706
	v_readlane_b32 s36, v250, 46
	s_lshl_b64 s[2:3], s[0:1], 23
	v_readlane_b32 s40, v250, 50
	v_readlane_b32 s41, v250, 51
	s_add_u32 s6, s40, s2
	s_mul_i32 s2, s0, 0xfffaa800
	s_addc_u32 s7, s41, s3
	s_add_i32 s2, s11, s2
	s_and_b32 s2, s2, 0x7ffc0
	s_lshl_b32 s3, s21, 6
	v_or_b32_e32 v4, s2, v72
	s_and_b32 s3, s3, 0x1c0
	v_lshlrev_b32_e32 v4, 11, v4
	v_mov_b32_e32 v5, v2
	v_lshl_add_u64 v[4:5], s[6:7], 0, v[4:5]
	s_lshl_b32 s14, s3, 2
	v_lshl_add_u64 v[4:5], v[4:5], 0, s[14:15]
	v_lshlrev_b32_e32 v6, 2, v68
	v_mov_b32_e32 v7, v2
	v_lshl_add_u64 v[4:5], v[4:5], 0, v[6:7]
	s_movk_i32 s6, 0x4000
	v_add_co_u32_e32 v6, vcc, s6, v4
	s_mov_b32 s6, 0x8000
	s_nop 0
	v_addc_co_u32_e32 v7, vcc, 0, v5, vcc
	global_load_dwordx4 v[60:63], v[4:5], off nt
	global_load_dwordx4 v[64:67], v[4:5], off offset:2048 nt
	global_load_dwordx4 v[52:55], v[6:7], off nt
	global_load_dwordx4 v[56:59], v[6:7], off offset:2048 nt
	v_add_co_u32_e32 v6, vcc, s6, v4
	s_mov_b32 s6, 0x10000
	s_nop 0
	v_addc_co_u32_e32 v7, vcc, 0, v5, vcc
	global_load_dwordx4 v[44:47], v[6:7], off nt
	global_load_dwordx4 v[48:51], v[6:7], off offset:2048 nt
	v_add_co_u32_e32 v6, vcc, 0xc000, v4
	v_readlane_b32 s37, v250, 47
	s_nop 0
	v_addc_co_u32_e32 v7, vcc, 0, v5, vcc
	global_load_dwordx4 v[36:39], v[6:7], off nt
	global_load_dwordx4 v[40:43], v[6:7], off offset:2048 nt
	v_add_co_u32_e32 v6, vcc, s6, v4
	s_mov_b32 s6, 0x14000
	s_nop 0
	v_addc_co_u32_e32 v7, vcc, 0, v5, vcc
	global_load_dwordx4 v[28:31], v[6:7], off nt
	global_load_dwordx4 v[32:35], v[6:7], off offset:2048 nt
	v_add_co_u32_e32 v6, vcc, s6, v4
	v_readlane_b32 s6, v253, 11
	s_nop 0
	v_addc_co_u32_e32 v7, vcc, 0, v5, vcc
	global_load_dwordx4 v[20:23], v[6:7], off nt
	global_load_dwordx4 v[24:27], v[6:7], off offset:2048 nt
	v_add_co_u32_e32 v6, vcc, 0x18000, v4
	v_readlane_b32 s7, v253, 12
	s_nop 0
	v_addc_co_u32_e32 v7, vcc, 0, v5, vcc
	v_add_co_u32_e32 v8, vcc, 0x1c000, v4
	global_load_dwordx4 v[12:15], v[6:7], off nt
	global_load_dwordx4 v[16:19], v[6:7], off offset:2048 nt
	v_addc_co_u32_e32 v9, vcc, 0, v5, vcc
	global_load_dwordx4 v[4:7], v[8:9], off nt
	s_nop 0
	global_load_dwordx4 v[8:11], v[8:9], off offset:2048 nt
	s_andn2_b64 vcc, exec, s[6:7]
	v_readlane_b32 s38, v250, 48
	v_readlane_b32 s39, v250, 49
	v_readlane_b32 s42, v250, 52
	v_readlane_b32 s43, v250, 53
	v_readlane_b32 s44, v250, 54
	v_readlane_b32 s45, v250, 55
	v_readlane_b32 s46, v250, 56
	v_readlane_b32 s47, v250, 57
	v_readlane_b32 s48, v250, 58
	v_readlane_b32 s49, v250, 59
	v_readlane_b32 s50, v250, 60
	v_readlane_b32 s51, v250, 61
	s_cbranch_vccnz .LBB0_1705
	s_lshl_b32 s6, s0, 12
	s_ashr_i32 s7, s6, 31
	s_lshl_b64 s[6:7], s[6:7], 2
	s_add_u32 s6, s36, s6
	s_addc_u32 s7, s37, s7
	s_lshl_b32 s8, s2, 2
	s_add_u32 s6, s6, s8
	s_addc_u32 s7, s7, 0
	v_lshlrev_b32_e32 v103, 2, v72
	global_load_dwordx2 v[104:105], v103, s[6:7]
	s_waitcnt vmcnt(0)
	v_pk_mul_f32 v[62:63], v[62:63], v[104:105] op_sel_hi:[1,0]
	v_pk_mul_f32 v[60:61], v[60:61], v[104:105] op_sel_hi:[1,0]
	v_pk_mul_f32 v[66:67], v[66:67], v[104:105] op_sel:[0,1]
	v_pk_mul_f32 v[64:65], v[64:65], v[104:105] op_sel:[0,1]
	global_load_dwordx2 v[104:105], v103, s[6:7] offset:32
	s_waitcnt vmcnt(0)
	v_pk_mul_f32 v[54:55], v[54:55], v[104:105] op_sel_hi:[1,0]
	v_pk_mul_f32 v[52:53], v[52:53], v[104:105] op_sel_hi:[1,0]
	v_pk_mul_f32 v[58:59], v[58:59], v[104:105] op_sel:[0,1]
	v_pk_mul_f32 v[56:57], v[56:57], v[104:105] op_sel:[0,1]
	global_load_dwordx2 v[104:105], v103, s[6:7] offset:64
	s_waitcnt vmcnt(0)
	v_pk_mul_f32 v[46:47], v[46:47], v[104:105] op_sel_hi:[1,0]
	v_pk_mul_f32 v[44:45], v[44:45], v[104:105] op_sel_hi:[1,0]
	v_pk_mul_f32 v[50:51], v[50:51], v[104:105] op_sel:[0,1]
	v_pk_mul_f32 v[48:49], v[48:49], v[104:105] op_sel:[0,1]
	global_load_dwordx2 v[104:105], v103, s[6:7] offset:96
	s_waitcnt vmcnt(0)
	v_pk_mul_f32 v[38:39], v[38:39], v[104:105] op_sel_hi:[1,0]
	v_pk_mul_f32 v[36:37], v[36:37], v[104:105] op_sel_hi:[1,0]
	v_pk_mul_f32 v[42:43], v[42:43], v[104:105] op_sel:[0,1]
	v_pk_mul_f32 v[40:41], v[40:41], v[104:105] op_sel:[0,1]
	global_load_dwordx2 v[104:105], v103, s[6:7] offset:128
	s_waitcnt vmcnt(0)
	v_pk_mul_f32 v[30:31], v[30:31], v[104:105] op_sel_hi:[1,0]
	v_pk_mul_f32 v[28:29], v[28:29], v[104:105] op_sel_hi:[1,0]
	v_pk_mul_f32 v[34:35], v[34:35], v[104:105] op_sel:[0,1]
	v_pk_mul_f32 v[32:33], v[32:33], v[104:105] op_sel:[0,1]
	global_load_dwordx2 v[104:105], v103, s[6:7] offset:160
	s_waitcnt vmcnt(0)
	v_pk_mul_f32 v[22:23], v[22:23], v[104:105] op_sel_hi:[1,0]
	v_pk_mul_f32 v[20:21], v[20:21], v[104:105] op_sel_hi:[1,0]
	v_pk_mul_f32 v[26:27], v[26:27], v[104:105] op_sel:[0,1]
	v_pk_mul_f32 v[24:25], v[24:25], v[104:105] op_sel:[0,1]
	global_load_dwordx2 v[104:105], v103, s[6:7] offset:192
	s_waitcnt vmcnt(0)
	v_pk_mul_f32 v[14:15], v[14:15], v[104:105] op_sel_hi:[1,0]
	v_pk_mul_f32 v[12:13], v[12:13], v[104:105] op_sel_hi:[1,0]
	v_pk_mul_f32 v[18:19], v[18:19], v[104:105] op_sel:[0,1]
	v_pk_mul_f32 v[16:17], v[16:17], v[104:105] op_sel:[0,1]
	global_load_dwordx2 v[104:105], v103, s[6:7] offset:224
	s_waitcnt vmcnt(0)
	v_pk_mul_f32 v[6:7], v[6:7], v[104:105] op_sel_hi:[1,0]
	v_pk_mul_f32 v[4:5], v[4:5], v[104:105] op_sel_hi:[1,0]
	v_pk_mul_f32 v[10:11], v[10:11], v[104:105] op_sel:[0,1]
	v_pk_mul_f32 v[8:9], v[8:9], v[104:105] op_sel:[0,1]

;     const int nblk = N / 64, kb = item / nblk, nb = item % nblk, k0 = 64 * kb, n0 = 64 * nb;
;     const int r16 = lane & 15, q = lane >> 4;
;     const float* src = W + (size_t)(k0 + 2 * q) * N + n0 + 4 * r16;
;     f32x4 v[16];
; #pragma unroll
;     for (int j = 0; j < 16; ++j) v[j] = *(const f32x4*)(src + (size_t)(8 * (j >> 1) + (j & 1)) * N);
; __device__ __forceinline__ void weights_pass(const Args& a, LAS unsigned char* scr, int gw, int NGW, int lane, int pass) {
;     ...
;         if (r < I_OUT / 2) { transpose_item<0>(a.in[I_WOUT] + (size_t)l * DM * DM + (size_t)2048 * DM, 2048, DM, (bf16_t*)(ws + WS_WLOW) + (size_t)l * DM * 2048, nullptr, nullptr, 0, scr, r, lane); continue; } r -= I_OUT / 2;
.LBB0_1707:
	s_andn2_b64 vcc, exec, s[6:7]
	s_cbranch_vccnz .LBB0_1709
	s_lshl_b64 s[2:3], s[0:1], 26
	s_add_u32 s8, s74, s2
	s_addc_u32 s9, s75, s3
	s_lshl_b64 s[6:7], s[0:1], 24
	v_readlane_b32 s2, v252, 53
	s_add_u32 s3, s2, s6
	v_readlane_b32 s2, v252, 54
	s_addc_u32 s6, s2, s7
	s_and_b32 s7, s23, 0xffc0
	s_lshl_b32 s2, s21, 6
	v_lshlrev_b32_e32 v4, 2, v3
	s_and_b32 s2, s2, 0xfc0
	v_lshl_or_b32 v4, s7, 14, v4
	v_mov_b32_e32 v5, v2
	v_lshl_add_u64 v[4:5], s[8:9], 0, v[4:5]
	s_lshl_b32 s14, s2, 2
	v_lshl_add_u64 v[4:5], v[4:5], 0, s[14:15]
	v_lshlrev_b32_e32 v6, 2, v68
	v_mov_b32_e32 v7, v2
	v_lshl_add_u64 v[60:61], v[4:5], 0, v[6:7]
	s_brev_b32 s8, 64
	v_add_co_u32_e32 v4, vcc, s8, v60
	s_mov_b32 s8, 0x2004000
	s_nop 0
	v_addc_co_u32_e32 v5, vcc, 0, v61, vcc
	v_add_co_u32_e32 v8, vcc, s8, v60
	s_mov_b32 s8, 0x2020000
	s_nop 0
	v_addc_co_u32_e32 v9, vcc, 0, v61, vcc
	global_load_dwordx4 v[4:7], v[4:5], off nt
	s_nop 0
	global_load_dwordx4 v[8:11], v[8:9], off nt
	v_add_co_u32_e32 v12, vcc, s8, v60
	s_mov_b32 s8, 0x2024000
	s_nop 0
	v_addc_co_u32_e32 v13, vcc, 0, v61, vcc
	v_add_co_u32_e32 v16, vcc, s8, v60
	s_mov_b32 s8, 0x2040000
	s_nop 0
	v_addc_co_u32_e32 v17, vcc, 0, v61, vcc
	global_load_dwordx4 v[12:15], v[12:13], off nt
	s_nop 0
	global_load_dwordx4 v[16:19], v[16:17], off nt
	v_add_co_u32_e32 v20, vcc, s8, v60
	s_mov_b32 s8, 0x2044000
	s_nop 0
	v_addc_co_u32_e32 v21, vcc, 0, v61, vcc
	v_add_co_u32_e32 v24, vcc, s8, v60
	s_mov_b32 s8, 0x2060000
	s_nop 0
	v_addc_co_u32_e32 v25, vcc, 0, v61, vcc
	global_load_dwordx4 v[20:23], v[20:21], off nt
	s_nop 0
	global_load_dwordx4 v[24:27], v[24:25], off nt
	v_add_co_u32_e32 v28, vcc, s8, v60
	s_mov_b32 s8, 0x2064000
	s_nop 0
	v_addc_co_u32_e32 v29, vcc, 0, v61, vcc
	v_add_co_u32_e32 v32, vcc, s8, v60
	s_mov_b32 s8, 0x2080000
	s_nop 0
	v_addc_co_u32_e32 v33, vcc, 0, v61, vcc
	global_load_dwordx4 v[28:31], v[28:29], off nt
	s_nop 0
	global_load_dwordx4 v[32:35], v[32:33], off nt
	v_add_co_u32_e32 v36, vcc, s8, v60
	s_mov_b32 s8, 0x2084000
	s_nop 0
	v_addc_co_u32_e32 v37, vcc, 0, v61, vcc
	v_add_co_u32_e32 v40, vcc, s8, v60
	s_mov_b32 s8, 0x20a0000
	s_nop 0
	v_addc_co_u32_e32 v41, vcc, 0, v61, vcc
	global_load_dwordx4 v[36:39], v[36:37], off nt
	s_nop 0
	global_load_dwordx4 v[40:43], v[40:41], off nt
	v_add_co_u32_e32 v44, vcc, s8, v60
	s_mov_b32 s8, 0x20a4000
	s_nop 0
	v_addc_co_u32_e32 v45, vcc, 0, v61, vcc
	v_add_co_u32_e32 v48, vcc, s8, v60
	s_mov_b32 s8, 0x20c0000
	s_nop 0
	v_addc_co_u32_e32 v49, vcc, 0, v61, vcc
	global_load_dwordx4 v[44:47], v[44:45], off nt
	s_nop 0
	global_load_dwordx4 v[48:51], v[48:49], off nt
	v_add_co_u32_e32 v52, vcc, s8, v60
	s_mov_b32 s8, 0x20c4000
	s_nop 0
	v_addc_co_u32_e32 v53, vcc, 0, v61, vcc
	v_add_co_u32_e32 v56, vcc, s8, v60
	s_mov_b32 s8, 0x20e0000
	s_nop 0
	v_addc_co_u32_e32 v57, vcc, 0, v61, vcc
	global_load_dwordx4 v[52:55], v[52:53], off nt
	s_nop 0
	global_load_dwordx4 v[56:59], v[56:57], off nt
	v_add_co_u32_e32 v62, vcc, s8, v60
	s_mov_b32 s8, 0x20e4000
	s_nop 0
	v_addc_co_u32_e32 v63, vcc, 0, v61, vcc
	v_add_co_u32_e32 v64, vcc, s8, v60
	s_lshl_b32 s7, s7, 1
	s_nop 0
	v_addc_co_u32_e32 v65, vcc, 0, v61, vcc
	global_load_dwordx4 v[60:63], v[62:63], off nt
	s_nop 0
	global_load_dwordx4 v[64:67], v[64:65], off nt
	s_waitcnt vmcnt(0)
; #define LAS __attribute__((address_space(3)))
; #define LDS_WAIT() asm volatile("s_waitcnt lgkmcnt(0)" ::: "memory")
; __device__ __forceinline__ unsigned cvt_pk_bf16(float lo, float hi) { unsigned r; asm volatile("v_cvt_pk_bf16_f32 %0, %1, %2" : "=v"(r) : "v"(lo), "v"(hi)); return r; }
;     ...
; #pragma unroll
;     for (int i = 0; i < 8; ++i)
; #pragma unroll
;         for (int e = 0; e < 4; ++e) *(LAS unsigned*)(scr + (4 * r16 + e) * 128 + ((i ^ (r16 & 7)) * 16) + q * 4) = cvt_pk_bf16(v[2 * i][e], v[2 * i + 1][e]);
;     LDS_WAIT(); asm volatile("" ::: "memory");
;     const int c = lane & 7;
; #pragma unroll
;     for (int j = 0; j < 8; ++j) { const int row = (lane >> 3) + 8 * j; const u32x4 o = *(const LAS u32x4*)(scr + row * 128 + ((c ^ ((row >> 2) & 7)) * 16));
;         const int lc = col_off + n0 + row; int dr;
;         if (MODE == 0) dr = lc;
;         else if (MODE == 1) dr = (lc & ~255) + 128 * ((lc >> 5) & 1) + 32 * ((lc >> 6) & 3) + (lc & 31);
;         else if (MODE == 2) dr = 256 * (lc >> 7) + (lc & 127);
;         else dr = 256 * (lc >> 7) + 128 + (lc & 127);
;         *(u32x4*)(WT + (size_t)dr * (ldt ? ldt : K) + k0 + 8 * c) = o; }
;     LDS_WAIT(); asm volatile("" ::: "memory");
	v_cvt_pk_bf16_f32 v4, v4, v8
	v_add_u32_e32 v8, v69, v71
	ds_write_b32 v8, v4
	v_cvt_pk_bf16_f32 v4, v5, v9
	ds_write_b32 v8, v4 offset:128
	v_cvt_pk_bf16_f32 v4, v6, v10
	ds_write_b32 v8, v4 offset:256
	v_cvt_pk_bf16_f32 v4, v7, v11
	ds_write_b32 v8, v4 offset:384
	v_cvt_pk_bf16_f32 v4, v12, v16
	v_add_u32_e32 v5, v73, v71
	ds_write_b32 v5, v4
	v_cvt_pk_bf16_f32 v4, v13, v17
	ds_write_b32 v5, v4 offset:128
	v_cvt_pk_bf16_f32 v4, v14, v18
	ds_write_b32 v5, v4 offset:256
	v_cvt_pk_bf16_f32 v4, v15, v19
	ds_write_b32 v5, v4 offset:384
	v_cvt_pk_bf16_f32 v4, v20, v24
	v_add_u32_e32 v5, v74, v71
	ds_write_b32 v5, v4
	v_cvt_pk_bf16_f32 v4, v21, v25
	ds_write_b32 v5, v4 offset:128
	v_cvt_pk_bf16_f32 v4, v22, v26
	ds_write_b32 v5, v4 offset:256
	v_cvt_pk_bf16_f32 v4, v23, v27
	ds_write_b32 v5, v4 offset:384
	v_cvt_pk_bf16_f32 v4, v28, v32
	v_add_u32_e32 v5, v75, v71
	ds_write_b32 v5, v4
	v_cvt_pk_bf16_f32 v4, v29, v33
	ds_write_b32 v5, v4 offset:128
	v_cvt_pk_bf16_f32 v4, v30, v34
	ds_write_b32 v5, v4 offset:256
	v_cvt_pk_bf16_f32 v4, v31, v35
	ds_write_b32 v5, v4 offset:384
	v_cvt_pk_bf16_f32 v4, v36, v40
	v_add_u32_e32 v5, v76, v71
	ds_write_b32 v5, v4
	v_cvt_pk_bf16_f32 v4, v37, v41
	ds_write_b32 v5, v4 offset:128
	v_cvt_pk_bf16_f32 v4, v38, v42
	ds_write_b32 v5, v4 offset:256
	v_cvt_pk_bf16_f32 v4, v39, v43
	ds_write_b32 v5, v4 offset:384
	v_cvt_pk_bf16_f32 v4, v44, v48
	v_add_u32_e32 v5, v77, v71
	ds_write_b32 v5, v4
	v_cvt_pk_bf16_f32 v4, v45, v49
	ds_write_b32 v5, v4 offset:128
	v_cvt_pk_bf16_f32 v4, v46, v50
	ds_write_b32 v5, v4 offset:256
	v_cvt_pk_bf16_f32 v4, v47, v51
	ds_write_b32 v5, v4 offset:384
	v_cvt_pk_bf16_f32 v4, v52, v56
	v_add_u32_e32 v5, v78, v71
	ds_write_b32 v5, v4
	v_cvt_pk_bf16_f32 v4, v53, v57
	ds_write_b32 v5, v4 offset:128
	v_cvt_pk_bf16_f32 v4, v54, v58
	ds_write_b32 v5, v4 offset:256
	v_cvt_pk_bf16_f32 v4, v55, v59
	ds_write_b32 v5, v4 offset:384
	v_cvt_pk_bf16_f32 v4, v60, v64
	v_add_u32_e32 v5, v79, v71
	ds_write_b32 v5, v4
	v_cvt_pk_bf16_f32 v4, v61, v65
	ds_write_b32 v5, v4 offset:128
	v_cvt_pk_bf16_f32 v4, v62, v66
	ds_write_b32 v5, v4 offset:256
	v_cvt_pk_bf16_f32 v4, v63, v67
	ds_write_b32 v5, v4 offset:384
	s_add_u32 s8, s3, s7
	s_waitcnt lgkmcnt(0)
	s_addc_u32 s9, s6, 0
	v_lshlrev_b32_e32 v4, 1, v70
	v_mov_b32_e32 v5, v2
	v_lshl_add_u64 v[12:13], s[8:9], 0, v[4:5]
	v_add_u32_e32 v4, v81, v82
	ds_read_b128 v[4:7], v4
	v_or_b32_e32 v8, s2, v80
	v_lshlrev_b32_e32 v8, 12, v8
	v_mov_b32_e32 v9, v2
	v_lshl_add_u64 v[14:15], v[12:13], 0, v[8:9]
	v_add_u32_e32 v8, v84, v85
	ds_read_b128 v[8:11], v8
	s_waitcnt lgkmcnt(1)
	global_store_dwordx4 v[14:15], v[4:7], off
	s_nop 1
	v_or_b32_e32 v4, s2, v83
	v_lshlrev_b32_e32 v4, 12, v4
	v_mov_b32_e32 v5, v2
	v_lshl_add_u64 v[4:5], v[12:13], 0, v[4:5]
	s_waitcnt lgkmcnt(0)
	global_store_dwordx4 v[4:5], v[8:11], off
	v_add_u32_e32 v4, v87, v88
	ds_read_b128 v[4:7], v4
	v_or_b32_e32 v8, s2, v86
	v_lshlrev_b32_e32 v8, 12, v8
	v_mov_b32_e32 v9, v2
	v_lshl_add_u64 v[14:15], v[12:13], 0, v[8:9]
	v_add_u32_e32 v8, v90, v91
	ds_read_b128 v[8:11], v8
	s_waitcnt lgkmcnt(1)
	global_store_dwordx4 v[14:15], v[4:7], off
	s_nop 1
	v_or_b32_e32 v4, s2, v89
	v_lshlrev_b32_e32 v4, 12, v4
	v_mov_b32_e32 v5, v2
	v_lshl_add_u64 v[4:5], v[12:13], 0, v[4:5]
	s_waitcnt lgkmcnt(0)
	global_store_dwordx4 v[4:5], v[8:11], off
	v_add_u32_e32 v4, v93, v82
	ds_read_b128 v[4:7], v4
	v_or_b32_e32 v8, s2, v92
	v_lshlrev_b32_e32 v8, 12, v8
	v_mov_b32_e32 v9, v2
	v_lshl_add_u64 v[14:15], v[12:13], 0, v[8:9]
	v_add_u32_e32 v8, v95, v96
	ds_read_b128 v[8:11], v8
	s_waitcnt lgkmcnt(1)
	global_store_dwordx4 v[14:15], v[4:7], off
	s_nop 1
	v_or_b32_e32 v4, s2, v94
	v_lshlrev_b32_e32 v4, 12, v4
	v_mov_b32_e32 v5, v2
	v_lshl_add_u64 v[4:5], v[12:13], 0, v[4:5]
	s_waitcnt lgkmcnt(0)
	global_store_dwordx4 v[4:5], v[8:11], off
	v_add_u32_e32 v4, v98, v99
	ds_read_b128 v[4:7], v4
	v_or_b32_e32 v8, s2, v97
	v_lshlrev_b32_e32 v8, 12, v8
	v_mov_b32_e32 v9, v2
	v_lshl_add_u64 v[14:15], v[12:13], 0, v[8:9]
	v_add_u32_e32 v8, v101, v102
	ds_read_b128 v[8:11], v8
	s_waitcnt lgkmcnt(1)
	global_store_dwordx4 v[14:15], v[4:7], off
	s_nop 1
	v_or_b32_e32 v4, s2, v100
	v_lshlrev_b32_e32 v4, 12, v4
	v_mov_b32_e32 v5, v2
	v_lshl_add_u64 v[4:5], v[12:13], 0, v[4:5]
	s_waitcnt lgkmcnt(0)
	global_store_dwordx4 v[4:5], v[8:11], off
	s_waitcnt lgkmcnt(0)

;     const int nblk = N / 64, kb = item / nblk, nb = item % nblk, k0 = 64 * kb, n0 = 64 * nb;
;     const int r16 = lane & 15, q = lane >> 4;
;     const float* src = W + (size_t)(k0 + 2 * q) * N + n0 + 4 * r16;
;     f32x4 v[16];
; #pragma unroll
;     for (int j = 0; j < 16; ++j) v[j] = *(const f32x4*)(src + (size_t)(8 * (j >> 1) + (j & 1)) * N);
; __device__ __forceinline__ void weights_pass(const Args& a, LAS unsigned char* scr, int gw, int NGW, int lane, int pass) {
;     ...
;         if (r < I_OUT / 2) { transpose_item<0>(a.in[I_WOUT] + (size_t)l * DM * DM, 2048, DM, (bf16_t*)(wl + WL_OUT), nullptr, nullptr, 0, scr, r, lane, DM); continue; } r -= I_OUT / 2;
.LBB0_1710:
	s_andn2_b64 vcc, exec, s[6:7]
	s_cbranch_vccnz .LBB0_1712
	s_lshl_b64 s[2:3], s[0:1], 26
	s_add_u32 s6, s74, s2
	s_addc_u32 s7, s75, s3
	s_add_i32 s1, s21, 0xee00
	s_and_b32 s2, s1, 0xffc0
	s_lshl_b32 s1, s21, 6
	v_lshlrev_b32_e32 v4, 2, v3
	s_and_b32 s1, s1, 0xfc0
	v_lshl_or_b32 v4, s2, 14, v4
	v_mov_b32_e32 v5, v2
	v_lshl_add_u64 v[4:5], s[6:7], 0, v[4:5]
	s_lshl_b32 s14, s1, 2
	v_lshl_add_u64 v[4:5], v[4:5], 0, s[14:15]
	v_lshlrev_b32_e32 v6, 2, v68
	v_mov_b32_e32 v7, v2
	v_lshl_add_u64 v[60:61], v[4:5], 0, v[6:7]
	s_movk_i32 s3, 0x4000
	v_add_co_u32_e32 v8, vcc, s3, v60
	s_mov_b32 s3, 0x24000
	s_nop 0
	v_addc_co_u32_e32 v9, vcc, 0, v61, vcc
	global_load_dwordx4 v[4:7], v[60:61], off nt
	s_nop 0
	global_load_dwordx4 v[8:11], v[8:9], off nt
	v_add_co_u32_e32 v12, vcc, s22, v60
	s_lshl_b32 s2, s2, 1
	s_nop 0
	v_addc_co_u32_e32 v13, vcc, 0, v61, vcc
	v_add_co_u32_e32 v16, vcc, s3, v60
	s_mov_b32 s3, 0x40000
	s_nop 0
	v_addc_co_u32_e32 v17, vcc, 0, v61, vcc
	global_load_dwordx4 v[12:15], v[12:13], off nt
	s_nop 0
	global_load_dwordx4 v[16:19], v[16:17], off nt
	v_add_co_u32_e32 v20, vcc, s3, v60
	s_mov_b32 s3, 0x44000
	s_nop 0
	v_addc_co_u32_e32 v21, vcc, 0, v61, vcc
	v_add_co_u32_e32 v24, vcc, s3, v60
	s_mov_b32 s3, 0x60000
	s_nop 0
	v_addc_co_u32_e32 v25, vcc, 0, v61, vcc
	global_load_dwordx4 v[20:23], v[20:21], off nt
	s_nop 0
	global_load_dwordx4 v[24:27], v[24:25], off nt
	v_add_co_u32_e32 v28, vcc, s3, v60
	s_mov_b32 s3, 0x64000
	s_nop 0
	v_addc_co_u32_e32 v29, vcc, 0, v61, vcc
	v_add_co_u32_e32 v32, vcc, s3, v60
	s_mov_b32 s3, 0x80000
	s_nop 0
	v_addc_co_u32_e32 v33, vcc, 0, v61, vcc
	global_load_dwordx4 v[28:31], v[28:29], off nt
	s_nop 0
	global_load_dwordx4 v[32:35], v[32:33], off nt
	v_add_co_u32_e32 v36, vcc, s3, v60
	s_mov_b32 s3, 0x84000
	s_nop 0
	v_addc_co_u32_e32 v37, vcc, 0, v61, vcc
	v_add_co_u32_e32 v40, vcc, s3, v60
	s_mov_b32 s3, 0xa0000
	s_nop 0
	v_addc_co_u32_e32 v41, vcc, 0, v61, vcc
	global_load_dwordx4 v[36:39], v[36:37], off nt
	s_nop 0
	global_load_dwordx4 v[40:43], v[40:41], off nt
	v_add_co_u32_e32 v44, vcc, s3, v60
	s_mov_b32 s3, 0xa4000
	s_nop 0
	v_addc_co_u32_e32 v45, vcc, 0, v61, vcc
	v_add_co_u32_e32 v48, vcc, s3, v60
	s_mov_b32 s3, 0xc0000
	s_nop 0
	v_addc_co_u32_e32 v49, vcc, 0, v61, vcc
	global_load_dwordx4 v[44:47], v[44:45], off nt
	s_nop 0
	global_load_dwordx4 v[48:51], v[48:49], off nt
	v_add_co_u32_e32 v52, vcc, s3, v60
	s_mov_b32 s3, 0xc4000
	s_nop 0
	v_addc_co_u32_e32 v53, vcc, 0, v61, vcc
	v_add_co_u32_e32 v56, vcc, s3, v60
	s_mov_b32 s3, 0xe0000
	s_nop 0
	v_addc_co_u32_e32 v57, vcc, 0, v61, vcc
	global_load_dwordx4 v[52:55], v[52:53], off nt
	s_nop 0
	global_load_dwordx4 v[56:59], v[56:57], off nt
	v_add_co_u32_e32 v62, vcc, s3, v60
	s_mov_b32 s3, 0xe4000
	s_nop 0
	v_addc_co_u32_e32 v63, vcc, 0, v61, vcc
	v_add_co_u32_e32 v64, vcc, s3, v60
	s_add_u32 s2, s19, s2
	s_nop 0
	v_addc_co_u32_e32 v65, vcc, 0, v61, vcc
	global_load_dwordx4 v[60:63], v[62:63], off nt
	s_nop 0
	global_load_dwordx4 v[64:67], v[64:65], off nt
	s_waitcnt vmcnt(0)
; #define LAS __attribute__((address_space(3)))
; #define LDS_WAIT() asm volatile("s_waitcnt lgkmcnt(0)" ::: "memory")
; __device__ __forceinline__ unsigned cvt_pk_bf16(float lo, float hi) { unsigned r; asm volatile("v_cvt_pk_bf16_f32 %0, %1, %2" : "=v"(r) : "v"(lo), "v"(hi)); return r; }
;     ...
; #pragma unroll
;     for (int i = 0; i < 8; ++i)
; #pragma unroll
;         for (int e = 0; e < 4; ++e) *(LAS unsigned*)(scr + (4 * r16 + e) * 128 + ((i ^ (r16 & 7)) * 16) + q * 4) = cvt_pk_bf16(v[2 * i][e], v[2 * i + 1][e]);
;     LDS_WAIT(); asm volatile("" ::: "memory");
;     const int c = lane & 7;
; #pragma unroll
;     for (int j = 0; j < 8; ++j) { const int row = (lane >> 3) + 8 * j; const u32x4 o = *(const LAS u32x4*)(scr + row * 128 + ((c ^ ((row >> 2) & 7)) * 16));
;         const int lc = col_off + n0 + row; int dr;
;         if (MODE == 0) dr = lc;
;         else if (MODE == 1) dr = (lc & ~255) + 128 * ((lc >> 5) & 1) + 32 * ((lc >> 6) & 3) + (lc & 31);
;         else if (MODE == 2) dr = 256 * (lc >> 7) + (lc & 127);
;         else dr = 256 * (lc >> 7) + 128 + (lc & 127);
;         *(u32x4*)(WT + (size_t)dr * (ldt ? ldt : K) + k0 + 8 * c) = o; }
;     LDS_WAIT(); asm volatile("" ::: "memory");
	v_cvt_pk_bf16_f32 v4, v4, v8
	v_add_u32_e32 v8, v69, v71
	ds_write_b32 v8, v4
	v_cvt_pk_bf16_f32 v4, v5, v9
	ds_write_b32 v8, v4 offset:128
	v_cvt_pk_bf16_f32 v4, v6, v10
	ds_write_b32 v8, v4 offset:256
	v_cvt_pk_bf16_f32 v4, v7, v11
	ds_write_b32 v8, v4 offset:384
	v_cvt_pk_bf16_f32 v4, v12, v16
	v_add_u32_e32 v5, v73, v71
	ds_write_b32 v5, v4
	v_cvt_pk_bf16_f32 v4, v13, v17
	ds_write_b32 v5, v4 offset:128
	v_cvt_pk_bf16_f32 v4, v14, v18
	ds_write_b32 v5, v4 offset:256
	v_cvt_pk_bf16_f32 v4, v15, v19
	ds_write_b32 v5, v4 offset:384
	v_cvt_pk_bf16_f32 v4, v20, v24
	v_add_u32_e32 v5, v74, v71
	ds_write_b32 v5, v4
	v_cvt_pk_bf16_f32 v4, v21, v25
	ds_write_b32 v5, v4 offset:128
	v_cvt_pk_bf16_f32 v4, v22, v26
	ds_write_b32 v5, v4 offset:256
	v_cvt_pk_bf16_f32 v4, v23, v27
	ds_write_b32 v5, v4 offset:384
	v_cvt_pk_bf16_f32 v4, v28, v32
	v_add_u32_e32 v5, v75, v71
	ds_write_b32 v5, v4
	v_cvt_pk_bf16_f32 v4, v29, v33
	ds_write_b32 v5, v4 offset:128
	v_cvt_pk_bf16_f32 v4, v30, v34
	ds_write_b32 v5, v4 offset:256
	v_cvt_pk_bf16_f32 v4, v31, v35
	ds_write_b32 v5, v4 offset:384
	v_cvt_pk_bf16_f32 v4, v36, v40
	v_add_u32_e32 v5, v76, v71
	ds_write_b32 v5, v4
	v_cvt_pk_bf16_f32 v4, v37, v41
	ds_write_b32 v5, v4 offset:128
	v_cvt_pk_bf16_f32 v4, v38, v42
	ds_write_b32 v5, v4 offset:256
	v_cvt_pk_bf16_f32 v4, v39, v43
	ds_write_b32 v5, v4 offset:384
	v_cvt_pk_bf16_f32 v4, v44, v48
	v_add_u32_e32 v5, v77, v71
	ds_write_b32 v5, v4
	v_cvt_pk_bf16_f32 v4, v45, v49
	ds_write_b32 v5, v4 offset:128
	v_cvt_pk_bf16_f32 v4, v46, v50
	ds_write_b32 v5, v4 offset:256
	v_cvt_pk_bf16_f32 v4, v47, v51
	ds_write_b32 v5, v4 offset:384
	v_cvt_pk_bf16_f32 v4, v52, v56
	v_add_u32_e32 v5, v78, v71
	ds_write_b32 v5, v4
	v_cvt_pk_bf16_f32 v4, v53, v57
	ds_write_b32 v5, v4 offset:128
	v_cvt_pk_bf16_f32 v4, v54, v58
	ds_write_b32 v5, v4 offset:256
	v_cvt_pk_bf16_f32 v4, v55, v59
	ds_write_b32 v5, v4 offset:384
	v_cvt_pk_bf16_f32 v4, v60, v64
	v_add_u32_e32 v5, v79, v71
	ds_write_b32 v5, v4
	v_cvt_pk_bf16_f32 v4, v61, v65
	ds_write_b32 v5, v4 offset:128
	v_cvt_pk_bf16_f32 v4, v62, v66
	ds_write_b32 v5, v4 offset:256
	v_cvt_pk_bf16_f32 v4, v63, v67
	ds_write_b32 v5, v4 offset:384
	s_addc_u32 s3, s20, 0
	v_lshlrev_b32_e32 v4, 1, v70
	v_mov_b32_e32 v5, v2
	s_waitcnt lgkmcnt(0)
	v_lshl_add_u64 v[4:5], s[2:3], 0, v[4:5]
	s_mov_b64 s[2:3], 0x2600000
	v_lshl_add_u64 v[12:13], v[4:5], 0, s[2:3]
	v_add_u32_e32 v4, v81, v82
	ds_read_b128 v[4:7], v4
	v_or_b32_e32 v8, s1, v80
	v_lshlrev_b32_e32 v8, 13, v8
	v_mov_b32_e32 v9, v2
	v_lshl_add_u64 v[14:15], v[12:13], 0, v[8:9]
	v_add_u32_e32 v8, v84, v85
	ds_read_b128 v[8:11], v8
	s_waitcnt lgkmcnt(1)
	global_store_dwordx4 v[14:15], v[4:7], off
	s_nop 1
	v_or_b32_e32 v4, s1, v83
	v_lshlrev_b32_e32 v4, 13, v4
	v_mov_b32_e32 v5, v2
	v_lshl_add_u64 v[4:5], v[12:13], 0, v[4:5]
	s_waitcnt lgkmcnt(0)
	global_store_dwordx4 v[4:5], v[8:11], off
	v_add_u32_e32 v4, v87, v88
	ds_read_b128 v[4:7], v4
	v_or_b32_e32 v8, s1, v86
	v_lshlrev_b32_e32 v8, 13, v8
	v_mov_b32_e32 v9, v2
	v_lshl_add_u64 v[14:15], v[12:13], 0, v[8:9]
	v_add_u32_e32 v8, v90, v91
	ds_read_b128 v[8:11], v8
	s_waitcnt lgkmcnt(1)
	global_store_dwordx4 v[14:15], v[4:7], off
	s_nop 1
	v_or_b32_e32 v4, s1, v89
	v_lshlrev_b32_e32 v4, 13, v4
	v_mov_b32_e32 v5, v2
	v_lshl_add_u64 v[4:5], v[12:13], 0, v[4:5]
	s_waitcnt lgkmcnt(0)
	global_store_dwordx4 v[4:5], v[8:11], off
	v_add_u32_e32 v4, v93, v82
	ds_read_b128 v[4:7], v4
	v_or_b32_e32 v8, s1, v92
	v_lshlrev_b32_e32 v8, 13, v8
	v_mov_b32_e32 v9, v2
	v_lshl_add_u64 v[14:15], v[12:13], 0, v[8:9]
	v_add_u32_e32 v8, v95, v96
	ds_read_b128 v[8:11], v8
	s_waitcnt lgkmcnt(1)
	global_store_dwordx4 v[14:15], v[4:7], off
	s_nop 1
	v_or_b32_e32 v4, s1, v94
	v_lshlrev_b32_e32 v4, 13, v4
	v_mov_b32_e32 v5, v2
	v_lshl_add_u64 v[4:5], v[12:13], 0, v[4:5]
	s_waitcnt lgkmcnt(0)
	global_store_dwordx4 v[4:5], v[8:11], off
	v_add_u32_e32 v4, v98, v99
	ds_read_b128 v[4:7], v4
	v_or_b32_e32 v8, s1, v97
	v_lshlrev_b32_e32 v8, 13, v8
	v_mov_b32_e32 v9, v2
	v_lshl_add_u64 v[14:15], v[12:13], 0, v[8:9]
	v_add_u32_e32 v8, v101, v102
	ds_read_b128 v[8:11], v8
	s_waitcnt lgkmcnt(1)
	global_store_dwordx4 v[14:15], v[4:7], off
	s_nop 1
	v_or_b32_e32 v4, s1, v100
	v_lshlrev_b32_e32 v4, 13, v4
	v_mov_b32_e32 v5, v2
	v_lshl_add_u64 v[4:5], v[12:13], 0, v[4:5]
	s_waitcnt lgkmcnt(0)
	global_store_dwordx4 v[4:5], v[8:11], off
	s_waitcnt lgkmcnt(0)

;     const int nblk = N / 64, kb = item / nblk, nb = item % nblk, k0 = 64 * kb, n0 = 64 * nb;
;     const int r16 = lane & 15, q = lane >> 4;
;     const float* src = W + (size_t)(k0 + 2 * q) * N + n0 + 4 * r16;
;     f32x4 v[16];
; #pragma unroll
;     for (int j = 0; j < 16; ++j) v[j] = *(const f32x4*)(src + (size_t)(8 * (j >> 1) + (j & 1)) * N);
;     if (nscale) { const f32x4 ns = *(const f32x4*)(nscale + n0 + 4 * r16);
; #pragma unroll
;         for (int j = 0; j < 16; ++j) v[j] = v[j] * ns; }
;     if (kscale) {
; #pragma unroll
;         for (int i = 0; i < 8; ++i) { const f32x2 g = *(const f32x2*)(kscale + k0 + 8 * i + 2 * q); v[2 * i] = v[2 * i] * g[0]; v[2 * i + 1] = v[2 * i + 1] * g[1]; } }
; __device__ __forceinline__ void weights_pass(const Args& a, LAS unsigned char* scr, int gw, int NGW, int lane, int pass) {
;     ...
;         if (r < I_IN) { transpose_item<1>(a.in[I_WIN] + (size_t)l * DM * INW, DM, INW, (bf16_t*)(wl + WL_IN), a.in[I_GMIX] + l * DM, nullptr, 0, scr, r, lane); continue; } r -= I_IN;
.LBB0_1713:
	s_andn2_b64 vcc, exec, s[6:7]
	s_cbranch_vccnz .LBB0_1667
	s_mul_i32 s2, s0, 0x4800000
	s_mul_hi_i32 s3, s0, 0x4800000
	s_add_u32 s2, s62, s2
	s_mul_hi_i32 s6, s21, 0x38e38e39
	s_addc_u32 s3, s63, s3
	s_lshr_b32 s7, s6, 31
	s_ashr_i32 s6, s6, 4
	s_add_i32 s6, s6, s7
	s_mul_i32 s1, s0, 0xab00
	s_mul_i32 s7, s6, 0xffffffb8
	s_sub_i32 s1, s7, s1
	s_add_i32 s1, s10, s1
	s_lshl_b32 s8, s6, 6
	s_lshl_b32 s6, s1, 6
	v_or_b32_e32 v4, s8, v72
	s_movk_i32 s1, 0x1200
	v_mul_lo_u32 v4, v4, s1
	v_ashrrev_i32_e32 v5, 31, v4
	v_lshl_add_u64 v[4:5], v[4:5], 2, s[2:3]
	s_ashr_i32 s7, s6, 31
	v_lshl_add_u64 v[4:5], s[6:7], 2, v[4:5]
	v_lshlrev_b32_e32 v6, 2, v68
	v_mov_b32_e32 v7, v2
	v_lshl_add_u64 v[4:5], v[4:5], 0, v[6:7]
	s_movk_i32 s1, 0x4000
	v_add_co_u32_e32 v6, vcc, s1, v4
	s_mov_b32 s1, 0x24000
	s_nop 0
	v_addc_co_u32_e32 v7, vcc, 0, v5, vcc
	global_load_dwordx4 v[60:63], v[4:5], off nt
	global_load_dwordx4 v[64:67], v[6:7], off offset:2048 nt
	v_add_co_u32_e32 v6, vcc, s1, v4
	s_mov_b32 s1, 0x28000
	s_nop 0
	v_addc_co_u32_e32 v7, vcc, 0, v5, vcc
	v_add_co_u32_e32 v8, vcc, s1, v4
	s_mov_b32 s1, 0x48000
	s_nop 0
	v_addc_co_u32_e32 v9, vcc, 0, v5, vcc
	global_load_dwordx4 v[52:55], v[6:7], off nt
	global_load_dwordx4 v[56:59], v[8:9], off offset:2048 nt
	v_add_co_u32_e32 v6, vcc, s1, v4
	s_mov_b32 s1, 0x4c000
	s_nop 0
	v_addc_co_u32_e32 v7, vcc, 0, v5, vcc
	v_add_co_u32_e32 v8, vcc, s1, v4
	s_mov_b32 s1, 0x6c000
	s_nop 0
	v_addc_co_u32_e32 v9, vcc, 0, v5, vcc
	global_load_dwordx4 v[44:47], v[6:7], off nt
	global_load_dwordx4 v[48:51], v[8:9], off offset:2048 nt
	v_add_co_u32_e32 v6, vcc, s1, v4
	s_mov_b32 s1, 0x70000
	s_nop 0
	v_addc_co_u32_e32 v7, vcc, 0, v5, vcc
	v_add_co_u32_e32 v8, vcc, s1, v4
	s_mov_b32 s1, 0x90000
	s_nop 0
	v_addc_co_u32_e32 v9, vcc, 0, v5, vcc
	global_load_dwordx4 v[28:31], v[6:7], off nt
	global_load_dwordx4 v[40:43], v[8:9], off offset:2048 nt
	v_add_co_u32_e32 v6, vcc, s1, v4
	s_mov_b32 s1, 0x94000
	s_nop 0
	v_addc_co_u32_e32 v7, vcc, 0, v5, vcc
	v_add_co_u32_e32 v8, vcc, s1, v4
	s_mov_b32 s1, 0xb4000
	s_nop 0
	v_addc_co_u32_e32 v9, vcc, 0, v5, vcc
	global_load_dwordx4 v[20:23], v[6:7], off nt
	global_load_dwordx4 v[36:39], v[8:9], off offset:2048 nt
	v_add_co_u32_e32 v6, vcc, s1, v4
	s_mov_b32 s1, 0xb8000
	s_nop 0
	v_addc_co_u32_e32 v7, vcc, 0, v5, vcc
	v_add_co_u32_e32 v8, vcc, s1, v4
	v_readlane_b32 s2, v254, 15
	s_nop 0
	v_addc_co_u32_e32 v9, vcc, 0, v5, vcc
	global_load_dwordx4 v[16:19], v[6:7], off nt
	global_load_dwordx4 v[32:35], v[8:9], off offset:2048 nt
	v_add_co_u32_e32 v6, vcc, 0xd8000, v4
	v_readlane_b32 s3, v254, 16
	s_nop 0
	v_addc_co_u32_e32 v7, vcc, 0, v5, vcc
	v_add_co_u32_e32 v12, vcc, 0xdc000, v4
	s_ashr_i32 s9, s8, 31
	s_nop 0
	v_addc_co_u32_e32 v13, vcc, 0, v5, vcc
	global_load_dwordx4 v[8:11], v[6:7], off nt
	global_load_dwordx4 v[24:27], v[12:13], off offset:2048 nt
	v_add_co_u32_e32 v6, vcc, 0xfc000, v4
	s_nop 1
	v_addc_co_u32_e32 v7, vcc, 0, v5, vcc
	v_add_co_u32_e32 v12, vcc, 0x100000, v4
	s_nop 1
	v_addc_co_u32_e32 v13, vcc, 0, v5, vcc
	global_load_dwordx4 v[4:7], v[6:7], off nt
	s_nop 0
	global_load_dwordx4 v[12:15], v[12:13], off offset:2048 nt
	s_andn2_b64 vcc, exec, s[2:3]
	s_cbranch_vccnz .LBB0_1666
	s_lshl_b32 s0, s0, 12
	s_ashr_i32 s1, s0, 31
	s_lshl_b64 s[0:1], s[0:1], 2
	s_add_u32 s2, s60, s0
	s_addc_u32 s3, s61, s1
	s_lshl_b64 s[0:1], s[8:9], 2
	s_add_u32 s0, s2, s0
	s_addc_u32 s1, s3, s1
	v_lshlrev_b32_e32 v103, 2, v72
	global_load_dwordx2 v[104:105], v103, s[0:1]
	s_waitcnt vmcnt(0)
	v_pk_mul_f32 v[62:63], v[62:63], v[104:105] op_sel_hi:[1,0]
	v_pk_mul_f32 v[60:61], v[60:61], v[104:105] op_sel_hi:[1,0]
	v_pk_mul_f32 v[66:67], v[66:67], v[104:105] op_sel:[0,1]
	v_pk_mul_f32 v[64:65], v[64:65], v[104:105] op_sel:[0,1]
	global_load_dwordx2 v[104:105], v103, s[0:1] offset:32
	s_waitcnt vmcnt(0)
	v_pk_mul_f32 v[54:55], v[54:55], v[104:105] op_sel_hi:[1,0]
	v_pk_mul_f32 v[52:53], v[52:53], v[104:105] op_sel_hi:[1,0]
	v_pk_mul_f32 v[58:59], v[58:59], v[104:105] op_sel:[0,1]
	v_pk_mul_f32 v[56:57], v[56:57], v[104:105] op_sel:[0,1]
	global_load_dwordx2 v[104:105], v103, s[0:1] offset:64
	s_waitcnt vmcnt(0)
	v_pk_mul_f32 v[46:47], v[46:47], v[104:105] op_sel_hi:[1,0]
	v_pk_mul_f32 v[44:45], v[44:45], v[104:105] op_sel_hi:[1,0]
	v_pk_mul_f32 v[50:51], v[50:51], v[104:105] op_sel:[0,1]
	v_pk_mul_f32 v[48:49], v[48:49], v[104:105] op_sel:[0,1]
	global_load_dwordx2 v[104:105], v103, s[0:1] offset:96
	s_waitcnt vmcnt(0)
	v_pk_mul_f32 v[30:31], v[30:31], v[104:105] op_sel_hi:[1,0]
	v_pk_mul_f32 v[28:29], v[28:29], v[104:105] op_sel_hi:[1,0]
	v_pk_mul_f32 v[42:43], v[42:43], v[104:105] op_sel:[0,1]
	v_pk_mul_f32 v[40:41], v[40:41], v[104:105] op_sel:[0,1]
	global_load_dwordx2 v[104:105], v103, s[0:1] offset:128
	s_waitcnt vmcnt(0)
	v_pk_mul_f32 v[22:23], v[22:23], v[104:105] op_sel_hi:[1,0]
	v_pk_mul_f32 v[20:21], v[20:21], v[104:105] op_sel_hi:[1,0]
	v_pk_mul_f32 v[38:39], v[38:39], v[104:105] op_sel:[0,1]
	v_pk_mul_f32 v[36:37], v[36:37], v[104:105] op_sel:[0,1]
	global_load_dwordx2 v[104:105], v103, s[0:1] offset:160
	s_waitcnt vmcnt(0)
	v_pk_mul_f32 v[18:19], v[18:19], v[104:105] op_sel_hi:[1,0]
	v_pk_mul_f32 v[16:17], v[16:17], v[104:105] op_sel_hi:[1,0]
	v_pk_mul_f32 v[34:35], v[34:35], v[104:105] op_sel:[0,1]
	v_pk_mul_f32 v[32:33], v[32:33], v[104:105] op_sel:[0,1]
	global_load_dwordx2 v[104:105], v103, s[0:1] offset:192
	s_waitcnt vmcnt(0)
	v_pk_mul_f32 v[10:11], v[10:11], v[104:105] op_sel_hi:[1,0]
	v_pk_mul_f32 v[8:9], v[8:9], v[104:105] op_sel_hi:[1,0]
	v_pk_mul_f32 v[26:27], v[26:27], v[104:105] op_sel:[0,1]
	v_pk_mul_f32 v[24:25], v[24:25], v[104:105] op_sel:[0,1]
	global_load_dwordx2 v[104:105], v103, s[0:1] offset:224
	s_waitcnt vmcnt(0)
	v_pk_mul_f32 v[6:7], v[6:7], v[104:105] op_sel_hi:[1,0]
	v_pk_mul_f32 v[4:5], v[4:5], v[104:105] op_sel_hi:[1,0]
	v_pk_mul_f32 v[14:15], v[14:15], v[104:105] op_sel:[0,1]
	v_pk_mul_f32 v[12:13], v[12:13], v[104:105] op_sel:[0,1]
	s_branch .LBB0_1666
